# speedup vs baseline: 1.0507x; 1.0345x over previous
; #define GAS __attribute__((address_space(1)))
; __device__ __forceinline__ uint2 pack4(f32x4 v) { return make_uint2(pack2(v[0], v[1]), pack2(v[2], v[3])); }
; template <int MODE>
; __device__ __forceinline__ void epi_elem(char* ws, float* outp, const float* b_gate, int g0, int rl, int col, f32x4 v) {
;     ...
;   } else if (MODE == E_T || MODE == E_FF) {
;     *(GAS uint2*)((u16*)(ws + (MODE == E_T ? W_T : W_FF)) + (size_t)rl * 1024 + col) = pack4(v);
;     ...
;     int em = (mode == E_FFX) ? (int)E_FF : (mode == E_DUAL ? (cur_sub ? (int)E_MG : (int)E_M1) : mode);
;     if (mode == 0) { int seg = cur_bcol >> 10; em = seg >= 5 ? E_G : seg; }
;     switch (em) {
;       case E_U:  epi_store<E_U>(wsl, outl, bgl, g0, acc, rbase, cbase); break;
;       case E_GV: epi_store<E_GV>(wsl, outl, bgl, g0, acc, rbase, cbase); break;
;       case E_Q:  epi_store<E_Q>(wsl, outl, bgl, g0, acc, rbase, cbase); break;
;       case E_K:  epi_store<E_K>(wsl, outl, bgl, g0, acc, rbase, cbase); break;
;       case E_V:  epi_store<E_V>(wsl, outl, bgl, g0, acc, rbase, cbase); break;
;       case E_G:  epi_store<E_G>(wsl, outl, bgl, g0, acc, rbase, cbase); break;
;       case E_M1: epi_store<E_M1>(wsl, outl, bgl, g0, acc, rbase, cbase); break;
;       case E_MG: epi_store<E_MG>(wsl, outl, bgl, g0, acc, rbase, cbase); break;
;       case E_T:  epi_store<E_T>(wsl, outl, bgl, g0, acc, rbase, cbase); break;
;       default:   epi_store<E_FF>(wsl, outl, bgl, g0, acc, rbase, cbase); break;
;     }
.LBB0_960:
	v_readlane_b32 s2, v255, 21
	v_readlane_b32 s3, v255, 22
	s_mov_b64 s[6:7], -1
	s_and_b64 vcc, exec, s[2:3]
	s_cbranch_vccz .LBB0_997
	s_and_b64 s[4:5], s[4:5], exec
	s_cselect_b32 s8, 6, 7
	s_and_b64 s[4:5], s[30:31], exec
	v_readlane_b32 s4, v255, 29
	v_add_u32_e32 v142, s86, v1
	v_add_u32_e32 v140, s70, v184
	s_cselect_b32 s8, s8, s4
	s_ashr_i32 s4, s70, 10
	s_load_dwordx2 s[6:7], s[0:1], 0xb8
	s_load_dwordx2 s[10:11], s[0:1], 0x60
	s_load_dwordx2 s[2:3], s[0:1], 0xc0
	s_min_i32 s9, s4, 5
	v_readlane_b32 s4, v255, 14
	v_readlane_b32 s5, v255, 15
	s_and_b64 s[4:5], s[4:5], exec
	s_cselect_b32 s16, s9, s8
	s_mov_b64 s[12:13], -1
	s_mov_b64 s[8:9], 0
	s_cmp_lt_i32 s16, 4
	s_mov_b64 s[4:5], 0
	s_waitcnt lgkmcnt(0)
	s_cbranch_scc1 .LBB0_980
	s_cmp_gt_i32 s16, 5
	s_cbranch_scc0 .LBB0_974
	s_cmp_gt_i32 s16, 6
	s_cbranch_scc0 .LBB0_971
	s_cmp_gt_i32 s16, 7
	s_cbranch_scc0 .LBB0_968
	s_cmp_eq_u32 s16, 8
	s_mov_b64 s[4:5], -1
	s_cbranch_scc0 .LBB0_967
	v_bfe_u32 v141, v184, 2, 2
	v_and_b32_e32 v143, 1, v141
	v_lshrrev_b32_e32 v187, 1, v141
	v_lshlrev_b32_e32 v143, 4, v143
	v_lshl_add_u32 v143, v187, 3, v143
	v_lshlrev_b32_e32 v141, 2, v141
	v_sub_u32_e32 v143, v143, v141
	v_add_u32_e32 v143, v140, v143
	v_lshlrev_b32_e32 v141, 11, v142
	v_lshl_add_u32 v250, v143, 1, v141
	v_add_u32_e32 v251, 0x8000, v250
	v_add_u32_e32 v252, 0x10000, v250
	v_add_u32_e32 v253, 0x18000, v250
	s_add_u32 s4, s2, 0x2aec0000
	s_addc_u32 s5, s3, 0
	s_add_u32 s6, s2, 0x2af00000
	s_addc_u32 s7, s3, 0
	v_cvt_pk_bf16_f32 v144, v126, v127
	v_cvt_pk_bf16_f32 v145, v128, v129
	v_cvt_pk_bf16_f32 v146, v122, v123
	v_cvt_pk_bf16_f32 v147, v124, v125
	v_cvt_pk_bf16_f32 v148, v118, v119
	v_cvt_pk_bf16_f32 v149, v120, v121
	v_cvt_pk_bf16_f32 v150, v114, v115
	v_cvt_pk_bf16_f32 v151, v116, v117
	v_permlane16_swap_b32_e32 v144, v146
	v_permlane16_swap_b32_e32 v145, v147
	global_store_dwordx4 v250, v[144:147], s[4:5]
	v_cvt_pk_bf16_f32 v152, v110, v111
	v_cvt_pk_bf16_f32 v153, v112, v113
	v_cvt_pk_bf16_f32 v154, v106, v107
	v_cvt_pk_bf16_f32 v155, v108, v109
	v_permlane16_swap_b32_e32 v148, v150
	v_permlane16_swap_b32_e32 v149, v151
	global_store_dwordx4 v251, v[148:151], s[4:5]
	v_cvt_pk_bf16_f32 v156, v102, v103
	v_cvt_pk_bf16_f32 v157, v104, v105
	v_cvt_pk_bf16_f32 v158, v98, v99
	v_cvt_pk_bf16_f32 v159, v100, v101
	v_permlane16_swap_b32_e32 v152, v154
	v_permlane16_swap_b32_e32 v153, v155
	global_store_dwordx4 v252, v[152:155], s[4:5]
	v_cvt_pk_bf16_f32 v144, v94, v95
	v_cvt_pk_bf16_f32 v145, v96, v97
	v_cvt_pk_bf16_f32 v146, v90, v91
	v_cvt_pk_bf16_f32 v147, v92, v93
	v_permlane16_swap_b32_e32 v156, v158
	v_permlane16_swap_b32_e32 v157, v159
	global_store_dwordx4 v253, v[156:159], s[4:5]
	v_cvt_pk_bf16_f32 v148, v86, v87
	v_cvt_pk_bf16_f32 v149, v88, v89
	v_cvt_pk_bf16_f32 v150, v82, v83
	v_cvt_pk_bf16_f32 v151, v84, v85
	v_permlane16_swap_b32_e32 v144, v146
	v_permlane16_swap_b32_e32 v145, v147
	global_store_dwordx4 v250, v[144:147], s[4:5] offset:256
	v_cvt_pk_bf16_f32 v152, v78, v79
	v_cvt_pk_bf16_f32 v153, v80, v81
	v_cvt_pk_bf16_f32 v154, v74, v75
	v_cvt_pk_bf16_f32 v155, v76, v77
	v_permlane16_swap_b32_e32 v148, v150
	v_permlane16_swap_b32_e32 v149, v151
	global_store_dwordx4 v251, v[148:151], s[4:5] offset:256
	v_cvt_pk_bf16_f32 v156, v70, v71
	v_cvt_pk_bf16_f32 v157, v72, v73
	v_cvt_pk_bf16_f32 v158, v66, v67
	v_cvt_pk_bf16_f32 v159, v68, v69
	v_permlane16_swap_b32_e32 v152, v154
	v_permlane16_swap_b32_e32 v153, v155
	global_store_dwordx4 v252, v[152:155], s[4:5] offset:256
	v_cvt_pk_bf16_f32 v144, v62, v63
	v_cvt_pk_bf16_f32 v145, v64, v65
	v_cvt_pk_bf16_f32 v146, v58, v59
	v_cvt_pk_bf16_f32 v147, v60, v61
	v_permlane16_swap_b32_e32 v156, v158
	v_permlane16_swap_b32_e32 v157, v159
	global_store_dwordx4 v253, v[156:159], s[4:5] offset:256
	v_cvt_pk_bf16_f32 v148, v54, v55
	v_cvt_pk_bf16_f32 v149, v56, v57
	v_cvt_pk_bf16_f32 v150, v50, v51
	v_cvt_pk_bf16_f32 v151, v52, v53
	v_permlane16_swap_b32_e32 v144, v146
	v_permlane16_swap_b32_e32 v145, v147
	global_store_dwordx4 v250, v[144:147], s[6:7]
	v_cvt_pk_bf16_f32 v152, v46, v47
	v_cvt_pk_bf16_f32 v153, v48, v49
	v_cvt_pk_bf16_f32 v154, v42, v43
	v_cvt_pk_bf16_f32 v155, v44, v45
	v_permlane16_swap_b32_e32 v148, v150
	v_permlane16_swap_b32_e32 v149, v151
	global_store_dwordx4 v251, v[148:151], s[6:7]
	v_cvt_pk_bf16_f32 v156, v38, v39
	v_cvt_pk_bf16_f32 v157, v40, v41
	v_cvt_pk_bf16_f32 v158, v34, v35
	v_cvt_pk_bf16_f32 v159, v36, v37
	v_permlane16_swap_b32_e32 v152, v154
	v_permlane16_swap_b32_e32 v153, v155
	global_store_dwordx4 v252, v[152:155], s[6:7]
	v_cvt_pk_bf16_f32 v144, v30, v31
	v_cvt_pk_bf16_f32 v145, v32, v33
	v_cvt_pk_bf16_f32 v146, v26, v27
	v_cvt_pk_bf16_f32 v147, v28, v29
	v_permlane16_swap_b32_e32 v156, v158
	v_permlane16_swap_b32_e32 v157, v159
	global_store_dwordx4 v253, v[156:159], s[6:7]
	v_cvt_pk_bf16_f32 v148, v22, v23
	v_cvt_pk_bf16_f32 v149, v24, v25
	v_cvt_pk_bf16_f32 v150, v18, v19
	v_cvt_pk_bf16_f32 v151, v20, v21
	v_permlane16_swap_b32_e32 v144, v146
	v_permlane16_swap_b32_e32 v145, v147
	global_store_dwordx4 v250, v[144:147], s[6:7] offset:256
	v_cvt_pk_bf16_f32 v152, v14, v15
	v_cvt_pk_bf16_f32 v153, v16, v17
	v_cvt_pk_bf16_f32 v154, v10, v11
	v_cvt_pk_bf16_f32 v155, v12, v13
	v_permlane16_swap_b32_e32 v148, v150
	v_permlane16_swap_b32_e32 v149, v151
	global_store_dwordx4 v251, v[148:151], s[6:7] offset:256
	v_cvt_pk_bf16_f32 v156, v6, v7
	v_cvt_pk_bf16_f32 v157, v8, v9
	v_cvt_pk_bf16_f32 v158, v2, v3
	v_cvt_pk_bf16_f32 v159, v4, v5
	v_permlane16_swap_b32_e32 v152, v154
	v_permlane16_swap_b32_e32 v153, v155
	global_store_dwordx4 v252, v[152:155], s[6:7] offset:256
	s_nop 1
	v_permlane16_swap_b32_e32 v156, v158
	v_permlane16_swap_b32_e32 v157, v159
	global_store_dwordx4 v253, v[156:159], s[6:7] offset:256
	s_branch .LBB0_996

; #define GAS __attribute__((address_space(1)))
; __device__ __forceinline__ float bf2f(u16 b) { return __uint_as_float(((uint32_t)b) << 16); }
; __device__ __forceinline__ uint2 pack4(f32x4 v) { return make_uint2(pack2(v[0], v[1]), pack2(v[2], v[3])); }
; template <int MODE>
; __device__ __forceinline__ void epi_elem(char* ws, float* outp, const float* b_gate, int g0, int rl, int col, f32x4 v) {
;     ...
;   } else if (MODE == E_MG) {
;     uint2 g = *(GAS const uint2*)((const u16*)(ws + W_G) + (size_t)rl * 2048 + 1024 + col);
;     uint2 m = *(GAS const uint2*)((const u16*)(ws + W_M1) + (size_t)rl * 1024 + col);
;     f32x4 o;
;     o[0] = bf2f((u16)(m.x & 0xffff)) + v[0] * bf2f((u16)(g.x & 0xffff));
;     o[1] = bf2f((u16)(m.x >> 16)) + v[1] * bf2f((u16)(g.x >> 16));
;     o[2] = bf2f((u16)(m.y & 0xffff)) + v[2] * bf2f((u16)(g.y & 0xffff));
;     o[3] = bf2f((u16)(m.y >> 16)) + v[3] * bf2f((u16)(g.y >> 16));
;     *(GAS uint2*)((u16*)(ws + W_MG) + (size_t)rl * 1024 + col) = pack4(o);
.LBB0_968:
	s_and_b64 vcc, exec, s[12:13]
	s_cbranch_vccz .LBB0_970
	v_bfe_u32 v141, v184, 2, 2
	v_and_b32_e32 v143, 1, v141
	v_lshrrev_b32_e32 v187, 1, v141
	v_lshlrev_b32_e32 v143, 4, v143
	v_lshl_add_u32 v143, v187, 3, v143
	v_lshlrev_b32_e32 v141, 2, v141
	v_sub_u32_e32 v143, v143, v141
	v_add_u32_e32 v143, v140, v143
	v_lshlrev_b32_e32 v141, 12, v142
	v_lshl_add_u32 v246, v143, 1, v141
	v_add_u32_e32 v247, 0x10000, v246
	v_add_u32_e32 v248, 0x20000, v246
	v_add_u32_e32 v249, 0x30000, v246
	v_lshlrev_b32_e32 v141, 11, v142
	v_lshl_add_u32 v250, v143, 1, v141
	v_add_u32_e32 v251, 0x8000, v250
	v_add_u32_e32 v252, 0x10000, v250
	v_add_u32_e32 v253, 0x18000, v250
	s_add_u32 s4, s2, 0x1aac0800
	s_addc_u32 s5, s3, 0
	s_add_u32 s6, s2, 0x1ab40800
	s_addc_u32 s7, s3, 0
	s_add_u32 s8, s2, 0x2aec0000
	s_addc_u32 s9, s3, 0
	s_add_u32 s12, s2, 0x2af00000
	s_addc_u32 s13, s3, 0
	s_add_u32 s14, s2, 0x2efc0000
	s_addc_u32 s15, s3, 0
	s_add_u32 s16, s2, 0x2f000000
	s_addc_u32 s17, s3, 0
	s_mov_b32 s18, 0xffff0000
	global_load_dwordx4 v[144:147], v246, s[4:5]
	global_load_dwordx4 v[148:151], v250, s[8:9]
	global_load_dwordx4 v[152:155], v247, s[4:5]
	global_load_dwordx4 v[156:159], v251, s[8:9]
	global_load_dwordx4 v[160:163], v248, s[4:5]
	global_load_dwordx4 v[164:167], v252, s[8:9]
	global_load_dwordx4 v[168:171], v249, s[4:5]
	global_load_dwordx4 v[172:175], v253, s[8:9]
	global_load_dwordx4 v[214:217], v246, s[4:5] offset:256
	global_load_dwordx4 v[218:221], v250, s[8:9] offset:256
	global_load_dwordx4 v[222:225], v247, s[4:5] offset:256
	global_load_dwordx4 v[226:229], v251, s[8:9] offset:256
	global_load_dwordx4 v[230:233], v248, s[4:5] offset:256
	global_load_dwordx4 v[234:237], v252, s[8:9] offset:256
	global_load_dwordx4 v[238:241], v249, s[4:5] offset:256
	global_load_dwordx4 v[242:245], v253, s[8:9] offset:256
	s_waitcnt vmcnt(8)
	v_permlane16_swap_b32_e32 v144, v146
	v_permlane16_swap_b32_e32 v145, v147
	v_permlane16_swap_b32_e32 v148, v150
	v_permlane16_swap_b32_e32 v149, v151
	v_lshlrev_b32_e32 v176, 16, v144
	v_and_b32_e32 v177, s18, v144
	v_lshlrev_b32_e32 v178, 16, v145
	v_and_b32_e32 v179, s18, v145
	v_lshlrev_b32_e32 v180, 16, v146
	v_and_b32_e32 v181, s18, v146
	v_lshlrev_b32_e32 v182, 16, v147
	v_and_b32_e32 v183, s18, v147
	v_lshlrev_b32_e32 v188, 16, v148
	v_and_b32_e32 v189, s18, v148
	v_lshlrev_b32_e32 v190, 16, v149
	v_and_b32_e32 v191, s18, v149
	v_lshlrev_b32_e32 v192, 16, v150
	v_and_b32_e32 v193, s18, v150
	v_lshlrev_b32_e32 v194, 16, v151
	v_and_b32_e32 v195, s18, v151
	v_pk_fma_f32 v[188:189], v[126:127], v[176:177], v[188:189]
	v_pk_fma_f32 v[190:191], v[128:129], v[178:179], v[190:191]
	v_pk_fma_f32 v[192:193], v[122:123], v[180:181], v[192:193]
	v_pk_fma_f32 v[194:195], v[124:125], v[182:183], v[194:195]
	v_cvt_pk_bf16_f32 v144, v188, v189
	v_cvt_pk_bf16_f32 v145, v190, v191
	v_cvt_pk_bf16_f32 v146, v192, v193
	v_cvt_pk_bf16_f32 v147, v194, v195
	v_permlane16_swap_b32_e32 v152, v154
	v_permlane16_swap_b32_e32 v153, v155
	v_permlane16_swap_b32_e32 v156, v158
	v_permlane16_swap_b32_e32 v157, v159
	v_lshlrev_b32_e32 v176, 16, v152
	v_and_b32_e32 v177, s18, v152
	v_lshlrev_b32_e32 v178, 16, v153
	v_and_b32_e32 v179, s18, v153
	v_lshlrev_b32_e32 v180, 16, v154
	v_and_b32_e32 v181, s18, v154
	v_lshlrev_b32_e32 v182, 16, v155
	v_and_b32_e32 v183, s18, v155
	v_lshlrev_b32_e32 v188, 16, v156
	v_and_b32_e32 v189, s18, v156
	v_lshlrev_b32_e32 v190, 16, v157
	v_and_b32_e32 v191, s18, v157
	v_lshlrev_b32_e32 v192, 16, v158
	v_and_b32_e32 v193, s18, v158
	v_lshlrev_b32_e32 v194, 16, v159
	v_and_b32_e32 v195, s18, v159
	v_pk_fma_f32 v[188:189], v[118:119], v[176:177], v[188:189]
	v_pk_fma_f32 v[190:191], v[120:121], v[178:179], v[190:191]
	v_pk_fma_f32 v[192:193], v[114:115], v[180:181], v[192:193]
	v_pk_fma_f32 v[194:195], v[116:117], v[182:183], v[194:195]
	v_cvt_pk_bf16_f32 v152, v188, v189
	v_cvt_pk_bf16_f32 v153, v190, v191
	v_cvt_pk_bf16_f32 v154, v192, v193
	v_cvt_pk_bf16_f32 v155, v194, v195
	v_permlane16_swap_b32_e32 v144, v146
	v_permlane16_swap_b32_e32 v145, v147
	global_store_dwordx4 v250, v[144:147], s[14:15]
	v_permlane16_swap_b32_e32 v160, v162
	v_permlane16_swap_b32_e32 v161, v163
	v_permlane16_swap_b32_e32 v164, v166
	v_permlane16_swap_b32_e32 v165, v167
	v_lshlrev_b32_e32 v176, 16, v160
	v_and_b32_e32 v177, s18, v160
	v_lshlrev_b32_e32 v178, 16, v161
	v_and_b32_e32 v179, s18, v161
	v_lshlrev_b32_e32 v180, 16, v162
	v_and_b32_e32 v181, s18, v162
	v_lshlrev_b32_e32 v182, 16, v163
	v_and_b32_e32 v183, s18, v163
	v_lshlrev_b32_e32 v188, 16, v164
	v_and_b32_e32 v189, s18, v164
	v_lshlrev_b32_e32 v190, 16, v165
	v_and_b32_e32 v191, s18, v165
	v_lshlrev_b32_e32 v192, 16, v166
	v_and_b32_e32 v193, s18, v166
	v_lshlrev_b32_e32 v194, 16, v167
	v_and_b32_e32 v195, s18, v167
	v_pk_fma_f32 v[188:189], v[110:111], v[176:177], v[188:189]
	v_pk_fma_f32 v[190:191], v[112:113], v[178:179], v[190:191]
	v_pk_fma_f32 v[192:193], v[106:107], v[180:181], v[192:193]
	v_pk_fma_f32 v[194:195], v[108:109], v[182:183], v[194:195]
	v_cvt_pk_bf16_f32 v160, v188, v189
	v_cvt_pk_bf16_f32 v161, v190, v191
	v_cvt_pk_bf16_f32 v162, v192, v193
	v_cvt_pk_bf16_f32 v163, v194, v195
	v_permlane16_swap_b32_e32 v152, v154
	v_permlane16_swap_b32_e32 v153, v155
	global_store_dwordx4 v251, v[152:155], s[14:15]
	v_permlane16_swap_b32_e32 v168, v170
	v_permlane16_swap_b32_e32 v169, v171
	v_permlane16_swap_b32_e32 v172, v174
	v_permlane16_swap_b32_e32 v173, v175
	v_lshlrev_b32_e32 v176, 16, v168
	v_and_b32_e32 v177, s18, v168
	v_lshlrev_b32_e32 v178, 16, v169
	v_and_b32_e32 v179, s18, v169
	v_lshlrev_b32_e32 v180, 16, v170
	v_and_b32_e32 v181, s18, v170
	v_lshlrev_b32_e32 v182, 16, v171
	v_and_b32_e32 v183, s18, v171
	v_lshlrev_b32_e32 v188, 16, v172
	v_and_b32_e32 v189, s18, v172
	v_lshlrev_b32_e32 v190, 16, v173
	v_and_b32_e32 v191, s18, v173
	v_lshlrev_b32_e32 v192, 16, v174
	v_and_b32_e32 v193, s18, v174
	v_lshlrev_b32_e32 v194, 16, v175
	v_and_b32_e32 v195, s18, v175
	v_pk_fma_f32 v[188:189], v[102:103], v[176:177], v[188:189]
	v_pk_fma_f32 v[190:191], v[104:105], v[178:179], v[190:191]
	v_pk_fma_f32 v[192:193], v[98:99], v[180:181], v[192:193]
	v_pk_fma_f32 v[194:195], v[100:101], v[182:183], v[194:195]
	v_cvt_pk_bf16_f32 v168, v188, v189
	v_cvt_pk_bf16_f32 v169, v190, v191
	v_cvt_pk_bf16_f32 v170, v192, v193
	v_cvt_pk_bf16_f32 v171, v194, v195
	v_permlane16_swap_b32_e32 v160, v162
	v_permlane16_swap_b32_e32 v161, v163
	global_store_dwordx4 v252, v[160:163], s[14:15]
	s_nop 1
	v_permlane16_swap_b32_e32 v168, v170
	v_permlane16_swap_b32_e32 v169, v171
	global_store_dwordx4 v253, v[168:171], s[14:15]
	global_load_dwordx4 v[144:147], v246, s[6:7]
	global_load_dwordx4 v[148:151], v250, s[12:13]
	global_load_dwordx4 v[152:155], v247, s[6:7]
	global_load_dwordx4 v[156:159], v251, s[12:13]
	global_load_dwordx4 v[160:163], v248, s[6:7]
	global_load_dwordx4 v[164:167], v252, s[12:13]
	global_load_dwordx4 v[168:171], v249, s[6:7]
	global_load_dwordx4 v[172:175], v253, s[12:13]
	s_waitcnt vmcnt(12)
; #define GAS __attribute__((address_space(1)))
; __device__ __forceinline__ float bf2f(u16 b) { return __uint_as_float(((uint32_t)b) << 16); }
; __device__ __forceinline__ uint2 pack4(f32x4 v) { return make_uint2(pack2(v[0], v[1]), pack2(v[2], v[3])); }
; template <int MODE>
; __device__ __forceinline__ void epi_elem(char* ws, float* outp, const float* b_gate, int g0, int rl, int col, f32x4 v) {
;     ...
;   } else if (MODE == E_MG) {
;     uint2 g = *(GAS const uint2*)((const u16*)(ws + W_G) + (size_t)rl * 2048 + 1024 + col);
;     uint2 m = *(GAS const uint2*)((const u16*)(ws + W_M1) + (size_t)rl * 1024 + col);
;     f32x4 o;
;     o[0] = bf2f((u16)(m.x & 0xffff)) + v[0] * bf2f((u16)(g.x & 0xffff));
;     o[1] = bf2f((u16)(m.x >> 16)) + v[1] * bf2f((u16)(g.x >> 16));
;     o[2] = bf2f((u16)(m.y & 0xffff)) + v[2] * bf2f((u16)(g.y & 0xffff));
;     o[3] = bf2f((u16)(m.y >> 16)) + v[3] * bf2f((u16)(g.y >> 16));
;     *(GAS uint2*)((u16*)(ws + W_MG) + (size_t)rl * 1024 + col) = pack4(o);
	v_permlane16_swap_b32_e32 v214, v216
	v_permlane16_swap_b32_e32 v215, v217
	v_permlane16_swap_b32_e32 v218, v220
	v_permlane16_swap_b32_e32 v219, v221
	v_lshlrev_b32_e32 v176, 16, v214
	v_and_b32_e32 v177, s18, v214
	v_lshlrev_b32_e32 v178, 16, v215
	v_and_b32_e32 v179, s18, v215
	v_lshlrev_b32_e32 v180, 16, v216
	v_and_b32_e32 v181, s18, v216
	v_lshlrev_b32_e32 v182, 16, v217
	v_and_b32_e32 v183, s18, v217
	v_lshlrev_b32_e32 v188, 16, v218
	v_and_b32_e32 v189, s18, v218
	v_lshlrev_b32_e32 v190, 16, v219
	v_and_b32_e32 v191, s18, v219
	v_lshlrev_b32_e32 v192, 16, v220
	v_and_b32_e32 v193, s18, v220
	v_lshlrev_b32_e32 v194, 16, v221
	v_and_b32_e32 v195, s18, v221
	v_pk_fma_f32 v[188:189], v[94:95], v[176:177], v[188:189]
	v_pk_fma_f32 v[190:191], v[96:97], v[178:179], v[190:191]
	v_pk_fma_f32 v[192:193], v[90:91], v[180:181], v[192:193]
	v_pk_fma_f32 v[194:195], v[92:93], v[182:183], v[194:195]
	v_cvt_pk_bf16_f32 v214, v188, v189
	v_cvt_pk_bf16_f32 v215, v190, v191
	v_cvt_pk_bf16_f32 v216, v192, v193
	v_cvt_pk_bf16_f32 v217, v194, v195
	v_permlane16_swap_b32_e32 v222, v224
	v_permlane16_swap_b32_e32 v223, v225
	v_permlane16_swap_b32_e32 v226, v228
	v_permlane16_swap_b32_e32 v227, v229
	v_lshlrev_b32_e32 v176, 16, v222
	v_and_b32_e32 v177, s18, v222
	v_lshlrev_b32_e32 v178, 16, v223
	v_and_b32_e32 v179, s18, v223
	v_lshlrev_b32_e32 v180, 16, v224
	v_and_b32_e32 v181, s18, v224
	v_lshlrev_b32_e32 v182, 16, v225
	v_and_b32_e32 v183, s18, v225
	v_lshlrev_b32_e32 v188, 16, v226
	v_and_b32_e32 v189, s18, v226
	v_lshlrev_b32_e32 v190, 16, v227
	v_and_b32_e32 v191, s18, v227
	v_lshlrev_b32_e32 v192, 16, v228
	v_and_b32_e32 v193, s18, v228
	v_lshlrev_b32_e32 v194, 16, v229
	v_and_b32_e32 v195, s18, v229
	v_pk_fma_f32 v[188:189], v[86:87], v[176:177], v[188:189]
	v_pk_fma_f32 v[190:191], v[88:89], v[178:179], v[190:191]
	v_pk_fma_f32 v[192:193], v[82:83], v[180:181], v[192:193]
	v_pk_fma_f32 v[194:195], v[84:85], v[182:183], v[194:195]
	v_cvt_pk_bf16_f32 v222, v188, v189
	v_cvt_pk_bf16_f32 v223, v190, v191
	v_cvt_pk_bf16_f32 v224, v192, v193
	v_cvt_pk_bf16_f32 v225, v194, v195
	v_permlane16_swap_b32_e32 v214, v216
	v_permlane16_swap_b32_e32 v215, v217
	global_store_dwordx4 v250, v[214:217], s[14:15] offset:256
	v_permlane16_swap_b32_e32 v230, v232
	v_permlane16_swap_b32_e32 v231, v233
	v_permlane16_swap_b32_e32 v234, v236
	v_permlane16_swap_b32_e32 v235, v237
	v_lshlrev_b32_e32 v176, 16, v230
	v_and_b32_e32 v177, s18, v230
	v_lshlrev_b32_e32 v178, 16, v231
	v_and_b32_e32 v179, s18, v231
	v_lshlrev_b32_e32 v180, 16, v232
	v_and_b32_e32 v181, s18, v232
	v_lshlrev_b32_e32 v182, 16, v233
	v_and_b32_e32 v183, s18, v233
	v_lshlrev_b32_e32 v188, 16, v234
	v_and_b32_e32 v189, s18, v234
	v_lshlrev_b32_e32 v190, 16, v235
	v_and_b32_e32 v191, s18, v235
	v_lshlrev_b32_e32 v192, 16, v236
	v_and_b32_e32 v193, s18, v236
	v_lshlrev_b32_e32 v194, 16, v237
	v_and_b32_e32 v195, s18, v237
	v_pk_fma_f32 v[188:189], v[78:79], v[176:177], v[188:189]
	v_pk_fma_f32 v[190:191], v[80:81], v[178:179], v[190:191]
	v_pk_fma_f32 v[192:193], v[74:75], v[180:181], v[192:193]
	v_pk_fma_f32 v[194:195], v[76:77], v[182:183], v[194:195]
	v_cvt_pk_bf16_f32 v230, v188, v189
	v_cvt_pk_bf16_f32 v231, v190, v191
	v_cvt_pk_bf16_f32 v232, v192, v193
	v_cvt_pk_bf16_f32 v233, v194, v195
	v_permlane16_swap_b32_e32 v222, v224
	v_permlane16_swap_b32_e32 v223, v225
	global_store_dwordx4 v251, v[222:225], s[14:15] offset:256
	v_permlane16_swap_b32_e32 v238, v240
	v_permlane16_swap_b32_e32 v239, v241
	v_permlane16_swap_b32_e32 v242, v244
	v_permlane16_swap_b32_e32 v243, v245
	v_lshlrev_b32_e32 v176, 16, v238
	v_and_b32_e32 v177, s18, v238
	v_lshlrev_b32_e32 v178, 16, v239
	v_and_b32_e32 v179, s18, v239
	v_lshlrev_b32_e32 v180, 16, v240
	v_and_b32_e32 v181, s18, v240
	v_lshlrev_b32_e32 v182, 16, v241
	v_and_b32_e32 v183, s18, v241
	v_lshlrev_b32_e32 v188, 16, v242
	v_and_b32_e32 v189, s18, v242
	v_lshlrev_b32_e32 v190, 16, v243
	v_and_b32_e32 v191, s18, v243
	v_lshlrev_b32_e32 v192, 16, v244
	v_and_b32_e32 v193, s18, v244
	v_lshlrev_b32_e32 v194, 16, v245
	v_and_b32_e32 v195, s18, v245
	v_pk_fma_f32 v[188:189], v[70:71], v[176:177], v[188:189]
	v_pk_fma_f32 v[190:191], v[72:73], v[178:179], v[190:191]
	v_pk_fma_f32 v[192:193], v[66:67], v[180:181], v[192:193]
	v_pk_fma_f32 v[194:195], v[68:69], v[182:183], v[194:195]
	v_cvt_pk_bf16_f32 v238, v188, v189
	v_cvt_pk_bf16_f32 v239, v190, v191
	v_cvt_pk_bf16_f32 v240, v192, v193
	v_cvt_pk_bf16_f32 v241, v194, v195
	v_permlane16_swap_b32_e32 v230, v232
	v_permlane16_swap_b32_e32 v231, v233
	global_store_dwordx4 v252, v[230:233], s[14:15] offset:256
	s_nop 1
	v_permlane16_swap_b32_e32 v238, v240
	v_permlane16_swap_b32_e32 v239, v241
	global_store_dwordx4 v253, v[238:241], s[14:15] offset:256
	global_load_dwordx4 v[214:217], v246, s[6:7] offset:256
	global_load_dwordx4 v[218:221], v250, s[12:13] offset:256
	global_load_dwordx4 v[222:225], v247, s[6:7] offset:256
	global_load_dwordx4 v[226:229], v251, s[12:13] offset:256
	global_load_dwordx4 v[230:233], v248, s[6:7] offset:256
	global_load_dwordx4 v[234:237], v252, s[12:13] offset:256
	global_load_dwordx4 v[238:241], v249, s[6:7] offset:256
	global_load_dwordx4 v[242:245], v253, s[12:13] offset:256
	s_waitcnt vmcnt(12)
; #define GAS __attribute__((address_space(1)))
; __device__ __forceinline__ float bf2f(u16 b) { return __uint_as_float(((uint32_t)b) << 16); }
; __device__ __forceinline__ uint2 pack4(f32x4 v) { return make_uint2(pack2(v[0], v[1]), pack2(v[2], v[3])); }
; template <int MODE>
; __device__ __forceinline__ void epi_elem(char* ws, float* outp, const float* b_gate, int g0, int rl, int col, f32x4 v) {
;     ...
;   } else if (MODE == E_MG) {
;     uint2 g = *(GAS const uint2*)((const u16*)(ws + W_G) + (size_t)rl * 2048 + 1024 + col);
;     uint2 m = *(GAS const uint2*)((const u16*)(ws + W_M1) + (size_t)rl * 1024 + col);
;     f32x4 o;
;     o[0] = bf2f((u16)(m.x & 0xffff)) + v[0] * bf2f((u16)(g.x & 0xffff));
;     o[1] = bf2f((u16)(m.x >> 16)) + v[1] * bf2f((u16)(g.x >> 16));
;     o[2] = bf2f((u16)(m.y & 0xffff)) + v[2] * bf2f((u16)(g.y & 0xffff));
;     o[3] = bf2f((u16)(m.y >> 16)) + v[3] * bf2f((u16)(g.y >> 16));
;     *(GAS uint2*)((u16*)(ws + W_MG) + (size_t)rl * 1024 + col) = pack4(o);
; template <int MODE>
; __device__ __forceinline__ void epi_store(char* ws, float* outp, const float* b_gate, int g0, const f32x4 (&acc)[2][2][4][2], int rbase, int cbase) {
; #pragma unroll
;   for (int ai = 0; ai < 2; ++ai)
; #pragma unroll
;     for (int bj = 0; bj < 2; ++bj)
; #pragma unroll
;       for (int m = 0; m < 4; ++m) {
; #pragma unroll
;         for (int n = 0; n < 2; ++n)
;           epi_elem<MODE>(ws, outp, b_gate, g0, rbase + ai * HALF + m * 16, cbase + bj * HALF + n * 16, acc[ai][bj][m][n]);
;         if ((m & 1) && (MODE != E_M1 && MODE != E_MG)) __builtin_amdgcn_sched_barrier(0);
;         if (m == 3 && (MODE == E_M1 || MODE == E_MG)) __builtin_amdgcn_sched_barrier(0);
;       }
	v_permlane16_swap_b32_e32 v144, v146
	v_permlane16_swap_b32_e32 v145, v147
	v_permlane16_swap_b32_e32 v148, v150
	v_permlane16_swap_b32_e32 v149, v151
	v_lshlrev_b32_e32 v176, 16, v144
	v_and_b32_e32 v177, s18, v144
	v_lshlrev_b32_e32 v178, 16, v145
	v_and_b32_e32 v179, s18, v145
	v_lshlrev_b32_e32 v180, 16, v146
	v_and_b32_e32 v181, s18, v146
	v_lshlrev_b32_e32 v182, 16, v147
	v_and_b32_e32 v183, s18, v147
	v_lshlrev_b32_e32 v188, 16, v148
	v_and_b32_e32 v189, s18, v148
	v_lshlrev_b32_e32 v190, 16, v149
	v_and_b32_e32 v191, s18, v149
	v_lshlrev_b32_e32 v192, 16, v150
	v_and_b32_e32 v193, s18, v150
	v_lshlrev_b32_e32 v194, 16, v151
	v_and_b32_e32 v195, s18, v151
	v_pk_fma_f32 v[188:189], v[62:63], v[176:177], v[188:189]
	v_pk_fma_f32 v[190:191], v[64:65], v[178:179], v[190:191]
	v_pk_fma_f32 v[192:193], v[58:59], v[180:181], v[192:193]
	v_pk_fma_f32 v[194:195], v[60:61], v[182:183], v[194:195]
	v_cvt_pk_bf16_f32 v144, v188, v189
	v_cvt_pk_bf16_f32 v145, v190, v191
	v_cvt_pk_bf16_f32 v146, v192, v193
	v_cvt_pk_bf16_f32 v147, v194, v195
	v_permlane16_swap_b32_e32 v152, v154
	v_permlane16_swap_b32_e32 v153, v155
	v_permlane16_swap_b32_e32 v156, v158
	v_permlane16_swap_b32_e32 v157, v159
	v_lshlrev_b32_e32 v176, 16, v152
	v_and_b32_e32 v177, s18, v152
	v_lshlrev_b32_e32 v178, 16, v153
	v_and_b32_e32 v179, s18, v153
	v_lshlrev_b32_e32 v180, 16, v154
	v_and_b32_e32 v181, s18, v154
	v_lshlrev_b32_e32 v182, 16, v155
	v_and_b32_e32 v183, s18, v155
	v_lshlrev_b32_e32 v188, 16, v156
	v_and_b32_e32 v189, s18, v156
	v_lshlrev_b32_e32 v190, 16, v157
	v_and_b32_e32 v191, s18, v157
	v_lshlrev_b32_e32 v192, 16, v158
	v_and_b32_e32 v193, s18, v158
	v_lshlrev_b32_e32 v194, 16, v159
	v_and_b32_e32 v195, s18, v159
	v_pk_fma_f32 v[188:189], v[54:55], v[176:177], v[188:189]
	v_pk_fma_f32 v[190:191], v[56:57], v[178:179], v[190:191]
	v_pk_fma_f32 v[192:193], v[50:51], v[180:181], v[192:193]
	v_pk_fma_f32 v[194:195], v[52:53], v[182:183], v[194:195]
	v_cvt_pk_bf16_f32 v152, v188, v189
	v_cvt_pk_bf16_f32 v153, v190, v191
	v_cvt_pk_bf16_f32 v154, v192, v193
	v_cvt_pk_bf16_f32 v155, v194, v195
	v_permlane16_swap_b32_e32 v144, v146
	v_permlane16_swap_b32_e32 v145, v147
	global_store_dwordx4 v250, v[144:147], s[16:17]
	v_permlane16_swap_b32_e32 v160, v162
	v_permlane16_swap_b32_e32 v161, v163
	v_permlane16_swap_b32_e32 v164, v166
	v_permlane16_swap_b32_e32 v165, v167
	v_lshlrev_b32_e32 v176, 16, v160
	v_and_b32_e32 v177, s18, v160
	v_lshlrev_b32_e32 v178, 16, v161
	v_and_b32_e32 v179, s18, v161
	v_lshlrev_b32_e32 v180, 16, v162
	v_and_b32_e32 v181, s18, v162
	v_lshlrev_b32_e32 v182, 16, v163
	v_and_b32_e32 v183, s18, v163
	v_lshlrev_b32_e32 v188, 16, v164
	v_and_b32_e32 v189, s18, v164
	v_lshlrev_b32_e32 v190, 16, v165
	v_and_b32_e32 v191, s18, v165
	v_lshlrev_b32_e32 v192, 16, v166
	v_and_b32_e32 v193, s18, v166
	v_lshlrev_b32_e32 v194, 16, v167
	v_and_b32_e32 v195, s18, v167
	v_pk_fma_f32 v[188:189], v[46:47], v[176:177], v[188:189]
	v_pk_fma_f32 v[190:191], v[48:49], v[178:179], v[190:191]
	v_pk_fma_f32 v[192:193], v[42:43], v[180:181], v[192:193]
	v_pk_fma_f32 v[194:195], v[44:45], v[182:183], v[194:195]
	v_cvt_pk_bf16_f32 v160, v188, v189
	v_cvt_pk_bf16_f32 v161, v190, v191
	v_cvt_pk_bf16_f32 v162, v192, v193
	v_cvt_pk_bf16_f32 v163, v194, v195
	v_permlane16_swap_b32_e32 v152, v154
	v_permlane16_swap_b32_e32 v153, v155
	global_store_dwordx4 v251, v[152:155], s[16:17]
	v_permlane16_swap_b32_e32 v168, v170
	v_permlane16_swap_b32_e32 v169, v171
	v_permlane16_swap_b32_e32 v172, v174
	v_permlane16_swap_b32_e32 v173, v175
	v_lshlrev_b32_e32 v176, 16, v168
	v_and_b32_e32 v177, s18, v168
	v_lshlrev_b32_e32 v178, 16, v169
	v_and_b32_e32 v179, s18, v169
	v_lshlrev_b32_e32 v180, 16, v170
	v_and_b32_e32 v181, s18, v170
	v_lshlrev_b32_e32 v182, 16, v171
	v_and_b32_e32 v183, s18, v171
	v_lshlrev_b32_e32 v188, 16, v172
	v_and_b32_e32 v189, s18, v172
	v_lshlrev_b32_e32 v190, 16, v173
	v_and_b32_e32 v191, s18, v173
	v_lshlrev_b32_e32 v192, 16, v174
	v_and_b32_e32 v193, s18, v174
	v_lshlrev_b32_e32 v194, 16, v175
	v_and_b32_e32 v195, s18, v175
	v_pk_fma_f32 v[188:189], v[38:39], v[176:177], v[188:189]
	v_pk_fma_f32 v[190:191], v[40:41], v[178:179], v[190:191]
	v_pk_fma_f32 v[192:193], v[34:35], v[180:181], v[192:193]
	v_pk_fma_f32 v[194:195], v[36:37], v[182:183], v[194:195]
	v_cvt_pk_bf16_f32 v168, v188, v189
	v_cvt_pk_bf16_f32 v169, v190, v191
	v_cvt_pk_bf16_f32 v170, v192, v193
	v_cvt_pk_bf16_f32 v171, v194, v195
	v_permlane16_swap_b32_e32 v160, v162
	v_permlane16_swap_b32_e32 v161, v163
	global_store_dwordx4 v252, v[160:163], s[16:17]
	s_nop 1
	v_permlane16_swap_b32_e32 v168, v170
	v_permlane16_swap_b32_e32 v169, v171
	global_store_dwordx4 v253, v[168:171], s[16:17]
	s_waitcnt vmcnt(4)
; #define GAS __attribute__((address_space(1)))
; __device__ __forceinline__ float bf2f(u16 b) { return __uint_as_float(((uint32_t)b) << 16); }
; __device__ __forceinline__ uint2 pack4(f32x4 v) { return make_uint2(pack2(v[0], v[1]), pack2(v[2], v[3])); }
; template <int MODE>
; __device__ __forceinline__ void epi_elem(char* ws, float* outp, const float* b_gate, int g0, int rl, int col, f32x4 v) {
;     ...
;   } else if (MODE == E_MG) {
;     uint2 g = *(GAS const uint2*)((const u16*)(ws + W_G) + (size_t)rl * 2048 + 1024 + col);
;     uint2 m = *(GAS const uint2*)((const u16*)(ws + W_M1) + (size_t)rl * 1024 + col);
;     f32x4 o;
;     o[0] = bf2f((u16)(m.x & 0xffff)) + v[0] * bf2f((u16)(g.x & 0xffff));
;     o[1] = bf2f((u16)(m.x >> 16)) + v[1] * bf2f((u16)(g.x >> 16));
;     o[2] = bf2f((u16)(m.y & 0xffff)) + v[2] * bf2f((u16)(g.y & 0xffff));
;     o[3] = bf2f((u16)(m.y >> 16)) + v[3] * bf2f((u16)(g.y >> 16));
;     *(GAS uint2*)((u16*)(ws + W_MG) + (size_t)rl * 1024 + col) = pack4(o);
; template <int MODE>
; __device__ __forceinline__ void epi_store(char* ws, float* outp, const float* b_gate, int g0, const f32x4 (&acc)[2][2][4][2], int rbase, int cbase) {
; #pragma unroll
;   for (int ai = 0; ai < 2; ++ai)
; #pragma unroll
;     for (int bj = 0; bj < 2; ++bj)
; #pragma unroll
;       for (int m = 0; m < 4; ++m) {
; #pragma unroll
;         for (int n = 0; n < 2; ++n)
;           epi_elem<MODE>(ws, outp, b_gate, g0, rbase + ai * HALF + m * 16, cbase + bj * HALF + n * 16, acc[ai][bj][m][n]);
;         if ((m & 1) && (MODE != E_M1 && MODE != E_MG)) __builtin_amdgcn_sched_barrier(0);
;         if (m == 3 && (MODE == E_M1 || MODE == E_MG)) __builtin_amdgcn_sched_barrier(0);
;       }
	v_permlane16_swap_b32_e32 v214, v216
	v_permlane16_swap_b32_e32 v215, v217
	v_permlane16_swap_b32_e32 v218, v220
	v_permlane16_swap_b32_e32 v219, v221
	v_lshlrev_b32_e32 v176, 16, v214
	v_and_b32_e32 v177, s18, v214
	v_lshlrev_b32_e32 v178, 16, v215
	v_and_b32_e32 v179, s18, v215
	v_lshlrev_b32_e32 v180, 16, v216
	v_and_b32_e32 v181, s18, v216
	v_lshlrev_b32_e32 v182, 16, v217
	v_and_b32_e32 v183, s18, v217
	v_lshlrev_b32_e32 v188, 16, v218
	v_and_b32_e32 v189, s18, v218
	v_lshlrev_b32_e32 v190, 16, v219
	v_and_b32_e32 v191, s18, v219
	v_lshlrev_b32_e32 v192, 16, v220
	v_and_b32_e32 v193, s18, v220
	v_lshlrev_b32_e32 v194, 16, v221
	v_and_b32_e32 v195, s18, v221
	v_pk_fma_f32 v[188:189], v[30:31], v[176:177], v[188:189]
	v_pk_fma_f32 v[190:191], v[32:33], v[178:179], v[190:191]
	v_pk_fma_f32 v[192:193], v[26:27], v[180:181], v[192:193]
	v_pk_fma_f32 v[194:195], v[28:29], v[182:183], v[194:195]
	v_cvt_pk_bf16_f32 v214, v188, v189
	v_cvt_pk_bf16_f32 v215, v190, v191
	v_cvt_pk_bf16_f32 v216, v192, v193
	v_cvt_pk_bf16_f32 v217, v194, v195
	v_permlane16_swap_b32_e32 v222, v224
	v_permlane16_swap_b32_e32 v223, v225
	v_permlane16_swap_b32_e32 v226, v228
	v_permlane16_swap_b32_e32 v227, v229
	v_lshlrev_b32_e32 v176, 16, v222
	v_and_b32_e32 v177, s18, v222
	v_lshlrev_b32_e32 v178, 16, v223
	v_and_b32_e32 v179, s18, v223
	v_lshlrev_b32_e32 v180, 16, v224
	v_and_b32_e32 v181, s18, v224
	v_lshlrev_b32_e32 v182, 16, v225
	v_and_b32_e32 v183, s18, v225
	v_lshlrev_b32_e32 v188, 16, v226
	v_and_b32_e32 v189, s18, v226
	v_lshlrev_b32_e32 v190, 16, v227
	v_and_b32_e32 v191, s18, v227
	v_lshlrev_b32_e32 v192, 16, v228
	v_and_b32_e32 v193, s18, v228
	v_lshlrev_b32_e32 v194, 16, v229
	v_and_b32_e32 v195, s18, v229
	v_pk_fma_f32 v[188:189], v[22:23], v[176:177], v[188:189]
	v_pk_fma_f32 v[190:191], v[24:25], v[178:179], v[190:191]
	v_pk_fma_f32 v[192:193], v[18:19], v[180:181], v[192:193]
	v_pk_fma_f32 v[194:195], v[20:21], v[182:183], v[194:195]
	v_cvt_pk_bf16_f32 v222, v188, v189
	v_cvt_pk_bf16_f32 v223, v190, v191
	v_cvt_pk_bf16_f32 v224, v192, v193
	v_cvt_pk_bf16_f32 v225, v194, v195
	v_permlane16_swap_b32_e32 v214, v216
	v_permlane16_swap_b32_e32 v215, v217
	global_store_dwordx4 v250, v[214:217], s[16:17] offset:256
	v_permlane16_swap_b32_e32 v230, v232
	v_permlane16_swap_b32_e32 v231, v233
	v_permlane16_swap_b32_e32 v234, v236
	v_permlane16_swap_b32_e32 v235, v237
	v_lshlrev_b32_e32 v176, 16, v230
	v_and_b32_e32 v177, s18, v230
	v_lshlrev_b32_e32 v178, 16, v231
	v_and_b32_e32 v179, s18, v231
	v_lshlrev_b32_e32 v180, 16, v232
	v_and_b32_e32 v181, s18, v232
	v_lshlrev_b32_e32 v182, 16, v233
	v_and_b32_e32 v183, s18, v233
	v_lshlrev_b32_e32 v188, 16, v234
	v_and_b32_e32 v189, s18, v234
	v_lshlrev_b32_e32 v190, 16, v235
	v_and_b32_e32 v191, s18, v235
	v_lshlrev_b32_e32 v192, 16, v236
	v_and_b32_e32 v193, s18, v236
	v_lshlrev_b32_e32 v194, 16, v237
	v_and_b32_e32 v195, s18, v237
	v_pk_fma_f32 v[188:189], v[14:15], v[176:177], v[188:189]
	v_pk_fma_f32 v[190:191], v[16:17], v[178:179], v[190:191]
	v_pk_fma_f32 v[192:193], v[10:11], v[180:181], v[192:193]
	v_pk_fma_f32 v[194:195], v[12:13], v[182:183], v[194:195]
	v_cvt_pk_bf16_f32 v230, v188, v189
	v_cvt_pk_bf16_f32 v231, v190, v191
	v_cvt_pk_bf16_f32 v232, v192, v193
	v_cvt_pk_bf16_f32 v233, v194, v195
	v_permlane16_swap_b32_e32 v222, v224
	v_permlane16_swap_b32_e32 v223, v225
	global_store_dwordx4 v251, v[222:225], s[16:17] offset:256
	v_permlane16_swap_b32_e32 v238, v240
	v_permlane16_swap_b32_e32 v239, v241
	v_permlane16_swap_b32_e32 v242, v244
	v_permlane16_swap_b32_e32 v243, v245
	v_lshlrev_b32_e32 v176, 16, v238
	v_and_b32_e32 v177, s18, v238
	v_lshlrev_b32_e32 v178, 16, v239
	v_and_b32_e32 v179, s18, v239
	v_lshlrev_b32_e32 v180, 16, v240
	v_and_b32_e32 v181, s18, v240
	v_lshlrev_b32_e32 v182, 16, v241
	v_and_b32_e32 v183, s18, v241
	v_lshlrev_b32_e32 v188, 16, v242
	v_and_b32_e32 v189, s18, v242
	v_lshlrev_b32_e32 v190, 16, v243
	v_and_b32_e32 v191, s18, v243
	v_lshlrev_b32_e32 v192, 16, v244
	v_and_b32_e32 v193, s18, v244
	v_lshlrev_b32_e32 v194, 16, v245
	v_and_b32_e32 v195, s18, v245
	v_pk_fma_f32 v[188:189], v[6:7], v[176:177], v[188:189]
	v_pk_fma_f32 v[190:191], v[8:9], v[178:179], v[190:191]
	v_pk_fma_f32 v[192:193], v[2:3], v[180:181], v[192:193]
	v_pk_fma_f32 v[194:195], v[4:5], v[182:183], v[194:195]
	v_cvt_pk_bf16_f32 v238, v188, v189
	v_cvt_pk_bf16_f32 v239, v190, v191
	v_cvt_pk_bf16_f32 v240, v192, v193
	v_cvt_pk_bf16_f32 v241, v194, v195
	v_permlane16_swap_b32_e32 v230, v232
	v_permlane16_swap_b32_e32 v231, v233
	global_store_dwordx4 v252, v[230:233], s[16:17] offset:256
	s_nop 1
	v_permlane16_swap_b32_e32 v238, v240
	v_permlane16_swap_b32_e32 v239, v241
	global_store_dwordx4 v253, v[238:241], s[16:17] offset:256
	s_branch .LBB0_996

; #define GAS __attribute__((address_space(1)))
; __device__ __forceinline__ float bf2f(u16 b) { return __uint_as_float(((uint32_t)b) << 16); }
; __device__ __forceinline__ uint2 pack4(f32x4 v) { return make_uint2(pack2(v[0], v[1]), pack2(v[2], v[3])); }
; template <int MODE>
; __device__ __forceinline__ void epi_elem(char* ws, float* outp, const float* b_gate, int g0, int rl, int col, f32x4 v) {
;     ...
;   } else if (MODE == E_M1) {
;     uint2 g = *(GAS const uint2*)((const u16*)(ws + W_G) + (size_t)rl * 2048 + col);
;     f32x4 o;
;     o[0] = v[0] * bf2f((u16)(g.x & 0xffff)); o[1] = v[1] * bf2f((u16)(g.x >> 16));
;     o[2] = v[2] * bf2f((u16)(g.y & 0xffff)); o[3] = v[3] * bf2f((u16)(g.y >> 16));
;     *(GAS uint2*)((u16*)(ws + W_M1) + (size_t)rl * 1024 + col) = pack4(o);
; template <int MODE>
; __device__ __forceinline__ void epi_store(char* ws, float* outp, const float* b_gate, int g0, const f32x4 (&acc)[2][2][4][2], int rbase, int cbase) {
; #pragma unroll
;   for (int ai = 0; ai < 2; ++ai)
; #pragma unroll
;     for (int bj = 0; bj < 2; ++bj)
; #pragma unroll
;       for (int m = 0; m < 4; ++m) {
; #pragma unroll
;         for (int n = 0; n < 2; ++n)
;           epi_elem<MODE>(ws, outp, b_gate, g0, rbase + ai * HALF + m * 16, cbase + bj * HALF + n * 16, acc[ai][bj][m][n]);
;         if ((m & 1) && (MODE != E_M1 && MODE != E_MG)) __builtin_amdgcn_sched_barrier(0);
;         if (m == 3 && (MODE == E_M1 || MODE == E_MG)) __builtin_amdgcn_sched_barrier(0);
;       }
.LBB0_971:
	s_and_b64 vcc, exec, s[12:13]
	s_cbranch_vccz .LBB0_973
	v_bfe_u32 v141, v184, 2, 2
	v_and_b32_e32 v143, 1, v141
	v_lshrrev_b32_e32 v187, 1, v141
	v_lshlrev_b32_e32 v143, 4, v143
	v_lshl_add_u32 v143, v187, 3, v143
	v_lshlrev_b32_e32 v141, 2, v141
	v_sub_u32_e32 v143, v143, v141
	v_add_u32_e32 v143, v140, v143
	v_lshlrev_b32_e32 v141, 12, v142
	v_lshl_add_u32 v246, v143, 1, v141
	v_add_u32_e32 v247, 0x10000, v246
	v_add_u32_e32 v248, 0x20000, v246
	v_add_u32_e32 v249, 0x30000, v246
	v_lshlrev_b32_e32 v141, 11, v142
	v_lshl_add_u32 v250, v143, 1, v141
	v_add_u32_e32 v251, 0x8000, v250
	v_add_u32_e32 v252, 0x10000, v250
	v_add_u32_e32 v253, 0x18000, v250
	s_add_u32 s4, s2, 0x1aac0000
	s_addc_u32 s5, s3, 0
	s_add_u32 s6, s2, 0x1ab40000
	s_addc_u32 s7, s3, 0
	s_add_u32 s8, s2, 0x2aec0000
	s_addc_u32 s9, s3, 0
	s_add_u32 s12, s2, 0x2af00000
	s_addc_u32 s13, s3, 0
	s_mov_b32 s18, 0xffff0000
	global_load_dwordx4 v[144:147], v246, s[4:5]
	global_load_dwordx4 v[148:151], v247, s[4:5]
	global_load_dwordx4 v[152:155], v248, s[4:5]
	global_load_dwordx4 v[156:159], v249, s[4:5]
	global_load_dwordx4 v[160:163], v246, s[4:5] offset:256
	global_load_dwordx4 v[164:167], v247, s[4:5] offset:256
	global_load_dwordx4 v[168:171], v248, s[4:5] offset:256
	global_load_dwordx4 v[172:175], v249, s[4:5] offset:256
	global_load_dwordx4 v[214:217], v246, s[6:7]
	global_load_dwordx4 v[218:221], v247, s[6:7]
	global_load_dwordx4 v[222:225], v248, s[6:7]
	global_load_dwordx4 v[226:229], v249, s[6:7]
	global_load_dwordx4 v[230:233], v246, s[6:7] offset:256
	global_load_dwordx4 v[234:237], v247, s[6:7] offset:256
	global_load_dwordx4 v[238:241], v248, s[6:7] offset:256
	global_load_dwordx4 v[242:245], v249, s[6:7] offset:256
	s_waitcnt vmcnt(12)
	v_permlane16_swap_b32_e32 v144, v146
	v_permlane16_swap_b32_e32 v145, v147
	v_lshlrev_b32_e32 v176, 16, v144
	v_and_b32_e32 v177, s18, v144
	v_lshlrev_b32_e32 v178, 16, v145
	v_and_b32_e32 v179, s18, v145
	v_lshlrev_b32_e32 v180, 16, v146
	v_and_b32_e32 v181, s18, v146
	v_lshlrev_b32_e32 v182, 16, v147
	v_and_b32_e32 v183, s18, v147
	v_pk_mul_f32 v[176:177], v[126:127], v[176:177]
	v_pk_mul_f32 v[178:179], v[128:129], v[178:179]
	v_pk_mul_f32 v[180:181], v[122:123], v[180:181]
	v_pk_mul_f32 v[182:183], v[124:125], v[182:183]
	v_cvt_pk_bf16_f32 v144, v176, v177
	v_cvt_pk_bf16_f32 v145, v178, v179
	v_cvt_pk_bf16_f32 v146, v180, v181
	v_cvt_pk_bf16_f32 v147, v182, v183
	v_permlane16_swap_b32_e32 v148, v150
	v_permlane16_swap_b32_e32 v149, v151
	v_lshlrev_b32_e32 v188, 16, v148
	v_and_b32_e32 v189, s18, v148
	v_lshlrev_b32_e32 v190, 16, v149
	v_and_b32_e32 v191, s18, v149
	v_lshlrev_b32_e32 v192, 16, v150
	v_and_b32_e32 v193, s18, v150
	v_lshlrev_b32_e32 v194, 16, v151
	v_and_b32_e32 v195, s18, v151
	v_pk_mul_f32 v[188:189], v[118:119], v[188:189]
	v_pk_mul_f32 v[190:191], v[120:121], v[190:191]
	v_pk_mul_f32 v[192:193], v[114:115], v[192:193]
	v_pk_mul_f32 v[194:195], v[116:117], v[194:195]
	v_cvt_pk_bf16_f32 v148, v188, v189
	v_cvt_pk_bf16_f32 v149, v190, v191
	v_cvt_pk_bf16_f32 v150, v192, v193
	v_cvt_pk_bf16_f32 v151, v194, v195
	v_permlane16_swap_b32_e32 v144, v146
	v_permlane16_swap_b32_e32 v145, v147
	global_store_dwordx4 v250, v[144:147], s[8:9]
	v_permlane16_swap_b32_e32 v152, v154
	v_permlane16_swap_b32_e32 v153, v155
	v_lshlrev_b32_e32 v176, 16, v152
	v_and_b32_e32 v177, s18, v152
	v_lshlrev_b32_e32 v178, 16, v153
	v_and_b32_e32 v179, s18, v153
	v_lshlrev_b32_e32 v180, 16, v154
	v_and_b32_e32 v181, s18, v154
	v_lshlrev_b32_e32 v182, 16, v155
	v_and_b32_e32 v183, s18, v155
	v_pk_mul_f32 v[176:177], v[110:111], v[176:177]
	v_pk_mul_f32 v[178:179], v[112:113], v[178:179]
	v_pk_mul_f32 v[180:181], v[106:107], v[180:181]
	v_pk_mul_f32 v[182:183], v[108:109], v[182:183]
	v_cvt_pk_bf16_f32 v152, v176, v177
	v_cvt_pk_bf16_f32 v153, v178, v179
	v_cvt_pk_bf16_f32 v154, v180, v181
	v_cvt_pk_bf16_f32 v155, v182, v183
	v_permlane16_swap_b32_e32 v148, v150
	v_permlane16_swap_b32_e32 v149, v151
	global_store_dwordx4 v251, v[148:151], s[8:9]
	v_permlane16_swap_b32_e32 v156, v158
	v_permlane16_swap_b32_e32 v157, v159
	v_lshlrev_b32_e32 v188, 16, v156
	v_and_b32_e32 v189, s18, v156
	v_lshlrev_b32_e32 v190, 16, v157
	v_and_b32_e32 v191, s18, v157
	v_lshlrev_b32_e32 v192, 16, v158
	v_and_b32_e32 v193, s18, v158
	v_lshlrev_b32_e32 v194, 16, v159
	v_and_b32_e32 v195, s18, v159
	v_pk_mul_f32 v[188:189], v[102:103], v[188:189]
	v_pk_mul_f32 v[190:191], v[104:105], v[190:191]
	v_pk_mul_f32 v[192:193], v[98:99], v[192:193]
	v_pk_mul_f32 v[194:195], v[100:101], v[194:195]
	v_cvt_pk_bf16_f32 v156, v188, v189
	v_cvt_pk_bf16_f32 v157, v190, v191
	v_cvt_pk_bf16_f32 v158, v192, v193
	v_cvt_pk_bf16_f32 v159, v194, v195
	v_permlane16_swap_b32_e32 v152, v154
	v_permlane16_swap_b32_e32 v153, v155
	global_store_dwordx4 v252, v[152:155], s[8:9]
	s_nop 1
	v_permlane16_swap_b32_e32 v156, v158
	v_permlane16_swap_b32_e32 v157, v159
	global_store_dwordx4 v253, v[156:159], s[8:9]
	s_waitcnt vmcnt(12)
; #define GAS __attribute__((address_space(1)))
; __device__ __forceinline__ float bf2f(u16 b) { return __uint_as_float(((uint32_t)b) << 16); }
; __device__ __forceinline__ uint2 pack4(f32x4 v) { return make_uint2(pack2(v[0], v[1]), pack2(v[2], v[3])); }
; template <int MODE>
; __device__ __forceinline__ void epi_elem(char* ws, float* outp, const float* b_gate, int g0, int rl, int col, f32x4 v) {
;     ...
;   } else if (MODE == E_M1) {
;     uint2 g = *(GAS const uint2*)((const u16*)(ws + W_G) + (size_t)rl * 2048 + col);
;     f32x4 o;
;     o[0] = v[0] * bf2f((u16)(g.x & 0xffff)); o[1] = v[1] * bf2f((u16)(g.x >> 16));
;     o[2] = v[2] * bf2f((u16)(g.y & 0xffff)); o[3] = v[3] * bf2f((u16)(g.y >> 16));
;     *(GAS uint2*)((u16*)(ws + W_M1) + (size_t)rl * 1024 + col) = pack4(o);
; template <int MODE>
; __device__ __forceinline__ void epi_store(char* ws, float* outp, const float* b_gate, int g0, const f32x4 (&acc)[2][2][4][2], int rbase, int cbase) {
; #pragma unroll
;   for (int ai = 0; ai < 2; ++ai)
; #pragma unroll
;     for (int bj = 0; bj < 2; ++bj)
; #pragma unroll
;       for (int m = 0; m < 4; ++m) {
; #pragma unroll
;         for (int n = 0; n < 2; ++n)
;           epi_elem<MODE>(ws, outp, b_gate, g0, rbase + ai * HALF + m * 16, cbase + bj * HALF + n * 16, acc[ai][bj][m][n]);
;         if ((m & 1) && (MODE != E_M1 && MODE != E_MG)) __builtin_amdgcn_sched_barrier(0);
;         if (m == 3 && (MODE == E_M1 || MODE == E_MG)) __builtin_amdgcn_sched_barrier(0);
;       }
	v_permlane16_swap_b32_e32 v160, v162
	v_permlane16_swap_b32_e32 v161, v163
	v_lshlrev_b32_e32 v176, 16, v160
	v_and_b32_e32 v177, s18, v160
	v_lshlrev_b32_e32 v178, 16, v161
	v_and_b32_e32 v179, s18, v161
	v_lshlrev_b32_e32 v180, 16, v162
	v_and_b32_e32 v181, s18, v162
	v_lshlrev_b32_e32 v182, 16, v163
	v_and_b32_e32 v183, s18, v163
	v_pk_mul_f32 v[176:177], v[94:95], v[176:177]
	v_pk_mul_f32 v[178:179], v[96:97], v[178:179]
	v_pk_mul_f32 v[180:181], v[90:91], v[180:181]
	v_pk_mul_f32 v[182:183], v[92:93], v[182:183]
	v_cvt_pk_bf16_f32 v160, v176, v177
	v_cvt_pk_bf16_f32 v161, v178, v179
	v_cvt_pk_bf16_f32 v162, v180, v181
	v_cvt_pk_bf16_f32 v163, v182, v183
	v_permlane16_swap_b32_e32 v164, v166
	v_permlane16_swap_b32_e32 v165, v167
	v_lshlrev_b32_e32 v188, 16, v164
	v_and_b32_e32 v189, s18, v164
	v_lshlrev_b32_e32 v190, 16, v165
	v_and_b32_e32 v191, s18, v165
	v_lshlrev_b32_e32 v192, 16, v166
	v_and_b32_e32 v193, s18, v166
	v_lshlrev_b32_e32 v194, 16, v167
	v_and_b32_e32 v195, s18, v167
	v_pk_mul_f32 v[188:189], v[86:87], v[188:189]
	v_pk_mul_f32 v[190:191], v[88:89], v[190:191]
	v_pk_mul_f32 v[192:193], v[82:83], v[192:193]
	v_pk_mul_f32 v[194:195], v[84:85], v[194:195]
	v_cvt_pk_bf16_f32 v164, v188, v189
	v_cvt_pk_bf16_f32 v165, v190, v191
	v_cvt_pk_bf16_f32 v166, v192, v193
	v_cvt_pk_bf16_f32 v167, v194, v195
	v_permlane16_swap_b32_e32 v160, v162
	v_permlane16_swap_b32_e32 v161, v163
	global_store_dwordx4 v250, v[160:163], s[8:9] offset:256
	v_permlane16_swap_b32_e32 v168, v170
	v_permlane16_swap_b32_e32 v169, v171
	v_lshlrev_b32_e32 v176, 16, v168
	v_and_b32_e32 v177, s18, v168
	v_lshlrev_b32_e32 v178, 16, v169
	v_and_b32_e32 v179, s18, v169
	v_lshlrev_b32_e32 v180, 16, v170
	v_and_b32_e32 v181, s18, v170
	v_lshlrev_b32_e32 v182, 16, v171
	v_and_b32_e32 v183, s18, v171
	v_pk_mul_f32 v[176:177], v[78:79], v[176:177]
	v_pk_mul_f32 v[178:179], v[80:81], v[178:179]
	v_pk_mul_f32 v[180:181], v[74:75], v[180:181]
	v_pk_mul_f32 v[182:183], v[76:77], v[182:183]
	v_cvt_pk_bf16_f32 v168, v176, v177
	v_cvt_pk_bf16_f32 v169, v178, v179
	v_cvt_pk_bf16_f32 v170, v180, v181
	v_cvt_pk_bf16_f32 v171, v182, v183
	v_permlane16_swap_b32_e32 v164, v166
	v_permlane16_swap_b32_e32 v165, v167
	global_store_dwordx4 v251, v[164:167], s[8:9] offset:256
	v_permlane16_swap_b32_e32 v172, v174
	v_permlane16_swap_b32_e32 v173, v175
	v_lshlrev_b32_e32 v188, 16, v172
	v_and_b32_e32 v189, s18, v172
	v_lshlrev_b32_e32 v190, 16, v173
	v_and_b32_e32 v191, s18, v173
	v_lshlrev_b32_e32 v192, 16, v174
	v_and_b32_e32 v193, s18, v174
	v_lshlrev_b32_e32 v194, 16, v175
	v_and_b32_e32 v195, s18, v175
	v_pk_mul_f32 v[188:189], v[70:71], v[188:189]
	v_pk_mul_f32 v[190:191], v[72:73], v[190:191]
	v_pk_mul_f32 v[192:193], v[66:67], v[192:193]
	v_pk_mul_f32 v[194:195], v[68:69], v[194:195]
	v_cvt_pk_bf16_f32 v172, v188, v189
	v_cvt_pk_bf16_f32 v173, v190, v191
	v_cvt_pk_bf16_f32 v174, v192, v193
	v_cvt_pk_bf16_f32 v175, v194, v195
	v_permlane16_swap_b32_e32 v168, v170
	v_permlane16_swap_b32_e32 v169, v171
	global_store_dwordx4 v252, v[168:171], s[8:9] offset:256
	s_nop 1
	v_permlane16_swap_b32_e32 v172, v174
	v_permlane16_swap_b32_e32 v173, v175
	global_store_dwordx4 v253, v[172:175], s[8:9] offset:256
	s_waitcnt vmcnt(12)
; #define GAS __attribute__((address_space(1)))
; __device__ __forceinline__ float bf2f(u16 b) { return __uint_as_float(((uint32_t)b) << 16); }
; __device__ __forceinline__ uint2 pack4(f32x4 v) { return make_uint2(pack2(v[0], v[1]), pack2(v[2], v[3])); }
; template <int MODE>
; __device__ __forceinline__ void epi_elem(char* ws, float* outp, const float* b_gate, int g0, int rl, int col, f32x4 v) {
;     ...
;   } else if (MODE == E_M1) {
;     uint2 g = *(GAS const uint2*)((const u16*)(ws + W_G) + (size_t)rl * 2048 + col);
;     f32x4 o;
;     o[0] = v[0] * bf2f((u16)(g.x & 0xffff)); o[1] = v[1] * bf2f((u16)(g.x >> 16));
;     o[2] = v[2] * bf2f((u16)(g.y & 0xffff)); o[3] = v[3] * bf2f((u16)(g.y >> 16));
;     *(GAS uint2*)((u16*)(ws + W_M1) + (size_t)rl * 1024 + col) = pack4(o);
; template <int MODE>
; __device__ __forceinline__ void epi_store(char* ws, float* outp, const float* b_gate, int g0, const f32x4 (&acc)[2][2][4][2], int rbase, int cbase) {
; #pragma unroll
;   for (int ai = 0; ai < 2; ++ai)
; #pragma unroll
;     for (int bj = 0; bj < 2; ++bj)
; #pragma unroll
;       for (int m = 0; m < 4; ++m) {
; #pragma unroll
;         for (int n = 0; n < 2; ++n)
;           epi_elem<MODE>(ws, outp, b_gate, g0, rbase + ai * HALF + m * 16, cbase + bj * HALF + n * 16, acc[ai][bj][m][n]);
;         if ((m & 1) && (MODE != E_M1 && MODE != E_MG)) __builtin_amdgcn_sched_barrier(0);
;         if (m == 3 && (MODE == E_M1 || MODE == E_MG)) __builtin_amdgcn_sched_barrier(0);
;       }
	v_permlane16_swap_b32_e32 v214, v216
	v_permlane16_swap_b32_e32 v215, v217
	v_lshlrev_b32_e32 v176, 16, v214
	v_and_b32_e32 v177, s18, v214
	v_lshlrev_b32_e32 v178, 16, v215
	v_and_b32_e32 v179, s18, v215
	v_lshlrev_b32_e32 v180, 16, v216
	v_and_b32_e32 v181, s18, v216
	v_lshlrev_b32_e32 v182, 16, v217
	v_and_b32_e32 v183, s18, v217
	v_pk_mul_f32 v[176:177], v[62:63], v[176:177]
	v_pk_mul_f32 v[178:179], v[64:65], v[178:179]
	v_pk_mul_f32 v[180:181], v[58:59], v[180:181]
	v_pk_mul_f32 v[182:183], v[60:61], v[182:183]
	v_cvt_pk_bf16_f32 v214, v176, v177
	v_cvt_pk_bf16_f32 v215, v178, v179
	v_cvt_pk_bf16_f32 v216, v180, v181
	v_cvt_pk_bf16_f32 v217, v182, v183
	v_permlane16_swap_b32_e32 v218, v220
	v_permlane16_swap_b32_e32 v219, v221
	v_lshlrev_b32_e32 v188, 16, v218
	v_and_b32_e32 v189, s18, v218
	v_lshlrev_b32_e32 v190, 16, v219
	v_and_b32_e32 v191, s18, v219
	v_lshlrev_b32_e32 v192, 16, v220
	v_and_b32_e32 v193, s18, v220
	v_lshlrev_b32_e32 v194, 16, v221
	v_and_b32_e32 v195, s18, v221
	v_pk_mul_f32 v[188:189], v[54:55], v[188:189]
	v_pk_mul_f32 v[190:191], v[56:57], v[190:191]
	v_pk_mul_f32 v[192:193], v[50:51], v[192:193]
	v_pk_mul_f32 v[194:195], v[52:53], v[194:195]
	v_cvt_pk_bf16_f32 v218, v188, v189
	v_cvt_pk_bf16_f32 v219, v190, v191
	v_cvt_pk_bf16_f32 v220, v192, v193
	v_cvt_pk_bf16_f32 v221, v194, v195
	v_permlane16_swap_b32_e32 v214, v216
	v_permlane16_swap_b32_e32 v215, v217
	global_store_dwordx4 v250, v[214:217], s[12:13]
	v_permlane16_swap_b32_e32 v222, v224
	v_permlane16_swap_b32_e32 v223, v225
	v_lshlrev_b32_e32 v176, 16, v222
	v_and_b32_e32 v177, s18, v222
	v_lshlrev_b32_e32 v178, 16, v223
	v_and_b32_e32 v179, s18, v223
	v_lshlrev_b32_e32 v180, 16, v224
	v_and_b32_e32 v181, s18, v224
	v_lshlrev_b32_e32 v182, 16, v225
	v_and_b32_e32 v183, s18, v225
	v_pk_mul_f32 v[176:177], v[46:47], v[176:177]
	v_pk_mul_f32 v[178:179], v[48:49], v[178:179]
	v_pk_mul_f32 v[180:181], v[42:43], v[180:181]
	v_pk_mul_f32 v[182:183], v[44:45], v[182:183]
	v_cvt_pk_bf16_f32 v222, v176, v177
	v_cvt_pk_bf16_f32 v223, v178, v179
	v_cvt_pk_bf16_f32 v224, v180, v181
	v_cvt_pk_bf16_f32 v225, v182, v183
	v_permlane16_swap_b32_e32 v218, v220
	v_permlane16_swap_b32_e32 v219, v221
	global_store_dwordx4 v251, v[218:221], s[12:13]
	v_permlane16_swap_b32_e32 v226, v228
	v_permlane16_swap_b32_e32 v227, v229
	v_lshlrev_b32_e32 v188, 16, v226
	v_and_b32_e32 v189, s18, v226
	v_lshlrev_b32_e32 v190, 16, v227
	v_and_b32_e32 v191, s18, v227
	v_lshlrev_b32_e32 v192, 16, v228
	v_and_b32_e32 v193, s18, v228
	v_lshlrev_b32_e32 v194, 16, v229
	v_and_b32_e32 v195, s18, v229
	v_pk_mul_f32 v[188:189], v[38:39], v[188:189]
	v_pk_mul_f32 v[190:191], v[40:41], v[190:191]
	v_pk_mul_f32 v[192:193], v[34:35], v[192:193]
	v_pk_mul_f32 v[194:195], v[36:37], v[194:195]
	v_cvt_pk_bf16_f32 v226, v188, v189
	v_cvt_pk_bf16_f32 v227, v190, v191
	v_cvt_pk_bf16_f32 v228, v192, v193
	v_cvt_pk_bf16_f32 v229, v194, v195
	v_permlane16_swap_b32_e32 v222, v224
	v_permlane16_swap_b32_e32 v223, v225
	global_store_dwordx4 v252, v[222:225], s[12:13]
	s_nop 1
	v_permlane16_swap_b32_e32 v226, v228
	v_permlane16_swap_b32_e32 v227, v229
	global_store_dwordx4 v253, v[226:229], s[12:13]
	s_waitcnt vmcnt(12)
	v_permlane16_swap_b32_e32 v230, v232
	v_permlane16_swap_b32_e32 v231, v233
	v_lshlrev_b32_e32 v176, 16, v230
	v_and_b32_e32 v177, s18, v230
	v_lshlrev_b32_e32 v178, 16, v231
	v_and_b32_e32 v179, s18, v231
	v_lshlrev_b32_e32 v180, 16, v232
	v_and_b32_e32 v181, s18, v232
	v_lshlrev_b32_e32 v182, 16, v233
	v_and_b32_e32 v183, s18, v233
	v_pk_mul_f32 v[176:177], v[30:31], v[176:177]
	v_pk_mul_f32 v[178:179], v[32:33], v[178:179]
	v_pk_mul_f32 v[180:181], v[26:27], v[180:181]
	v_pk_mul_f32 v[182:183], v[28:29], v[182:183]
	v_cvt_pk_bf16_f32 v230, v176, v177
	v_cvt_pk_bf16_f32 v231, v178, v179
	v_cvt_pk_bf16_f32 v232, v180, v181
	v_cvt_pk_bf16_f32 v233, v182, v183
	v_permlane16_swap_b32_e32 v234, v236
	v_permlane16_swap_b32_e32 v235, v237
	v_lshlrev_b32_e32 v188, 16, v234
	v_and_b32_e32 v189, s18, v234
	v_lshlrev_b32_e32 v190, 16, v235
	v_and_b32_e32 v191, s18, v235
	v_lshlrev_b32_e32 v192, 16, v236
	v_and_b32_e32 v193, s18, v236
	v_lshlrev_b32_e32 v194, 16, v237
	v_and_b32_e32 v195, s18, v237
	v_pk_mul_f32 v[188:189], v[22:23], v[188:189]
	v_pk_mul_f32 v[190:191], v[24:25], v[190:191]
	v_pk_mul_f32 v[192:193], v[18:19], v[192:193]
	v_pk_mul_f32 v[194:195], v[20:21], v[194:195]
	v_cvt_pk_bf16_f32 v234, v188, v189
	v_cvt_pk_bf16_f32 v235, v190, v191
	v_cvt_pk_bf16_f32 v236, v192, v193
	v_cvt_pk_bf16_f32 v237, v194, v195
	v_permlane16_swap_b32_e32 v230, v232
	v_permlane16_swap_b32_e32 v231, v233
	global_store_dwordx4 v250, v[230:233], s[12:13] offset:256
	v_permlane16_swap_b32_e32 v238, v240
	v_permlane16_swap_b32_e32 v239, v241
	v_lshlrev_b32_e32 v176, 16, v238
	v_and_b32_e32 v177, s18, v238
	v_lshlrev_b32_e32 v178, 16, v239
	v_and_b32_e32 v179, s18, v239
	v_lshlrev_b32_e32 v180, 16, v240
	v_and_b32_e32 v181, s18, v240
	v_lshlrev_b32_e32 v182, 16, v241
	v_and_b32_e32 v183, s18, v241
	v_pk_mul_f32 v[176:177], v[14:15], v[176:177]
	v_pk_mul_f32 v[178:179], v[16:17], v[178:179]
	v_pk_mul_f32 v[180:181], v[10:11], v[180:181]
	v_pk_mul_f32 v[182:183], v[12:13], v[182:183]
	v_cvt_pk_bf16_f32 v238, v176, v177
	v_cvt_pk_bf16_f32 v239, v178, v179
	v_cvt_pk_bf16_f32 v240, v180, v181
	v_cvt_pk_bf16_f32 v241, v182, v183
	v_permlane16_swap_b32_e32 v234, v236
	v_permlane16_swap_b32_e32 v235, v237
	global_store_dwordx4 v251, v[234:237], s[12:13] offset:256
	v_permlane16_swap_b32_e32 v242, v244
	v_permlane16_swap_b32_e32 v243, v245
	v_lshlrev_b32_e32 v188, 16, v242
	v_and_b32_e32 v189, s18, v242
	v_lshlrev_b32_e32 v190, 16, v243
	v_and_b32_e32 v191, s18, v243
	v_lshlrev_b32_e32 v192, 16, v244
	v_and_b32_e32 v193, s18, v244
	v_lshlrev_b32_e32 v194, 16, v245
	v_and_b32_e32 v195, s18, v245
	v_pk_mul_f32 v[188:189], v[6:7], v[188:189]
	v_pk_mul_f32 v[190:191], v[8:9], v[190:191]
	v_pk_mul_f32 v[192:193], v[2:3], v[192:193]
	v_pk_mul_f32 v[194:195], v[4:5], v[194:195]
	v_cvt_pk_bf16_f32 v242, v188, v189
	v_cvt_pk_bf16_f32 v243, v190, v191
	v_cvt_pk_bf16_f32 v244, v192, v193
	v_cvt_pk_bf16_f32 v245, v194, v195
	v_permlane16_swap_b32_e32 v238, v240
	v_permlane16_swap_b32_e32 v239, v241
	global_store_dwordx4 v252, v[238:241], s[12:13] offset:256
	s_nop 1
	v_permlane16_swap_b32_e32 v242, v244
	v_permlane16_swap_b32_e32 v243, v245
	global_store_dwordx4 v253, v[242:245], s[12:13] offset:256
	s_branch .LBB0_996

; #define GAS __attribute__((address_space(1)))
; __device__ __forceinline__ uint2 pack4(f32x4 v) { return make_uint2(pack2(v[0], v[1]), pack2(v[2], v[3])); }
; __device__ __forceinline__ float sigmoid_f(float x) { return __builtin_amdgcn_rcpf(1.0f + __builtin_amdgcn_exp2f(x * -1.4426950408889634f)); }
; template <int MODE>
; __device__ __forceinline__ void epi_elem(char* ws, float* outp, const float* b_gate, int g0, int rl, int col, f32x4 v) {
;     ...
;   } else if (MODE == E_G) {
;     int gc = col - 5120;
;     float4 bg = *(GAS const float4*)(b_gate + gc);
;     f32x4 o;
;     o[0] = sigmoid_f(v[0] + bg.x); o[1] = sigmoid_f(v[1] + bg.y); o[2] = sigmoid_f(v[2] + bg.z); o[3] = sigmoid_f(v[3] + bg.w);
;     *(GAS uint2*)((u16*)(ws + W_G) + (size_t)rl * 2048 + gc) = pack4(o);
; template <int MODE>
; __device__ __forceinline__ void epi_store(char* ws, float* outp, const float* b_gate, int g0, const f32x4 (&acc)[2][2][4][2], int rbase, int cbase) {
; #pragma unroll
;   for (int ai = 0; ai < 2; ++ai)
; #pragma unroll
;     for (int bj = 0; bj < 2; ++bj)
; #pragma unroll
;       for (int m = 0; m < 4; ++m) {
; #pragma unroll
;         for (int n = 0; n < 2; ++n)
;           epi_elem<MODE>(ws, outp, b_gate, g0, rbase + ai * HALF + m * 16, cbase + bj * HALF + n * 16, acc[ai][bj][m][n]);
;         if ((m & 1) && (MODE != E_M1 && MODE != E_MG)) __builtin_amdgcn_sched_barrier(0);
;         if (m == 3 && (MODE == E_M1 || MODE == E_MG)) __builtin_amdgcn_sched_barrier(0);
;       }
.LBB0_974:
	s_and_b64 vcc, exec, s[12:13]
	s_cbranch_vccz .LBB0_979
	s_cmp_gt_i32 s16, 4
	s_mov_b64 s[12:13], -1
	s_cbranch_scc0 .LBB0_977
	v_add_u32_e32 v141, 0xffffec00, v140
	v_lshlrev_b32_e32 v188, 2, v141
	global_load_dwordx4 v[176:179], v188, s[10:11]
	global_load_dwordx4 v[180:183], v188, s[10:11] offset:64
	global_load_dwordx4 v[214:217], v188, s[10:11] offset:512
	global_load_dwordx4 v[218:221], v188, s[10:11] offset:576
	v_bfe_u32 v141, v184, 2, 2
	v_and_b32_e32 v143, 1, v141
	v_lshrrev_b32_e32 v187, 1, v141
	v_lshlrev_b32_e32 v143, 4, v143
	v_lshl_add_u32 v143, v187, 3, v143
	v_lshlrev_b32_e32 v141, 2, v141
	v_sub_u32_e32 v143, v143, v141
	v_add_u32_e32 v143, v140, v143
	v_add_u32_e32 v143, 0xffffec00, v143
	v_lshlrev_b32_e32 v141, 12, v142
	v_lshl_add_u32 v246, v143, 1, v141
	v_add_u32_e32 v247, 0x10000, v246
	v_add_u32_e32 v248, 0x20000, v246
	v_add_u32_e32 v249, 0x30000, v246
	s_add_u32 s4, s2, 0x1aac0000
	s_addc_u32 s5, s3, 0
	s_add_u32 s6, s2, 0x1ab40000
	s_addc_u32 s7, s3, 0
	s_mov_b32 s18, 0xbfb8aa3b
	s_waitcnt vmcnt(0)
	v_add_f32_e32 v160, v126, v176
	v_add_f32_e32 v161, v127, v177
	v_add_f32_e32 v162, v128, v178
	v_add_f32_e32 v163, v129, v179
	v_add_f32_e32 v164, v122, v180
	v_add_f32_e32 v165, v123, v181
	v_add_f32_e32 v166, v124, v182
	v_add_f32_e32 v167, v125, v183
	v_mul_f32_e32 v160, s18, v160
	v_mul_f32_e32 v161, s18, v161
	v_mul_f32_e32 v162, s18, v162
	v_mul_f32_e32 v163, s18, v163
	v_mul_f32_e32 v164, s18, v164
	v_mul_f32_e32 v165, s18, v165
	v_mul_f32_e32 v166, s18, v166
	v_mul_f32_e32 v167, s18, v167
	v_exp_f32_e32 v160, v160
	v_exp_f32_e32 v161, v161
	v_exp_f32_e32 v162, v162
	v_exp_f32_e32 v163, v163
	v_exp_f32_e32 v164, v164
	v_exp_f32_e32 v165, v165
	v_exp_f32_e32 v166, v166
	v_exp_f32_e32 v167, v167
	v_add_f32_e32 v160, 1.0, v160
	v_add_f32_e32 v161, 1.0, v161
	v_add_f32_e32 v162, 1.0, v162
	v_add_f32_e32 v163, 1.0, v163
	v_add_f32_e32 v164, 1.0, v164
	v_add_f32_e32 v165, 1.0, v165
	v_add_f32_e32 v166, 1.0, v166
	v_add_f32_e32 v167, 1.0, v167
	v_rcp_f32_e32 v160, v160
	v_rcp_f32_e32 v161, v161
	v_rcp_f32_e32 v162, v162
	v_rcp_f32_e32 v163, v163
	v_rcp_f32_e32 v164, v164
	v_rcp_f32_e32 v165, v165
	v_rcp_f32_e32 v166, v166
	v_rcp_f32_e32 v167, v167
	v_cvt_pk_bf16_f32 v144, v160, v161
	v_cvt_pk_bf16_f32 v145, v162, v163
	v_cvt_pk_bf16_f32 v146, v164, v165
	v_cvt_pk_bf16_f32 v147, v166, v167
	v_add_f32_e32 v168, v118, v176
	v_add_f32_e32 v169, v119, v177
	v_add_f32_e32 v170, v120, v178
	v_add_f32_e32 v171, v121, v179
	v_add_f32_e32 v172, v114, v180
	v_add_f32_e32 v173, v115, v181
	v_add_f32_e32 v174, v116, v182
	v_add_f32_e32 v175, v117, v183
	v_mul_f32_e32 v168, s18, v168
	v_mul_f32_e32 v169, s18, v169
	v_mul_f32_e32 v170, s18, v170
	v_mul_f32_e32 v171, s18, v171
	v_mul_f32_e32 v172, s18, v172
	v_mul_f32_e32 v173, s18, v173
	v_mul_f32_e32 v174, s18, v174
	v_mul_f32_e32 v175, s18, v175
	v_exp_f32_e32 v168, v168
	v_exp_f32_e32 v169, v169
	v_exp_f32_e32 v170, v170
	v_exp_f32_e32 v171, v171
	v_exp_f32_e32 v172, v172
	v_exp_f32_e32 v173, v173
	v_exp_f32_e32 v174, v174
	v_exp_f32_e32 v175, v175
	v_add_f32_e32 v168, 1.0, v168
	v_add_f32_e32 v169, 1.0, v169
	v_add_f32_e32 v170, 1.0, v170
	v_add_f32_e32 v171, 1.0, v171
	v_add_f32_e32 v172, 1.0, v172
	v_add_f32_e32 v173, 1.0, v173
	v_add_f32_e32 v174, 1.0, v174
	v_add_f32_e32 v175, 1.0, v175
	v_rcp_f32_e32 v168, v168
	v_rcp_f32_e32 v169, v169
	v_rcp_f32_e32 v170, v170
	v_rcp_f32_e32 v171, v171
	v_rcp_f32_e32 v172, v172
	v_rcp_f32_e32 v173, v173
	v_rcp_f32_e32 v174, v174
	v_rcp_f32_e32 v175, v175
	v_cvt_pk_bf16_f32 v148, v168, v169
	v_cvt_pk_bf16_f32 v149, v170, v171
	v_cvt_pk_bf16_f32 v150, v172, v173
	v_cvt_pk_bf16_f32 v151, v174, v175
	v_permlane16_swap_b32_e32 v144, v146
	v_permlane16_swap_b32_e32 v145, v147
	global_store_dwordx4 v246, v[144:147], s[4:5]
	v_add_f32_e32 v160, v110, v176
	v_add_f32_e32 v161, v111, v177
	v_add_f32_e32 v162, v112, v178
	v_add_f32_e32 v163, v113, v179
	v_add_f32_e32 v164, v106, v180
	v_add_f32_e32 v165, v107, v181
	v_add_f32_e32 v166, v108, v182
	v_add_f32_e32 v167, v109, v183
	v_mul_f32_e32 v160, s18, v160
	v_mul_f32_e32 v161, s18, v161
	v_mul_f32_e32 v162, s18, v162
	v_mul_f32_e32 v163, s18, v163
	v_mul_f32_e32 v164, s18, v164
	v_mul_f32_e32 v165, s18, v165
	v_mul_f32_e32 v166, s18, v166
	v_mul_f32_e32 v167, s18, v167
	v_exp_f32_e32 v160, v160
	v_exp_f32_e32 v161, v161
	v_exp_f32_e32 v162, v162
	v_exp_f32_e32 v163, v163
	v_exp_f32_e32 v164, v164
	v_exp_f32_e32 v165, v165
	v_exp_f32_e32 v166, v166
	v_exp_f32_e32 v167, v167
	v_add_f32_e32 v160, 1.0, v160
	v_add_f32_e32 v161, 1.0, v161
	v_add_f32_e32 v162, 1.0, v162
	v_add_f32_e32 v163, 1.0, v163
	v_add_f32_e32 v164, 1.0, v164
	v_add_f32_e32 v165, 1.0, v165
	v_add_f32_e32 v166, 1.0, v166
	v_add_f32_e32 v167, 1.0, v167
	v_rcp_f32_e32 v160, v160
	v_rcp_f32_e32 v161, v161
	v_rcp_f32_e32 v162, v162
	v_rcp_f32_e32 v163, v163
	v_rcp_f32_e32 v164, v164
	v_rcp_f32_e32 v165, v165
	v_rcp_f32_e32 v166, v166
	v_rcp_f32_e32 v167, v167
	v_cvt_pk_bf16_f32 v152, v160, v161
	v_cvt_pk_bf16_f32 v153, v162, v163
	v_cvt_pk_bf16_f32 v154, v164, v165
	v_cvt_pk_bf16_f32 v155, v166, v167
	v_permlane16_swap_b32_e32 v148, v150
	v_permlane16_swap_b32_e32 v149, v151
	global_store_dwordx4 v247, v[148:151], s[4:5]
	v_add_f32_e32 v168, v102, v176
	v_add_f32_e32 v169, v103, v177
	v_add_f32_e32 v170, v104, v178
	v_add_f32_e32 v171, v105, v179
	v_add_f32_e32 v172, v98, v180
	v_add_f32_e32 v173, v99, v181
	v_add_f32_e32 v174, v100, v182
	v_add_f32_e32 v175, v101, v183
	v_mul_f32_e32 v168, s18, v168
	v_mul_f32_e32 v169, s18, v169
	v_mul_f32_e32 v170, s18, v170
	v_mul_f32_e32 v171, s18, v171
	v_mul_f32_e32 v172, s18, v172
; #define GAS __attribute__((address_space(1)))
; __device__ __forceinline__ uint2 pack4(f32x4 v) { return make_uint2(pack2(v[0], v[1]), pack2(v[2], v[3])); }
; __device__ __forceinline__ float sigmoid_f(float x) { return __builtin_amdgcn_rcpf(1.0f + __builtin_amdgcn_exp2f(x * -1.4426950408889634f)); }
; template <int MODE>
; __device__ __forceinline__ void epi_elem(char* ws, float* outp, const float* b_gate, int g0, int rl, int col, f32x4 v) {
;     ...
;   } else if (MODE == E_G) {
;     int gc = col - 5120;
;     float4 bg = *(GAS const float4*)(b_gate + gc);
;     f32x4 o;
;     o[0] = sigmoid_f(v[0] + bg.x); o[1] = sigmoid_f(v[1] + bg.y); o[2] = sigmoid_f(v[2] + bg.z); o[3] = sigmoid_f(v[3] + bg.w);
;     *(GAS uint2*)((u16*)(ws + W_G) + (size_t)rl * 2048 + gc) = pack4(o);
; template <int MODE>
; __device__ __forceinline__ void epi_store(char* ws, float* outp, const float* b_gate, int g0, const f32x4 (&acc)[2][2][4][2], int rbase, int cbase) {
; #pragma unroll
;   for (int ai = 0; ai < 2; ++ai)
; #pragma unroll
;     for (int bj = 0; bj < 2; ++bj)
; #pragma unroll
;       for (int m = 0; m < 4; ++m) {
; #pragma unroll
;         for (int n = 0; n < 2; ++n)
;           epi_elem<MODE>(ws, outp, b_gate, g0, rbase + ai * HALF + m * 16, cbase + bj * HALF + n * 16, acc[ai][bj][m][n]);
;         if ((m & 1) && (MODE != E_M1 && MODE != E_MG)) __builtin_amdgcn_sched_barrier(0);
;         if (m == 3 && (MODE == E_M1 || MODE == E_MG)) __builtin_amdgcn_sched_barrier(0);
;       }
	v_mul_f32_e32 v173, s18, v173
	v_mul_f32_e32 v174, s18, v174
	v_mul_f32_e32 v175, s18, v175
	v_exp_f32_e32 v168, v168
	v_exp_f32_e32 v169, v169
	v_exp_f32_e32 v170, v170
	v_exp_f32_e32 v171, v171
	v_exp_f32_e32 v172, v172
	v_exp_f32_e32 v173, v173
	v_exp_f32_e32 v174, v174
	v_exp_f32_e32 v175, v175
	v_add_f32_e32 v168, 1.0, v168
	v_add_f32_e32 v169, 1.0, v169
	v_add_f32_e32 v170, 1.0, v170
	v_add_f32_e32 v171, 1.0, v171
	v_add_f32_e32 v172, 1.0, v172
	v_add_f32_e32 v173, 1.0, v173
	v_add_f32_e32 v174, 1.0, v174
	v_add_f32_e32 v175, 1.0, v175
	v_rcp_f32_e32 v168, v168
	v_rcp_f32_e32 v169, v169
	v_rcp_f32_e32 v170, v170
	v_rcp_f32_e32 v171, v171
	v_rcp_f32_e32 v172, v172
	v_rcp_f32_e32 v173, v173
	v_rcp_f32_e32 v174, v174
	v_rcp_f32_e32 v175, v175
	v_cvt_pk_bf16_f32 v156, v168, v169
	v_cvt_pk_bf16_f32 v157, v170, v171
	v_cvt_pk_bf16_f32 v158, v172, v173
	v_cvt_pk_bf16_f32 v159, v174, v175
	v_permlane16_swap_b32_e32 v152, v154
	v_permlane16_swap_b32_e32 v153, v155
	global_store_dwordx4 v248, v[152:155], s[4:5]
	v_add_f32_e32 v160, v94, v214
	v_add_f32_e32 v161, v95, v215
	v_add_f32_e32 v162, v96, v216
	v_add_f32_e32 v163, v97, v217
	v_add_f32_e32 v164, v90, v218
	v_add_f32_e32 v165, v91, v219
	v_add_f32_e32 v166, v92, v220
	v_add_f32_e32 v167, v93, v221
	v_mul_f32_e32 v160, s18, v160
	v_mul_f32_e32 v161, s18, v161
	v_mul_f32_e32 v162, s18, v162
	v_mul_f32_e32 v163, s18, v163
	v_mul_f32_e32 v164, s18, v164
	v_mul_f32_e32 v165, s18, v165
	v_mul_f32_e32 v166, s18, v166
	v_mul_f32_e32 v167, s18, v167
	v_exp_f32_e32 v160, v160
	v_exp_f32_e32 v161, v161
	v_exp_f32_e32 v162, v162
	v_exp_f32_e32 v163, v163
	v_exp_f32_e32 v164, v164
	v_exp_f32_e32 v165, v165
	v_exp_f32_e32 v166, v166
	v_exp_f32_e32 v167, v167
	v_add_f32_e32 v160, 1.0, v160
	v_add_f32_e32 v161, 1.0, v161
	v_add_f32_e32 v162, 1.0, v162
	v_add_f32_e32 v163, 1.0, v163
	v_add_f32_e32 v164, 1.0, v164
	v_add_f32_e32 v165, 1.0, v165
	v_add_f32_e32 v166, 1.0, v166
	v_add_f32_e32 v167, 1.0, v167
	v_rcp_f32_e32 v160, v160
	v_rcp_f32_e32 v161, v161
	v_rcp_f32_e32 v162, v162
	v_rcp_f32_e32 v163, v163
	v_rcp_f32_e32 v164, v164
	v_rcp_f32_e32 v165, v165
	v_rcp_f32_e32 v166, v166
	v_rcp_f32_e32 v167, v167
	v_cvt_pk_bf16_f32 v144, v160, v161
	v_cvt_pk_bf16_f32 v145, v162, v163
	v_cvt_pk_bf16_f32 v146, v164, v165
	v_cvt_pk_bf16_f32 v147, v166, v167
	v_permlane16_swap_b32_e32 v156, v158
	v_permlane16_swap_b32_e32 v157, v159
	global_store_dwordx4 v249, v[156:159], s[4:5]
	v_add_f32_e32 v168, v86, v214
	v_add_f32_e32 v169, v87, v215
	v_add_f32_e32 v170, v88, v216
	v_add_f32_e32 v171, v89, v217
	v_add_f32_e32 v172, v82, v218
	v_add_f32_e32 v173, v83, v219
	v_add_f32_e32 v174, v84, v220
	v_add_f32_e32 v175, v85, v221
	v_mul_f32_e32 v168, s18, v168
	v_mul_f32_e32 v169, s18, v169
	v_mul_f32_e32 v170, s18, v170
	v_mul_f32_e32 v171, s18, v171
	v_mul_f32_e32 v172, s18, v172
	v_mul_f32_e32 v173, s18, v173
	v_mul_f32_e32 v174, s18, v174
	v_mul_f32_e32 v175, s18, v175
	v_exp_f32_e32 v168, v168
	v_exp_f32_e32 v169, v169
	v_exp_f32_e32 v170, v170
	v_exp_f32_e32 v171, v171
	v_exp_f32_e32 v172, v172
	v_exp_f32_e32 v173, v173
	v_exp_f32_e32 v174, v174
	v_exp_f32_e32 v175, v175
	v_add_f32_e32 v168, 1.0, v168
	v_add_f32_e32 v169, 1.0, v169
	v_add_f32_e32 v170, 1.0, v170
	v_add_f32_e32 v171, 1.0, v171
	v_add_f32_e32 v172, 1.0, v172
	v_add_f32_e32 v173, 1.0, v173
	v_add_f32_e32 v174, 1.0, v174
	v_add_f32_e32 v175, 1.0, v175
	v_rcp_f32_e32 v168, v168
	v_rcp_f32_e32 v169, v169
	v_rcp_f32_e32 v170, v170
	v_rcp_f32_e32 v171, v171
	v_rcp_f32_e32 v172, v172
	v_rcp_f32_e32 v173, v173
	v_rcp_f32_e32 v174, v174
	v_rcp_f32_e32 v175, v175
	v_cvt_pk_bf16_f32 v148, v168, v169
	v_cvt_pk_bf16_f32 v149, v170, v171
	v_cvt_pk_bf16_f32 v150, v172, v173
	v_cvt_pk_bf16_f32 v151, v174, v175
	v_permlane16_swap_b32_e32 v144, v146
	v_permlane16_swap_b32_e32 v145, v147
	global_store_dwordx4 v246, v[144:147], s[4:5] offset:256
	v_add_f32_e32 v160, v78, v214
	v_add_f32_e32 v161, v79, v215
	v_add_f32_e32 v162, v80, v216
	v_add_f32_e32 v163, v81, v217
	v_add_f32_e32 v164, v74, v218
	v_add_f32_e32 v165, v75, v219
	v_add_f32_e32 v166, v76, v220
	v_add_f32_e32 v167, v77, v221
	v_mul_f32_e32 v160, s18, v160
	v_mul_f32_e32 v161, s18, v161
	v_mul_f32_e32 v162, s18, v162
	v_mul_f32_e32 v163, s18, v163
	v_mul_f32_e32 v164, s18, v164
	v_mul_f32_e32 v165, s18, v165
	v_mul_f32_e32 v166, s18, v166
	v_mul_f32_e32 v167, s18, v167
	v_exp_f32_e32 v160, v160
	v_exp_f32_e32 v161, v161
	v_exp_f32_e32 v162, v162
	v_exp_f32_e32 v163, v163
	v_exp_f32_e32 v164, v164
	v_exp_f32_e32 v165, v165
	v_exp_f32_e32 v166, v166
	v_exp_f32_e32 v167, v167
	v_add_f32_e32 v160, 1.0, v160
	v_add_f32_e32 v161, 1.0, v161
	v_add_f32_e32 v162, 1.0, v162
	v_add_f32_e32 v163, 1.0, v163
	v_add_f32_e32 v164, 1.0, v164
	v_add_f32_e32 v165, 1.0, v165
	v_add_f32_e32 v166, 1.0, v166
	v_add_f32_e32 v167, 1.0, v167
	v_rcp_f32_e32 v160, v160
	v_rcp_f32_e32 v161, v161
	v_rcp_f32_e32 v162, v162
	v_rcp_f32_e32 v163, v163
	v_rcp_f32_e32 v164, v164
	v_rcp_f32_e32 v165, v165
	v_rcp_f32_e32 v166, v166
	v_rcp_f32_e32 v167, v167
	v_cvt_pk_bf16_f32 v152, v160, v161
	v_cvt_pk_bf16_f32 v153, v162, v163
	v_cvt_pk_bf16_f32 v154, v164, v165
	v_cvt_pk_bf16_f32 v155, v166, v167
	v_permlane16_swap_b32_e32 v148, v150
	v_permlane16_swap_b32_e32 v149, v151
	global_store_dwordx4 v247, v[148:151], s[4:5] offset:256
	v_add_f32_e32 v168, v70, v214
	v_add_f32_e32 v169, v71, v215
	v_add_f32_e32 v170, v72, v216
	v_add_f32_e32 v171, v73, v217
	v_add_f32_e32 v172, v66, v218
	v_add_f32_e32 v173, v67, v219
	v_add_f32_e32 v174, v68, v220
	v_add_f32_e32 v175, v69, v221
	v_mul_f32_e32 v168, s18, v168
	v_mul_f32_e32 v169, s18, v169
; #define GAS __attribute__((address_space(1)))
; __device__ __forceinline__ uint2 pack4(f32x4 v) { return make_uint2(pack2(v[0], v[1]), pack2(v[2], v[3])); }
; __device__ __forceinline__ float sigmoid_f(float x) { return __builtin_amdgcn_rcpf(1.0f + __builtin_amdgcn_exp2f(x * -1.4426950408889634f)); }
; template <int MODE>
; __device__ __forceinline__ void epi_elem(char* ws, float* outp, const float* b_gate, int g0, int rl, int col, f32x4 v) {
;     ...
;   } else if (MODE == E_G) {
;     int gc = col - 5120;
;     float4 bg = *(GAS const float4*)(b_gate + gc);
;     f32x4 o;
;     o[0] = sigmoid_f(v[0] + bg.x); o[1] = sigmoid_f(v[1] + bg.y); o[2] = sigmoid_f(v[2] + bg.z); o[3] = sigmoid_f(v[3] + bg.w);
;     *(GAS uint2*)((u16*)(ws + W_G) + (size_t)rl * 2048 + gc) = pack4(o);
; template <int MODE>
; __device__ __forceinline__ void epi_store(char* ws, float* outp, const float* b_gate, int g0, const f32x4 (&acc)[2][2][4][2], int rbase, int cbase) {
; #pragma unroll
;   for (int ai = 0; ai < 2; ++ai)
; #pragma unroll
;     for (int bj = 0; bj < 2; ++bj)
; #pragma unroll
;       for (int m = 0; m < 4; ++m) {
; #pragma unroll
;         for (int n = 0; n < 2; ++n)
;           epi_elem<MODE>(ws, outp, b_gate, g0, rbase + ai * HALF + m * 16, cbase + bj * HALF + n * 16, acc[ai][bj][m][n]);
;         if ((m & 1) && (MODE != E_M1 && MODE != E_MG)) __builtin_amdgcn_sched_barrier(0);
;         if (m == 3 && (MODE == E_M1 || MODE == E_MG)) __builtin_amdgcn_sched_barrier(0);
;       }
	v_mul_f32_e32 v170, s18, v170
	v_mul_f32_e32 v171, s18, v171
	v_mul_f32_e32 v172, s18, v172
	v_mul_f32_e32 v173, s18, v173
	v_mul_f32_e32 v174, s18, v174
	v_mul_f32_e32 v175, s18, v175
	v_exp_f32_e32 v168, v168
	v_exp_f32_e32 v169, v169
	v_exp_f32_e32 v170, v170
	v_exp_f32_e32 v171, v171
	v_exp_f32_e32 v172, v172
	v_exp_f32_e32 v173, v173
	v_exp_f32_e32 v174, v174
	v_exp_f32_e32 v175, v175
	v_add_f32_e32 v168, 1.0, v168
	v_add_f32_e32 v169, 1.0, v169
	v_add_f32_e32 v170, 1.0, v170
	v_add_f32_e32 v171, 1.0, v171
	v_add_f32_e32 v172, 1.0, v172
	v_add_f32_e32 v173, 1.0, v173
	v_add_f32_e32 v174, 1.0, v174
	v_add_f32_e32 v175, 1.0, v175
	v_rcp_f32_e32 v168, v168
	v_rcp_f32_e32 v169, v169
	v_rcp_f32_e32 v170, v170
	v_rcp_f32_e32 v171, v171
	v_rcp_f32_e32 v172, v172
	v_rcp_f32_e32 v173, v173
	v_rcp_f32_e32 v174, v174
	v_rcp_f32_e32 v175, v175
	v_cvt_pk_bf16_f32 v156, v168, v169
	v_cvt_pk_bf16_f32 v157, v170, v171
	v_cvt_pk_bf16_f32 v158, v172, v173
	v_cvt_pk_bf16_f32 v159, v174, v175
	v_permlane16_swap_b32_e32 v152, v154
	v_permlane16_swap_b32_e32 v153, v155
	global_store_dwordx4 v248, v[152:155], s[4:5] offset:256
	v_add_f32_e32 v160, v62, v176
	v_add_f32_e32 v161, v63, v177
	v_add_f32_e32 v162, v64, v178
	v_add_f32_e32 v163, v65, v179
	v_add_f32_e32 v164, v58, v180
	v_add_f32_e32 v165, v59, v181
	v_add_f32_e32 v166, v60, v182
	v_add_f32_e32 v167, v61, v183
	v_mul_f32_e32 v160, s18, v160
	v_mul_f32_e32 v161, s18, v161
	v_mul_f32_e32 v162, s18, v162
	v_mul_f32_e32 v163, s18, v163
	v_mul_f32_e32 v164, s18, v164
	v_mul_f32_e32 v165, s18, v165
	v_mul_f32_e32 v166, s18, v166
	v_mul_f32_e32 v167, s18, v167
	v_exp_f32_e32 v160, v160
	v_exp_f32_e32 v161, v161
	v_exp_f32_e32 v162, v162
	v_exp_f32_e32 v163, v163
	v_exp_f32_e32 v164, v164
	v_exp_f32_e32 v165, v165
	v_exp_f32_e32 v166, v166
	v_exp_f32_e32 v167, v167
	v_add_f32_e32 v160, 1.0, v160
	v_add_f32_e32 v161, 1.0, v161
	v_add_f32_e32 v162, 1.0, v162
	v_add_f32_e32 v163, 1.0, v163
	v_add_f32_e32 v164, 1.0, v164
	v_add_f32_e32 v165, 1.0, v165
	v_add_f32_e32 v166, 1.0, v166
	v_add_f32_e32 v167, 1.0, v167
	v_rcp_f32_e32 v160, v160
	v_rcp_f32_e32 v161, v161
	v_rcp_f32_e32 v162, v162
	v_rcp_f32_e32 v163, v163
	v_rcp_f32_e32 v164, v164
	v_rcp_f32_e32 v165, v165
	v_rcp_f32_e32 v166, v166
	v_rcp_f32_e32 v167, v167
	v_cvt_pk_bf16_f32 v144, v160, v161
	v_cvt_pk_bf16_f32 v145, v162, v163
	v_cvt_pk_bf16_f32 v146, v164, v165
	v_cvt_pk_bf16_f32 v147, v166, v167
	v_permlane16_swap_b32_e32 v156, v158
	v_permlane16_swap_b32_e32 v157, v159
	global_store_dwordx4 v249, v[156:159], s[4:5] offset:256
	v_add_f32_e32 v168, v54, v176
	v_add_f32_e32 v169, v55, v177
	v_add_f32_e32 v170, v56, v178
	v_add_f32_e32 v171, v57, v179
	v_add_f32_e32 v172, v50, v180
	v_add_f32_e32 v173, v51, v181
	v_add_f32_e32 v174, v52, v182
	v_add_f32_e32 v175, v53, v183
	v_mul_f32_e32 v168, s18, v168
	v_mul_f32_e32 v169, s18, v169
	v_mul_f32_e32 v170, s18, v170
	v_mul_f32_e32 v171, s18, v171
	v_mul_f32_e32 v172, s18, v172
	v_mul_f32_e32 v173, s18, v173
	v_mul_f32_e32 v174, s18, v174
	v_mul_f32_e32 v175, s18, v175
	v_exp_f32_e32 v168, v168
	v_exp_f32_e32 v169, v169
	v_exp_f32_e32 v170, v170
	v_exp_f32_e32 v171, v171
	v_exp_f32_e32 v172, v172
	v_exp_f32_e32 v173, v173
	v_exp_f32_e32 v174, v174
	v_exp_f32_e32 v175, v175
	v_add_f32_e32 v168, 1.0, v168
	v_add_f32_e32 v169, 1.0, v169
	v_add_f32_e32 v170, 1.0, v170
	v_add_f32_e32 v171, 1.0, v171
	v_add_f32_e32 v172, 1.0, v172
	v_add_f32_e32 v173, 1.0, v173
	v_add_f32_e32 v174, 1.0, v174
	v_add_f32_e32 v175, 1.0, v175
	v_rcp_f32_e32 v168, v168
	v_rcp_f32_e32 v169, v169
	v_rcp_f32_e32 v170, v170
	v_rcp_f32_e32 v171, v171
	v_rcp_f32_e32 v172, v172
	v_rcp_f32_e32 v173, v173
	v_rcp_f32_e32 v174, v174
	v_rcp_f32_e32 v175, v175
	v_cvt_pk_bf16_f32 v148, v168, v169
	v_cvt_pk_bf16_f32 v149, v170, v171
	v_cvt_pk_bf16_f32 v150, v172, v173
	v_cvt_pk_bf16_f32 v151, v174, v175
	v_permlane16_swap_b32_e32 v144, v146
	v_permlane16_swap_b32_e32 v145, v147
	global_store_dwordx4 v246, v[144:147], s[6:7]
	v_add_f32_e32 v160, v46, v176
	v_add_f32_e32 v161, v47, v177
	v_add_f32_e32 v162, v48, v178
	v_add_f32_e32 v163, v49, v179
	v_add_f32_e32 v164, v42, v180
	v_add_f32_e32 v165, v43, v181
	v_add_f32_e32 v166, v44, v182
	v_add_f32_e32 v167, v45, v183
	v_mul_f32_e32 v160, s18, v160
	v_mul_f32_e32 v161, s18, v161
	v_mul_f32_e32 v162, s18, v162
	v_mul_f32_e32 v163, s18, v163
	v_mul_f32_e32 v164, s18, v164
	v_mul_f32_e32 v165, s18, v165
	v_mul_f32_e32 v166, s18, v166
	v_mul_f32_e32 v167, s18, v167
	v_exp_f32_e32 v160, v160
	v_exp_f32_e32 v161, v161
	v_exp_f32_e32 v162, v162
	v_exp_f32_e32 v163, v163
	v_exp_f32_e32 v164, v164
	v_exp_f32_e32 v165, v165
	v_exp_f32_e32 v166, v166
	v_exp_f32_e32 v167, v167
	v_add_f32_e32 v160, 1.0, v160
	v_add_f32_e32 v161, 1.0, v161
	v_add_f32_e32 v162, 1.0, v162
	v_add_f32_e32 v163, 1.0, v163
	v_add_f32_e32 v164, 1.0, v164
	v_add_f32_e32 v165, 1.0, v165
	v_add_f32_e32 v166, 1.0, v166
	v_add_f32_e32 v167, 1.0, v167
	v_rcp_f32_e32 v160, v160
	v_rcp_f32_e32 v161, v161
	v_rcp_f32_e32 v162, v162
	v_rcp_f32_e32 v163, v163
	v_rcp_f32_e32 v164, v164
	v_rcp_f32_e32 v165, v165
	v_rcp_f32_e32 v166, v166
	v_rcp_f32_e32 v167, v167
	v_cvt_pk_bf16_f32 v152, v160, v161
	v_cvt_pk_bf16_f32 v153, v162, v163
	v_cvt_pk_bf16_f32 v154, v164, v165
	v_cvt_pk_bf16_f32 v155, v166, v167
	v_permlane16_swap_b32_e32 v148, v150
	v_permlane16_swap_b32_e32 v149, v151
	global_store_dwordx4 v247, v[148:151], s[6:7]
	v_add_f32_e32 v168, v38, v176
	v_add_f32_e32 v169, v39, v177
	v_add_f32_e32 v170, v40, v178
	v_add_f32_e32 v171, v41, v179
	v_add_f32_e32 v172, v34, v180
	v_add_f32_e32 v173, v35, v181
	v_add_f32_e32 v174, v36, v182
; #define GAS __attribute__((address_space(1)))
; __device__ __forceinline__ uint2 pack4(f32x4 v) { return make_uint2(pack2(v[0], v[1]), pack2(v[2], v[3])); }
; __device__ __forceinline__ float sigmoid_f(float x) { return __builtin_amdgcn_rcpf(1.0f + __builtin_amdgcn_exp2f(x * -1.4426950408889634f)); }
; template <int MODE>
; __device__ __forceinline__ void epi_elem(char* ws, float* outp, const float* b_gate, int g0, int rl, int col, f32x4 v) {
;     ...
;   } else if (MODE == E_G) {
;     int gc = col - 5120;
;     float4 bg = *(GAS const float4*)(b_gate + gc);
;     f32x4 o;
;     o[0] = sigmoid_f(v[0] + bg.x); o[1] = sigmoid_f(v[1] + bg.y); o[2] = sigmoid_f(v[2] + bg.z); o[3] = sigmoid_f(v[3] + bg.w);
;     *(GAS uint2*)((u16*)(ws + W_G) + (size_t)rl * 2048 + gc) = pack4(o);
; template <int MODE>
; __device__ __forceinline__ void epi_store(char* ws, float* outp, const float* b_gate, int g0, const f32x4 (&acc)[2][2][4][2], int rbase, int cbase) {
; #pragma unroll
;   for (int ai = 0; ai < 2; ++ai)
; #pragma unroll
;     for (int bj = 0; bj < 2; ++bj)
; #pragma unroll
;       for (int m = 0; m < 4; ++m) {
; #pragma unroll
;         for (int n = 0; n < 2; ++n)
;           epi_elem<MODE>(ws, outp, b_gate, g0, rbase + ai * HALF + m * 16, cbase + bj * HALF + n * 16, acc[ai][bj][m][n]);
;         if ((m & 1) && (MODE != E_M1 && MODE != E_MG)) __builtin_amdgcn_sched_barrier(0);
;         if (m == 3 && (MODE == E_M1 || MODE == E_MG)) __builtin_amdgcn_sched_barrier(0);
;       }
	v_add_f32_e32 v175, v37, v183
	v_mul_f32_e32 v168, s18, v168
	v_mul_f32_e32 v169, s18, v169
	v_mul_f32_e32 v170, s18, v170
	v_mul_f32_e32 v171, s18, v171
	v_mul_f32_e32 v172, s18, v172
	v_mul_f32_e32 v173, s18, v173
	v_mul_f32_e32 v174, s18, v174
	v_mul_f32_e32 v175, s18, v175
	v_exp_f32_e32 v168, v168
	v_exp_f32_e32 v169, v169
	v_exp_f32_e32 v170, v170
	v_exp_f32_e32 v171, v171
	v_exp_f32_e32 v172, v172
	v_exp_f32_e32 v173, v173
	v_exp_f32_e32 v174, v174
	v_exp_f32_e32 v175, v175
	v_add_f32_e32 v168, 1.0, v168
	v_add_f32_e32 v169, 1.0, v169
	v_add_f32_e32 v170, 1.0, v170
	v_add_f32_e32 v171, 1.0, v171
	v_add_f32_e32 v172, 1.0, v172
	v_add_f32_e32 v173, 1.0, v173
	v_add_f32_e32 v174, 1.0, v174
	v_add_f32_e32 v175, 1.0, v175
	v_rcp_f32_e32 v168, v168
	v_rcp_f32_e32 v169, v169
	v_rcp_f32_e32 v170, v170
	v_rcp_f32_e32 v171, v171
	v_rcp_f32_e32 v172, v172
	v_rcp_f32_e32 v173, v173
	v_rcp_f32_e32 v174, v174
	v_rcp_f32_e32 v175, v175
	v_cvt_pk_bf16_f32 v156, v168, v169
	v_cvt_pk_bf16_f32 v157, v170, v171
	v_cvt_pk_bf16_f32 v158, v172, v173
	v_cvt_pk_bf16_f32 v159, v174, v175
	v_permlane16_swap_b32_e32 v152, v154
	v_permlane16_swap_b32_e32 v153, v155
	global_store_dwordx4 v248, v[152:155], s[6:7]
	v_add_f32_e32 v160, v30, v214
	v_add_f32_e32 v161, v31, v215
	v_add_f32_e32 v162, v32, v216
	v_add_f32_e32 v163, v33, v217
	v_add_f32_e32 v164, v26, v218
	v_add_f32_e32 v165, v27, v219
	v_add_f32_e32 v166, v28, v220
	v_add_f32_e32 v167, v29, v221
	v_mul_f32_e32 v160, s18, v160
	v_mul_f32_e32 v161, s18, v161
	v_mul_f32_e32 v162, s18, v162
	v_mul_f32_e32 v163, s18, v163
	v_mul_f32_e32 v164, s18, v164
	v_mul_f32_e32 v165, s18, v165
	v_mul_f32_e32 v166, s18, v166
	v_mul_f32_e32 v167, s18, v167
	v_exp_f32_e32 v160, v160
	v_exp_f32_e32 v161, v161
	v_exp_f32_e32 v162, v162
	v_exp_f32_e32 v163, v163
	v_exp_f32_e32 v164, v164
	v_exp_f32_e32 v165, v165
	v_exp_f32_e32 v166, v166
	v_exp_f32_e32 v167, v167
	v_add_f32_e32 v160, 1.0, v160
	v_add_f32_e32 v161, 1.0, v161
	v_add_f32_e32 v162, 1.0, v162
	v_add_f32_e32 v163, 1.0, v163
	v_add_f32_e32 v164, 1.0, v164
	v_add_f32_e32 v165, 1.0, v165
	v_add_f32_e32 v166, 1.0, v166
	v_add_f32_e32 v167, 1.0, v167
	v_rcp_f32_e32 v160, v160
	v_rcp_f32_e32 v161, v161
	v_rcp_f32_e32 v162, v162
	v_rcp_f32_e32 v163, v163
	v_rcp_f32_e32 v164, v164
	v_rcp_f32_e32 v165, v165
	v_rcp_f32_e32 v166, v166
	v_rcp_f32_e32 v167, v167
	v_cvt_pk_bf16_f32 v144, v160, v161
	v_cvt_pk_bf16_f32 v145, v162, v163
	v_cvt_pk_bf16_f32 v146, v164, v165
	v_cvt_pk_bf16_f32 v147, v166, v167
	v_permlane16_swap_b32_e32 v156, v158
	v_permlane16_swap_b32_e32 v157, v159
	global_store_dwordx4 v249, v[156:159], s[6:7]
	v_add_f32_e32 v168, v22, v214
	v_add_f32_e32 v169, v23, v215
	v_add_f32_e32 v170, v24, v216
	v_add_f32_e32 v171, v25, v217
	v_add_f32_e32 v172, v18, v218
	v_add_f32_e32 v173, v19, v219
	v_add_f32_e32 v174, v20, v220
	v_add_f32_e32 v175, v21, v221
	v_mul_f32_e32 v168, s18, v168
	v_mul_f32_e32 v169, s18, v169
	v_mul_f32_e32 v170, s18, v170
	v_mul_f32_e32 v171, s18, v171
	v_mul_f32_e32 v172, s18, v172
	v_mul_f32_e32 v173, s18, v173
	v_mul_f32_e32 v174, s18, v174
	v_mul_f32_e32 v175, s18, v175
	v_exp_f32_e32 v168, v168
	v_exp_f32_e32 v169, v169
	v_exp_f32_e32 v170, v170
	v_exp_f32_e32 v171, v171
	v_exp_f32_e32 v172, v172
	v_exp_f32_e32 v173, v173
	v_exp_f32_e32 v174, v174
	v_exp_f32_e32 v175, v175
	v_add_f32_e32 v168, 1.0, v168
	v_add_f32_e32 v169, 1.0, v169
	v_add_f32_e32 v170, 1.0, v170
	v_add_f32_e32 v171, 1.0, v171
	v_add_f32_e32 v172, 1.0, v172
	v_add_f32_e32 v173, 1.0, v173
	v_add_f32_e32 v174, 1.0, v174
; #define GAS __attribute__((address_space(1)))
; __device__ __forceinline__ uint2 pack4(f32x4 v) { return make_uint2(pack2(v[0], v[1]), pack2(v[2], v[3])); }
; __device__ __forceinline__ float sigmoid_f(float x) { return __builtin_amdgcn_rcpf(1.0f + __builtin_amdgcn_exp2f(x * -1.4426950408889634f)); }
; template <int MODE>
; __device__ __forceinline__ void epi_elem(char* ws, float* outp, const float* b_gate, int g0, int rl, int col, f32x4 v) {
;     ...
;   } else if (MODE == E_G) {
;     int gc = col - 5120;
;     float4 bg = *(GAS const float4*)(b_gate + gc);
;     f32x4 o;
;     o[0] = sigmoid_f(v[0] + bg.x); o[1] = sigmoid_f(v[1] + bg.y); o[2] = sigmoid_f(v[2] + bg.z); o[3] = sigmoid_f(v[3] + bg.w);
;     *(GAS uint2*)((u16*)(ws + W_G) + (size_t)rl * 2048 + gc) = pack4(o);
; template <int MODE>
; __device__ __forceinline__ void epi_store(char* ws, float* outp, const float* b_gate, int g0, const f32x4 (&acc)[2][2][4][2], int rbase, int cbase) {
; #pragma unroll
;   for (int ai = 0; ai < 2; ++ai)
; #pragma unroll
;     for (int bj = 0; bj < 2; ++bj)
; #pragma unroll
;       for (int m = 0; m < 4; ++m) {
; #pragma unroll
;         for (int n = 0; n < 2; ++n)
;           epi_elem<MODE>(ws, outp, b_gate, g0, rbase + ai * HALF + m * 16, cbase + bj * HALF + n * 16, acc[ai][bj][m][n]);
;         if ((m & 1) && (MODE != E_M1 && MODE != E_MG)) __builtin_amdgcn_sched_barrier(0);
;         if (m == 3 && (MODE == E_M1 || MODE == E_MG)) __builtin_amdgcn_sched_barrier(0);
;       }
	v_add_f32_e32 v175, 1.0, v175
	v_rcp_f32_e32 v168, v168
	v_rcp_f32_e32 v169, v169
	v_rcp_f32_e32 v170, v170
	v_rcp_f32_e32 v171, v171
	v_rcp_f32_e32 v172, v172
	v_rcp_f32_e32 v173, v173
	v_rcp_f32_e32 v174, v174
	v_rcp_f32_e32 v175, v175
	v_cvt_pk_bf16_f32 v148, v168, v169
	v_cvt_pk_bf16_f32 v149, v170, v171
	v_cvt_pk_bf16_f32 v150, v172, v173
	v_cvt_pk_bf16_f32 v151, v174, v175
	v_permlane16_swap_b32_e32 v144, v146
	v_permlane16_swap_b32_e32 v145, v147
	global_store_dwordx4 v246, v[144:147], s[6:7] offset:256
	v_add_f32_e32 v160, v14, v214
	v_add_f32_e32 v161, v15, v215
	v_add_f32_e32 v162, v16, v216
	v_add_f32_e32 v163, v17, v217
	v_add_f32_e32 v164, v10, v218
	v_add_f32_e32 v165, v11, v219
	v_add_f32_e32 v166, v12, v220
	v_add_f32_e32 v167, v13, v221
	v_mul_f32_e32 v160, s18, v160
	v_mul_f32_e32 v161, s18, v161
	v_mul_f32_e32 v162, s18, v162
	v_mul_f32_e32 v163, s18, v163
	v_mul_f32_e32 v164, s18, v164
	v_mul_f32_e32 v165, s18, v165
	v_mul_f32_e32 v166, s18, v166
	v_mul_f32_e32 v167, s18, v167
	v_exp_f32_e32 v160, v160
	v_exp_f32_e32 v161, v161
	v_exp_f32_e32 v162, v162
	v_exp_f32_e32 v163, v163
	v_exp_f32_e32 v164, v164
	v_exp_f32_e32 v165, v165
	v_exp_f32_e32 v166, v166
	v_exp_f32_e32 v167, v167
	v_add_f32_e32 v160, 1.0, v160
	v_add_f32_e32 v161, 1.0, v161
	v_add_f32_e32 v162, 1.0, v162
	v_add_f32_e32 v163, 1.0, v163
	v_add_f32_e32 v164, 1.0, v164
	v_add_f32_e32 v165, 1.0, v165
	v_add_f32_e32 v166, 1.0, v166
	v_add_f32_e32 v167, 1.0, v167
	v_rcp_f32_e32 v160, v160
	v_rcp_f32_e32 v161, v161
	v_rcp_f32_e32 v162, v162
	v_rcp_f32_e32 v163, v163
	v_rcp_f32_e32 v164, v164
	v_rcp_f32_e32 v165, v165
	v_rcp_f32_e32 v166, v166
	v_rcp_f32_e32 v167, v167
	v_cvt_pk_bf16_f32 v152, v160, v161
	v_cvt_pk_bf16_f32 v153, v162, v163
	v_cvt_pk_bf16_f32 v154, v164, v165
	v_cvt_pk_bf16_f32 v155, v166, v167
	v_permlane16_swap_b32_e32 v148, v150
	v_permlane16_swap_b32_e32 v149, v151
	global_store_dwordx4 v247, v[148:151], s[6:7] offset:256
	v_add_f32_e32 v168, v6, v214
	v_add_f32_e32 v169, v7, v215
	v_add_f32_e32 v170, v8, v216
	v_add_f32_e32 v171, v9, v217
	v_add_f32_e32 v172, v2, v218
	v_add_f32_e32 v173, v3, v219
	v_add_f32_e32 v174, v4, v220
	v_add_f32_e32 v175, v5, v221
	v_mul_f32_e32 v168, s18, v168
	v_mul_f32_e32 v169, s18, v169
	v_mul_f32_e32 v170, s18, v170
	v_mul_f32_e32 v171, s18, v171
	v_mul_f32_e32 v172, s18, v172
	v_mul_f32_e32 v173, s18, v173
	v_mul_f32_e32 v174, s18, v174
	v_mul_f32_e32 v175, s18, v175
	v_exp_f32_e32 v168, v168
	v_exp_f32_e32 v169, v169
	v_exp_f32_e32 v170, v170
	v_exp_f32_e32 v171, v171
	v_exp_f32_e32 v172, v172
	v_exp_f32_e32 v173, v173
	v_exp_f32_e32 v174, v174
	v_exp_f32_e32 v175, v175
	v_add_f32_e32 v168, 1.0, v168
	v_add_f32_e32 v169, 1.0, v169
	v_add_f32_e32 v170, 1.0, v170
	v_add_f32_e32 v171, 1.0, v171
	v_add_f32_e32 v172, 1.0, v172
	v_add_f32_e32 v173, 1.0, v173
	v_add_f32_e32 v174, 1.0, v174
	v_add_f32_e32 v175, 1.0, v175
	v_rcp_f32_e32 v168, v168
	v_rcp_f32_e32 v169, v169
	v_rcp_f32_e32 v170, v170
	v_rcp_f32_e32 v171, v171
	v_rcp_f32_e32 v172, v172
	v_rcp_f32_e32 v173, v173
	v_rcp_f32_e32 v174, v174
	v_rcp_f32_e32 v175, v175
	v_cvt_pk_bf16_f32 v156, v168, v169
	v_cvt_pk_bf16_f32 v157, v170, v171
	v_cvt_pk_bf16_f32 v158, v172, v173
	v_cvt_pk_bf16_f32 v159, v174, v175
	v_permlane16_swap_b32_e32 v152, v154
	v_permlane16_swap_b32_e32 v153, v155
	global_store_dwordx4 v248, v[152:155], s[6:7] offset:256
	s_nop 1
	v_permlane16_swap_b32_e32 v156, v158
	v_permlane16_swap_b32_e32 v157, v159
	global_store_dwordx4 v249, v[156:159], s[6:7] offset:256
	s_branch .LBB0_996

; #define GAS __attribute__((address_space(1)))
; __device__ __forceinline__ uint2 pack4(f32x4 v) { return make_uint2(pack2(v[0], v[1]), pack2(v[2], v[3])); }
; template <int MODE>
; __device__ __forceinline__ void epi_elem(char* ws, float* outp, const float* b_gate, int g0, int rl, int col, f32x4 v) {
;     ...
;   } else if (MODE == E_Q) {
;     int lc = col & 1023;
;     f32x4 o = v * 0.18033688011112042f;
;     *(GAS uint2*)((u16*)(ws + W_Q) + (size_t)rl * 1024 + lc) = pack4(o);
; template <int MODE>
; __device__ __forceinline__ void epi_store(char* ws, float* outp, const float* b_gate, int g0, const f32x4 (&acc)[2][2][4][2], int rbase, int cbase) {
; #pragma unroll
;   for (int ai = 0; ai < 2; ++ai)
; #pragma unroll
;     for (int bj = 0; bj < 2; ++bj)
; #pragma unroll
;       for (int m = 0; m < 4; ++m) {
; #pragma unroll
;         for (int n = 0; n < 2; ++n)
;           epi_elem<MODE>(ws, outp, b_gate, g0, rbase + ai * HALF + m * 16, cbase + bj * HALF + n * 16, acc[ai][bj][m][n]);
;         if ((m & 1) && (MODE != E_M1 && MODE != E_MG)) __builtin_amdgcn_sched_barrier(0);
;         if (m == 3 && (MODE == E_M1 || MODE == E_MG)) __builtin_amdgcn_sched_barrier(0);
;       }
.LBB0_984:
	s_andn2_b64 vcc, exec, s[8:9]
	s_cbranch_vccnz .LBB0_986
	v_bfe_u32 v141, v184, 2, 2
	v_and_b32_e32 v143, 1, v141
	v_lshrrev_b32_e32 v187, 1, v141
	v_lshlrev_b32_e32 v143, 4, v143
	v_lshl_add_u32 v143, v187, 3, v143
	v_lshlrev_b32_e32 v141, 2, v141
	v_sub_u32_e32 v143, v143, v141
	v_add_u32_e32 v143, v140, v143
	v_and_b32_e32 v143, 0x3ff, v143
	v_lshlrev_b32_e32 v141, 11, v142
	v_lshl_add_u32 v250, v143, 1, v141
	v_add_u32_e32 v251, 0x8000, v250
	v_add_u32_e32 v252, 0x10000, v250
	v_add_u32_e32 v253, 0x18000, v250
	s_add_u32 s4, s2, 0xe7c0000
	s_addc_u32 s5, s3, 0
	s_add_u32 s6, s2, 0xe800000
	s_addc_u32 s7, s3, 0
	s_mov_b32 s18, 0x3e38aa3b
	v_mul_f32_e32 v160, s18, v126
	v_mul_f32_e32 v161, s18, v127
	v_mul_f32_e32 v162, s18, v128
	v_mul_f32_e32 v163, s18, v129
	v_mul_f32_e32 v164, s18, v122
	v_mul_f32_e32 v165, s18, v123
	v_mul_f32_e32 v166, s18, v124
	v_mul_f32_e32 v167, s18, v125
	v_cvt_pk_bf16_f32 v144, v160, v161
	v_cvt_pk_bf16_f32 v145, v162, v163
	v_cvt_pk_bf16_f32 v146, v164, v165
	v_cvt_pk_bf16_f32 v147, v166, v167
	v_mul_f32_e32 v168, s18, v118
	v_mul_f32_e32 v169, s18, v119
	v_mul_f32_e32 v170, s18, v120
	v_mul_f32_e32 v171, s18, v121
	v_mul_f32_e32 v172, s18, v114
	v_mul_f32_e32 v173, s18, v115
	v_mul_f32_e32 v174, s18, v116
	v_mul_f32_e32 v175, s18, v117
	v_cvt_pk_bf16_f32 v148, v168, v169
	v_cvt_pk_bf16_f32 v149, v170, v171
	v_cvt_pk_bf16_f32 v150, v172, v173
	v_cvt_pk_bf16_f32 v151, v174, v175
	v_permlane16_swap_b32_e32 v144, v146
	v_permlane16_swap_b32_e32 v145, v147
	global_store_dwordx4 v250, v[144:147], s[4:5]
	v_mul_f32_e32 v160, s18, v110
	v_mul_f32_e32 v161, s18, v111
	v_mul_f32_e32 v162, s18, v112
	v_mul_f32_e32 v163, s18, v113
	v_mul_f32_e32 v164, s18, v106
	v_mul_f32_e32 v165, s18, v107
	v_mul_f32_e32 v166, s18, v108
	v_mul_f32_e32 v167, s18, v109
	v_cvt_pk_bf16_f32 v152, v160, v161
	v_cvt_pk_bf16_f32 v153, v162, v163
	v_cvt_pk_bf16_f32 v154, v164, v165
	v_cvt_pk_bf16_f32 v155, v166, v167
	v_permlane16_swap_b32_e32 v148, v150
	v_permlane16_swap_b32_e32 v149, v151
	global_store_dwordx4 v251, v[148:151], s[4:5]
	v_mul_f32_e32 v168, s18, v102
	v_mul_f32_e32 v169, s18, v103
	v_mul_f32_e32 v170, s18, v104
	v_mul_f32_e32 v171, s18, v105
	v_mul_f32_e32 v172, s18, v98
	v_mul_f32_e32 v173, s18, v99
	v_mul_f32_e32 v174, s18, v100
	v_mul_f32_e32 v175, s18, v101
	v_cvt_pk_bf16_f32 v156, v168, v169
	v_cvt_pk_bf16_f32 v157, v170, v171
	v_cvt_pk_bf16_f32 v158, v172, v173
	v_cvt_pk_bf16_f32 v159, v174, v175
	v_permlane16_swap_b32_e32 v152, v154
	v_permlane16_swap_b32_e32 v153, v155
	global_store_dwordx4 v252, v[152:155], s[4:5]
	v_mul_f32_e32 v160, s18, v94
	v_mul_f32_e32 v161, s18, v95
	v_mul_f32_e32 v162, s18, v96
	v_mul_f32_e32 v163, s18, v97
	v_mul_f32_e32 v164, s18, v90
	v_mul_f32_e32 v165, s18, v91
	v_mul_f32_e32 v166, s18, v92
	v_mul_f32_e32 v167, s18, v93
	v_cvt_pk_bf16_f32 v144, v160, v161
	v_cvt_pk_bf16_f32 v145, v162, v163
	v_cvt_pk_bf16_f32 v146, v164, v165
	v_cvt_pk_bf16_f32 v147, v166, v167
	v_permlane16_swap_b32_e32 v156, v158
	v_permlane16_swap_b32_e32 v157, v159
	global_store_dwordx4 v253, v[156:159], s[4:5]
	v_mul_f32_e32 v168, s18, v86
	v_mul_f32_e32 v169, s18, v87
	v_mul_f32_e32 v170, s18, v88
	v_mul_f32_e32 v171, s18, v89
	v_mul_f32_e32 v172, s18, v82
	v_mul_f32_e32 v173, s18, v83
	v_mul_f32_e32 v174, s18, v84
	v_mul_f32_e32 v175, s18, v85
	v_cvt_pk_bf16_f32 v148, v168, v169
	v_cvt_pk_bf16_f32 v149, v170, v171
	v_cvt_pk_bf16_f32 v150, v172, v173
	v_cvt_pk_bf16_f32 v151, v174, v175
	v_permlane16_swap_b32_e32 v144, v146
	v_permlane16_swap_b32_e32 v145, v147
	global_store_dwordx4 v250, v[144:147], s[4:5] offset:256
	v_mul_f32_e32 v160, s18, v78
	v_mul_f32_e32 v161, s18, v79
	v_mul_f32_e32 v162, s18, v80
	v_mul_f32_e32 v163, s18, v81
	v_mul_f32_e32 v164, s18, v74
	v_mul_f32_e32 v165, s18, v75
	v_mul_f32_e32 v166, s18, v76
	v_mul_f32_e32 v167, s18, v77
	v_cvt_pk_bf16_f32 v152, v160, v161
	v_cvt_pk_bf16_f32 v153, v162, v163
	v_cvt_pk_bf16_f32 v154, v164, v165
	v_cvt_pk_bf16_f32 v155, v166, v167
	v_permlane16_swap_b32_e32 v148, v150
	v_permlane16_swap_b32_e32 v149, v151
	global_store_dwordx4 v251, v[148:151], s[4:5] offset:256
	v_mul_f32_e32 v168, s18, v70
	v_mul_f32_e32 v169, s18, v71
	v_mul_f32_e32 v170, s18, v72
	v_mul_f32_e32 v171, s18, v73
	v_mul_f32_e32 v172, s18, v66
	v_mul_f32_e32 v173, s18, v67
	v_mul_f32_e32 v174, s18, v68
	v_mul_f32_e32 v175, s18, v69
	v_cvt_pk_bf16_f32 v156, v168, v169
	v_cvt_pk_bf16_f32 v157, v170, v171
; #define GAS __attribute__((address_space(1)))
; __device__ __forceinline__ uint2 pack4(f32x4 v) { return make_uint2(pack2(v[0], v[1]), pack2(v[2], v[3])); }
; template <int MODE>
; __device__ __forceinline__ void epi_elem(char* ws, float* outp, const float* b_gate, int g0, int rl, int col, f32x4 v) {
;     ...
;   } else if (MODE == E_Q) {
;     int lc = col & 1023;
;     f32x4 o = v * 0.18033688011112042f;
;     *(GAS uint2*)((u16*)(ws + W_Q) + (size_t)rl * 1024 + lc) = pack4(o);
; template <int MODE>
; __device__ __forceinline__ void epi_store(char* ws, float* outp, const float* b_gate, int g0, const f32x4 (&acc)[2][2][4][2], int rbase, int cbase) {
; #pragma unroll
;   for (int ai = 0; ai < 2; ++ai)
; #pragma unroll
;     for (int bj = 0; bj < 2; ++bj)
; #pragma unroll
;       for (int m = 0; m < 4; ++m) {
; #pragma unroll
;         for (int n = 0; n < 2; ++n)
;           epi_elem<MODE>(ws, outp, b_gate, g0, rbase + ai * HALF + m * 16, cbase + bj * HALF + n * 16, acc[ai][bj][m][n]);
;         if ((m & 1) && (MODE != E_M1 && MODE != E_MG)) __builtin_amdgcn_sched_barrier(0);
;         if (m == 3 && (MODE == E_M1 || MODE == E_MG)) __builtin_amdgcn_sched_barrier(0);
;       }
	v_cvt_pk_bf16_f32 v158, v172, v173
	v_cvt_pk_bf16_f32 v159, v174, v175
	v_permlane16_swap_b32_e32 v152, v154
	v_permlane16_swap_b32_e32 v153, v155
	global_store_dwordx4 v252, v[152:155], s[4:5] offset:256
	v_mul_f32_e32 v160, s18, v62
	v_mul_f32_e32 v161, s18, v63
	v_mul_f32_e32 v162, s18, v64
	v_mul_f32_e32 v163, s18, v65
	v_mul_f32_e32 v164, s18, v58
	v_mul_f32_e32 v165, s18, v59
	v_mul_f32_e32 v166, s18, v60
	v_mul_f32_e32 v167, s18, v61
	v_cvt_pk_bf16_f32 v144, v160, v161
	v_cvt_pk_bf16_f32 v145, v162, v163
	v_cvt_pk_bf16_f32 v146, v164, v165
	v_cvt_pk_bf16_f32 v147, v166, v167
	v_permlane16_swap_b32_e32 v156, v158
	v_permlane16_swap_b32_e32 v157, v159
	global_store_dwordx4 v253, v[156:159], s[4:5] offset:256
	v_mul_f32_e32 v168, s18, v54
	v_mul_f32_e32 v169, s18, v55
	v_mul_f32_e32 v170, s18, v56
	v_mul_f32_e32 v171, s18, v57
	v_mul_f32_e32 v172, s18, v50
	v_mul_f32_e32 v173, s18, v51
	v_mul_f32_e32 v174, s18, v52
	v_mul_f32_e32 v175, s18, v53
	v_cvt_pk_bf16_f32 v148, v168, v169
	v_cvt_pk_bf16_f32 v149, v170, v171
	v_cvt_pk_bf16_f32 v150, v172, v173
	v_cvt_pk_bf16_f32 v151, v174, v175
	v_permlane16_swap_b32_e32 v144, v146
	v_permlane16_swap_b32_e32 v145, v147
	global_store_dwordx4 v250, v[144:147], s[6:7]
	v_mul_f32_e32 v160, s18, v46
	v_mul_f32_e32 v161, s18, v47
	v_mul_f32_e32 v162, s18, v48
	v_mul_f32_e32 v163, s18, v49
	v_mul_f32_e32 v164, s18, v42
	v_mul_f32_e32 v165, s18, v43
	v_mul_f32_e32 v166, s18, v44
	v_mul_f32_e32 v167, s18, v45
	v_cvt_pk_bf16_f32 v152, v160, v161
	v_cvt_pk_bf16_f32 v153, v162, v163
	v_cvt_pk_bf16_f32 v154, v164, v165
	v_cvt_pk_bf16_f32 v155, v166, v167
	v_permlane16_swap_b32_e32 v148, v150
	v_permlane16_swap_b32_e32 v149, v151
	global_store_dwordx4 v251, v[148:151], s[6:7]
	v_mul_f32_e32 v168, s18, v38
	v_mul_f32_e32 v169, s18, v39
	v_mul_f32_e32 v170, s18, v40
	v_mul_f32_e32 v171, s18, v41
	v_mul_f32_e32 v172, s18, v34
	v_mul_f32_e32 v173, s18, v35
	v_mul_f32_e32 v174, s18, v36
	v_mul_f32_e32 v175, s18, v37
	v_cvt_pk_bf16_f32 v156, v168, v169
	v_cvt_pk_bf16_f32 v157, v170, v171
	v_cvt_pk_bf16_f32 v158, v172, v173
	v_cvt_pk_bf16_f32 v159, v174, v175
	v_permlane16_swap_b32_e32 v152, v154
	v_permlane16_swap_b32_e32 v153, v155
	global_store_dwordx4 v252, v[152:155], s[6:7]
	v_mul_f32_e32 v160, s18, v30
	v_mul_f32_e32 v161, s18, v31
	v_mul_f32_e32 v162, s18, v32
	v_mul_f32_e32 v163, s18, v33
	v_mul_f32_e32 v164, s18, v26
	v_mul_f32_e32 v165, s18, v27
	v_mul_f32_e32 v166, s18, v28
	v_mul_f32_e32 v167, s18, v29
	v_cvt_pk_bf16_f32 v144, v160, v161
	v_cvt_pk_bf16_f32 v145, v162, v163
	v_cvt_pk_bf16_f32 v146, v164, v165
	v_cvt_pk_bf16_f32 v147, v166, v167
	v_permlane16_swap_b32_e32 v156, v158
	v_permlane16_swap_b32_e32 v157, v159
	global_store_dwordx4 v253, v[156:159], s[6:7]
	v_mul_f32_e32 v168, s18, v22
	v_mul_f32_e32 v169, s18, v23
	v_mul_f32_e32 v170, s18, v24
	v_mul_f32_e32 v171, s18, v25
	v_mul_f32_e32 v172, s18, v18
	v_mul_f32_e32 v173, s18, v19
	v_mul_f32_e32 v174, s18, v20
	v_mul_f32_e32 v175, s18, v21
	v_cvt_pk_bf16_f32 v148, v168, v169
	v_cvt_pk_bf16_f32 v149, v170, v171
	v_cvt_pk_bf16_f32 v150, v172, v173
	v_cvt_pk_bf16_f32 v151, v174, v175
	v_permlane16_swap_b32_e32 v144, v146
	v_permlane16_swap_b32_e32 v145, v147
	global_store_dwordx4 v250, v[144:147], s[6:7] offset:256
	v_mul_f32_e32 v160, s18, v14
	v_mul_f32_e32 v161, s18, v15
	v_mul_f32_e32 v162, s18, v16
	v_mul_f32_e32 v163, s18, v17
	v_mul_f32_e32 v164, s18, v10
	v_mul_f32_e32 v165, s18, v11
	v_mul_f32_e32 v166, s18, v12
	v_mul_f32_e32 v167, s18, v13
	v_cvt_pk_bf16_f32 v152, v160, v161
	v_cvt_pk_bf16_f32 v153, v162, v163
	v_cvt_pk_bf16_f32 v154, v164, v165
	v_cvt_pk_bf16_f32 v155, v166, v167
	v_permlane16_swap_b32_e32 v148, v150
	v_permlane16_swap_b32_e32 v149, v151
	global_store_dwordx4 v251, v[148:151], s[6:7] offset:256
	v_mul_f32_e32 v168, s18, v6
	v_mul_f32_e32 v169, s18, v7
	v_mul_f32_e32 v170, s18, v8
	v_mul_f32_e32 v171, s18, v9
	v_mul_f32_e32 v172, s18, v2
	v_mul_f32_e32 v173, s18, v3
	v_mul_f32_e32 v174, s18, v4
	v_mul_f32_e32 v175, s18, v5
	v_cvt_pk_bf16_f32 v156, v168, v169
	v_cvt_pk_bf16_f32 v157, v170, v171
	v_cvt_pk_bf16_f32 v158, v172, v173
	v_cvt_pk_bf16_f32 v159, v174, v175
	v_permlane16_swap_b32_e32 v152, v154
	v_permlane16_swap_b32_e32 v153, v155
	global_store_dwordx4 v252, v[152:155], s[6:7] offset:256
	s_nop 1
	v_permlane16_swap_b32_e32 v156, v158
	v_permlane16_swap_b32_e32 v157, v159
	global_store_dwordx4 v253, v[156:159], s[6:7] offset:256
	s_branch .LBB0_996

; #define GAS __attribute__((address_space(1)))
; __device__ __forceinline__ uint2 pack4(f32x4 v) { return make_uint2(pack2(v[0], v[1]), pack2(v[2], v[3])); }
; template <int MODE>
; __device__ __forceinline__ void epi_elem(char* ws, float* outp, const float* b_gate, int g0, int rl, int col, f32x4 v) {
;   if (MODE == E_U || MODE == E_GV) {
;     int lc = col & 1023;
;     f32x4 o; for (int i = 0; i < 4; ++i) o[i] = gelu_f(v[i]);
;     u16* dst = (u16*)(ws + (MODE == E_U ? W_U : W_GV));
;     *(GAS uint2*)(dst + (size_t)rl * 1024 + lc) = pack4(o);
; template <int MODE>
; __device__ __forceinline__ void epi_store(char* ws, float* outp, const float* b_gate, int g0, const f32x4 (&acc)[2][2][4][2], int rbase, int cbase) {
; #pragma unroll
;   for (int ai = 0; ai < 2; ++ai)
; #pragma unroll
;     for (int bj = 0; bj < 2; ++bj)
; #pragma unroll
;       for (int m = 0; m < 4; ++m) {
; #pragma unroll
;         for (int n = 0; n < 2; ++n)
;           epi_elem<MODE>(ws, outp, b_gate, g0, rbase + ai * HALF + m * 16, cbase + bj * HALF + n * 16, acc[ai][bj][m][n]);
;         if ((m & 1) && (MODE != E_M1 && MODE != E_MG)) __builtin_amdgcn_sched_barrier(0);
;         if (m == 3 && (MODE == E_M1 || MODE == E_MG)) __builtin_amdgcn_sched_barrier(0);
;       }
.LBB0_987:
	s_andn2_b64 vcc, exec, s[8:9]
	s_mov_b64 s[8:9], 0
	s_cbranch_vccnz .LBB0_992
	s_cmp_gt_i32 s16, 0
	s_mov_b64 s[6:7], -1
	s_cbranch_scc0 .LBB0_990
	v_bfe_u32 v141, v184, 2, 2
	v_and_b32_e32 v143, 1, v141
	v_lshrrev_b32_e32 v187, 1, v141
	v_lshlrev_b32_e32 v143, 4, v143
	v_lshl_add_u32 v143, v187, 3, v143
	v_lshlrev_b32_e32 v141, 2, v141
	v_sub_u32_e32 v143, v143, v141
	v_add_u32_e32 v143, v140, v143
	v_and_b32_e32 v143, 0x3ff, v143
	v_lshlrev_b32_e32 v141, 11, v142
	v_lshl_add_u32 v250, v143, 1, v141
	v_add_u32_e32 v251, 0x8000, v250
	v_add_u32_e32 v252, 0x10000, v250
	v_add_u32_e32 v253, 0x18000, v250
	s_add_u32 s4, s2, 0xa6c0000
	s_addc_u32 s5, s3, 0
	s_add_u32 s6, s2, 0xa700000
	s_addc_u32 s7, s3, 0
	s_mov_b32 s18, 0xbdd2d3e7
	v_mul_f32_e32 v160, v126, v126
	v_mul_f32_e32 v161, v127, v127
	v_mul_f32_e32 v162, v128, v128
	v_mul_f32_e32 v163, v129, v129
	v_mul_f32_e32 v164, v122, v122
	v_mul_f32_e32 v165, v123, v123
	v_mul_f32_e32 v166, v124, v124
	v_mul_f32_e32 v167, v125, v125
	v_fma_f32 v160, v160, s18, v198
	v_fma_f32 v161, v161, s18, v198
	v_fma_f32 v162, v162, s18, v198
	v_fma_f32 v163, v163, s18, v198
	v_fma_f32 v164, v164, s18, v198
	v_fma_f32 v165, v165, s18, v198
	v_fma_f32 v166, v166, s18, v198
	v_fma_f32 v167, v167, s18, v198
	v_mul_f32_e32 v160, v126, v160
	v_mul_f32_e32 v161, v127, v161
	v_mul_f32_e32 v162, v128, v162
	v_mul_f32_e32 v163, v129, v163
	v_mul_f32_e32 v164, v122, v164
	v_mul_f32_e32 v165, v123, v165
	v_mul_f32_e32 v166, v124, v166
	v_mul_f32_e32 v167, v125, v167
	v_exp_f32_e32 v160, v160
	v_exp_f32_e32 v161, v161
	v_exp_f32_e32 v162, v162
	v_exp_f32_e32 v163, v163
	v_exp_f32_e32 v164, v164
	v_exp_f32_e32 v165, v165
	v_exp_f32_e32 v166, v166
	v_exp_f32_e32 v167, v167
	v_add_f32_e32 v160, 1.0, v160
	v_add_f32_e32 v161, 1.0, v161
	v_add_f32_e32 v162, 1.0, v162
	v_add_f32_e32 v163, 1.0, v163
	v_add_f32_e32 v164, 1.0, v164
	v_add_f32_e32 v165, 1.0, v165
	v_add_f32_e32 v166, 1.0, v166
	v_add_f32_e32 v167, 1.0, v167
	v_rcp_f32_e32 v160, v160
	v_rcp_f32_e32 v161, v161
	v_rcp_f32_e32 v162, v162
	v_rcp_f32_e32 v163, v163
	v_rcp_f32_e32 v164, v164
	v_rcp_f32_e32 v165, v165
	v_rcp_f32_e32 v166, v166
	v_rcp_f32_e32 v167, v167
	v_mul_f32_e32 v160, v126, v160
	v_mul_f32_e32 v161, v127, v161
	v_mul_f32_e32 v162, v128, v162
	v_mul_f32_e32 v163, v129, v163
	v_mul_f32_e32 v164, v122, v164
	v_mul_f32_e32 v165, v123, v165
	v_mul_f32_e32 v166, v124, v166
	v_mul_f32_e32 v167, v125, v167
	v_cvt_pk_bf16_f32 v144, v160, v161
	v_cvt_pk_bf16_f32 v145, v162, v163
	v_cvt_pk_bf16_f32 v146, v164, v165
	v_cvt_pk_bf16_f32 v147, v166, v167
	v_mul_f32_e32 v168, v118, v118
	v_mul_f32_e32 v169, v119, v119
	v_mul_f32_e32 v170, v120, v120
	v_mul_f32_e32 v171, v121, v121
	v_mul_f32_e32 v172, v114, v114
	v_mul_f32_e32 v173, v115, v115
	v_mul_f32_e32 v174, v116, v116
	v_mul_f32_e32 v175, v117, v117
	v_fma_f32 v168, v168, s18, v198
	v_fma_f32 v169, v169, s18, v198
	v_fma_f32 v170, v170, s18, v198
	v_fma_f32 v171, v171, s18, v198
	v_fma_f32 v172, v172, s18, v198
	v_fma_f32 v173, v173, s18, v198
	v_fma_f32 v174, v174, s18, v198
	v_fma_f32 v175, v175, s18, v198
	v_mul_f32_e32 v168, v118, v168
	v_mul_f32_e32 v169, v119, v169
	v_mul_f32_e32 v170, v120, v170
	v_mul_f32_e32 v171, v121, v171
	v_mul_f32_e32 v172, v114, v172
	v_mul_f32_e32 v173, v115, v173
	v_mul_f32_e32 v174, v116, v174
	v_mul_f32_e32 v175, v117, v175
	v_exp_f32_e32 v168, v168
	v_exp_f32_e32 v169, v169
	v_exp_f32_e32 v170, v170
	v_exp_f32_e32 v171, v171
	v_exp_f32_e32 v172, v172
	v_exp_f32_e32 v173, v173
	v_exp_f32_e32 v174, v174
	v_exp_f32_e32 v175, v175
	v_add_f32_e32 v168, 1.0, v168
	v_add_f32_e32 v169, 1.0, v169
	v_add_f32_e32 v170, 1.0, v170
	v_add_f32_e32 v171, 1.0, v171
	v_add_f32_e32 v172, 1.0, v172
	v_add_f32_e32 v173, 1.0, v173
	v_add_f32_e32 v174, 1.0, v174
	v_add_f32_e32 v175, 1.0, v175
	v_rcp_f32_e32 v168, v168
	v_rcp_f32_e32 v169, v169
	v_rcp_f32_e32 v170, v170
	v_rcp_f32_e32 v171, v171
	v_rcp_f32_e32 v172, v172
	v_rcp_f32_e32 v173, v173
	v_rcp_f32_e32 v174, v174
	v_rcp_f32_e32 v175, v175
	v_mul_f32_e32 v168, v118, v168
	v_mul_f32_e32 v169, v119, v169
	v_mul_f32_e32 v170, v120, v170
	v_mul_f32_e32 v171, v121, v171
	v_mul_f32_e32 v172, v114, v172
	v_mul_f32_e32 v173, v115, v173
	v_mul_f32_e32 v174, v116, v174
	v_mul_f32_e32 v175, v117, v175
	v_cvt_pk_bf16_f32 v148, v168, v169
	v_cvt_pk_bf16_f32 v149, v170, v171
	v_cvt_pk_bf16_f32 v150, v172, v173
	v_cvt_pk_bf16_f32 v151, v174, v175
	v_permlane16_swap_b32_e32 v144, v146
	v_permlane16_swap_b32_e32 v145, v147
	global_store_dwordx4 v250, v[144:147], s[4:5]
	v_mul_f32_e32 v160, v110, v110
	v_mul_f32_e32 v161, v111, v111
	v_mul_f32_e32 v162, v112, v112
	v_mul_f32_e32 v163, v113, v113
	v_mul_f32_e32 v164, v106, v106
	v_mul_f32_e32 v165, v107, v107
	v_mul_f32_e32 v166, v108, v108
	v_mul_f32_e32 v167, v109, v109
	v_fma_f32 v160, v160, s18, v198
	v_fma_f32 v161, v161, s18, v198
	v_fma_f32 v162, v162, s18, v198
	v_fma_f32 v163, v163, s18, v198
	v_fma_f32 v164, v164, s18, v198
	v_fma_f32 v165, v165, s18, v198
	v_fma_f32 v166, v166, s18, v198
	v_fma_f32 v167, v167, s18, v198
	v_mul_f32_e32 v160, v110, v160
	v_mul_f32_e32 v161, v111, v161
	v_mul_f32_e32 v162, v112, v162
	v_mul_f32_e32 v163, v113, v163
	v_mul_f32_e32 v164, v106, v164
	v_mul_f32_e32 v165, v107, v165
	v_mul_f32_e32 v166, v108, v166
	v_mul_f32_e32 v167, v109, v167
	v_exp_f32_e32 v160, v160
	v_exp_f32_e32 v161, v161
	v_exp_f32_e32 v162, v162
	v_exp_f32_e32 v163, v163
	v_exp_f32_e32 v164, v164
	v_exp_f32_e32 v165, v165
	v_exp_f32_e32 v166, v166
	v_exp_f32_e32 v167, v167
	v_add_f32_e32 v160, 1.0, v160
	v_add_f32_e32 v161, 1.0, v161
	v_add_f32_e32 v162, 1.0, v162
; #define GAS __attribute__((address_space(1)))
; __device__ __forceinline__ uint2 pack4(f32x4 v) { return make_uint2(pack2(v[0], v[1]), pack2(v[2], v[3])); }
; template <int MODE>
; __device__ __forceinline__ void epi_elem(char* ws, float* outp, const float* b_gate, int g0, int rl, int col, f32x4 v) {
;   if (MODE == E_U || MODE == E_GV) {
;     int lc = col & 1023;
;     f32x4 o; for (int i = 0; i < 4; ++i) o[i] = gelu_f(v[i]);
;     u16* dst = (u16*)(ws + (MODE == E_U ? W_U : W_GV));
;     *(GAS uint2*)(dst + (size_t)rl * 1024 + lc) = pack4(o);
; template <int MODE>
; __device__ __forceinline__ void epi_store(char* ws, float* outp, const float* b_gate, int g0, const f32x4 (&acc)[2][2][4][2], int rbase, int cbase) {
; #pragma unroll
;   for (int ai = 0; ai < 2; ++ai)
; #pragma unroll
;     for (int bj = 0; bj < 2; ++bj)
; #pragma unroll
;       for (int m = 0; m < 4; ++m) {
; #pragma unroll
;         for (int n = 0; n < 2; ++n)
;           epi_elem<MODE>(ws, outp, b_gate, g0, rbase + ai * HALF + m * 16, cbase + bj * HALF + n * 16, acc[ai][bj][m][n]);
;         if ((m & 1) && (MODE != E_M1 && MODE != E_MG)) __builtin_amdgcn_sched_barrier(0);
;         if (m == 3 && (MODE == E_M1 || MODE == E_MG)) __builtin_amdgcn_sched_barrier(0);
;       }
	v_add_f32_e32 v163, 1.0, v163
	v_add_f32_e32 v164, 1.0, v164
	v_add_f32_e32 v165, 1.0, v165
	v_add_f32_e32 v166, 1.0, v166
	v_add_f32_e32 v167, 1.0, v167
	v_rcp_f32_e32 v160, v160
	v_rcp_f32_e32 v161, v161
	v_rcp_f32_e32 v162, v162
	v_rcp_f32_e32 v163, v163
	v_rcp_f32_e32 v164, v164
	v_rcp_f32_e32 v165, v165
	v_rcp_f32_e32 v166, v166
	v_rcp_f32_e32 v167, v167
	v_mul_f32_e32 v160, v110, v160
	v_mul_f32_e32 v161, v111, v161
	v_mul_f32_e32 v162, v112, v162
	v_mul_f32_e32 v163, v113, v163
	v_mul_f32_e32 v164, v106, v164
	v_mul_f32_e32 v165, v107, v165
	v_mul_f32_e32 v166, v108, v166
	v_mul_f32_e32 v167, v109, v167
	v_cvt_pk_bf16_f32 v152, v160, v161
	v_cvt_pk_bf16_f32 v153, v162, v163
	v_cvt_pk_bf16_f32 v154, v164, v165
	v_cvt_pk_bf16_f32 v155, v166, v167
	v_permlane16_swap_b32_e32 v148, v150
	v_permlane16_swap_b32_e32 v149, v151
	global_store_dwordx4 v251, v[148:151], s[4:5]
	v_mul_f32_e32 v168, v102, v102
	v_mul_f32_e32 v169, v103, v103
	v_mul_f32_e32 v170, v104, v104
	v_mul_f32_e32 v171, v105, v105
	v_mul_f32_e32 v172, v98, v98
	v_mul_f32_e32 v173, v99, v99
	v_mul_f32_e32 v174, v100, v100
	v_mul_f32_e32 v175, v101, v101
	v_fma_f32 v168, v168, s18, v198
	v_fma_f32 v169, v169, s18, v198
	v_fma_f32 v170, v170, s18, v198
	v_fma_f32 v171, v171, s18, v198
	v_fma_f32 v172, v172, s18, v198
	v_fma_f32 v173, v173, s18, v198
	v_fma_f32 v174, v174, s18, v198
	v_fma_f32 v175, v175, s18, v198
	v_mul_f32_e32 v168, v102, v168
	v_mul_f32_e32 v169, v103, v169
	v_mul_f32_e32 v170, v104, v170
	v_mul_f32_e32 v171, v105, v171
	v_mul_f32_e32 v172, v98, v172
	v_mul_f32_e32 v173, v99, v173
	v_mul_f32_e32 v174, v100, v174
	v_mul_f32_e32 v175, v101, v175
	v_exp_f32_e32 v168, v168
	v_exp_f32_e32 v169, v169
	v_exp_f32_e32 v170, v170
	v_exp_f32_e32 v171, v171
	v_exp_f32_e32 v172, v172
	v_exp_f32_e32 v173, v173
	v_exp_f32_e32 v174, v174
	v_exp_f32_e32 v175, v175
	v_add_f32_e32 v168, 1.0, v168
	v_add_f32_e32 v169, 1.0, v169
	v_add_f32_e32 v170, 1.0, v170
	v_add_f32_e32 v171, 1.0, v171
	v_add_f32_e32 v172, 1.0, v172
	v_add_f32_e32 v173, 1.0, v173
	v_add_f32_e32 v174, 1.0, v174
	v_add_f32_e32 v175, 1.0, v175
	v_rcp_f32_e32 v168, v168
	v_rcp_f32_e32 v169, v169
	v_rcp_f32_e32 v170, v170
	v_rcp_f32_e32 v171, v171
	v_rcp_f32_e32 v172, v172
	v_rcp_f32_e32 v173, v173
	v_rcp_f32_e32 v174, v174
	v_rcp_f32_e32 v175, v175
	v_mul_f32_e32 v168, v102, v168
	v_mul_f32_e32 v169, v103, v169
	v_mul_f32_e32 v170, v104, v170
	v_mul_f32_e32 v171, v105, v171
	v_mul_f32_e32 v172, v98, v172
	v_mul_f32_e32 v173, v99, v173
	v_mul_f32_e32 v174, v100, v174
	v_mul_f32_e32 v175, v101, v175
	v_cvt_pk_bf16_f32 v156, v168, v169
	v_cvt_pk_bf16_f32 v157, v170, v171
	v_cvt_pk_bf16_f32 v158, v172, v173
	v_cvt_pk_bf16_f32 v159, v174, v175
	v_permlane16_swap_b32_e32 v152, v154
	v_permlane16_swap_b32_e32 v153, v155
	global_store_dwordx4 v252, v[152:155], s[4:5]
	v_mul_f32_e32 v160, v94, v94
	v_mul_f32_e32 v161, v95, v95
	v_mul_f32_e32 v162, v96, v96
	v_mul_f32_e32 v163, v97, v97
	v_mul_f32_e32 v164, v90, v90
	v_mul_f32_e32 v165, v91, v91
	v_mul_f32_e32 v166, v92, v92
	v_mul_f32_e32 v167, v93, v93
	v_fma_f32 v160, v160, s18, v198
	v_fma_f32 v161, v161, s18, v198
	v_fma_f32 v162, v162, s18, v198
	v_fma_f32 v163, v163, s18, v198
	v_fma_f32 v164, v164, s18, v198
	v_fma_f32 v165, v165, s18, v198
	v_fma_f32 v166, v166, s18, v198
	v_fma_f32 v167, v167, s18, v198
	v_mul_f32_e32 v160, v94, v160
	v_mul_f32_e32 v161, v95, v161
	v_mul_f32_e32 v162, v96, v162
	v_mul_f32_e32 v163, v97, v163
	v_mul_f32_e32 v164, v90, v164
	v_mul_f32_e32 v165, v91, v165
	v_mul_f32_e32 v166, v92, v166
	v_mul_f32_e32 v167, v93, v167
	v_exp_f32_e32 v160, v160
	v_exp_f32_e32 v161, v161
	v_exp_f32_e32 v162, v162
	v_exp_f32_e32 v163, v163
	v_exp_f32_e32 v164, v164
	v_exp_f32_e32 v165, v165
	v_exp_f32_e32 v166, v166
	v_exp_f32_e32 v167, v167
	v_add_f32_e32 v160, 1.0, v160
	v_add_f32_e32 v161, 1.0, v161
	v_add_f32_e32 v162, 1.0, v162
	v_add_f32_e32 v163, 1.0, v163
	v_add_f32_e32 v164, 1.0, v164
	v_add_f32_e32 v165, 1.0, v165
	v_add_f32_e32 v166, 1.0, v166
	v_add_f32_e32 v167, 1.0, v167
	v_rcp_f32_e32 v160, v160
	v_rcp_f32_e32 v161, v161
	v_rcp_f32_e32 v162, v162
	v_rcp_f32_e32 v163, v163
	v_rcp_f32_e32 v164, v164
	v_rcp_f32_e32 v165, v165
	v_rcp_f32_e32 v166, v166
	v_rcp_f32_e32 v167, v167
	v_mul_f32_e32 v160, v94, v160
	v_mul_f32_e32 v161, v95, v161
	v_mul_f32_e32 v162, v96, v162
	v_mul_f32_e32 v163, v97, v163
	v_mul_f32_e32 v164, v90, v164
	v_mul_f32_e32 v165, v91, v165
	v_mul_f32_e32 v166, v92, v166
	v_mul_f32_e32 v167, v93, v167
	v_cvt_pk_bf16_f32 v144, v160, v161
	v_cvt_pk_bf16_f32 v145, v162, v163
	v_cvt_pk_bf16_f32 v146, v164, v165
	v_cvt_pk_bf16_f32 v147, v166, v167
	v_permlane16_swap_b32_e32 v156, v158
	v_permlane16_swap_b32_e32 v157, v159
	global_store_dwordx4 v253, v[156:159], s[4:5]
	v_mul_f32_e32 v168, v86, v86
	v_mul_f32_e32 v169, v87, v87
	v_mul_f32_e32 v170, v88, v88
	v_mul_f32_e32 v171, v89, v89
	v_mul_f32_e32 v172, v82, v82
	v_mul_f32_e32 v173, v83, v83
	v_mul_f32_e32 v174, v84, v84
	v_mul_f32_e32 v175, v85, v85
	v_fma_f32 v168, v168, s18, v198
	v_fma_f32 v169, v169, s18, v198
	v_fma_f32 v170, v170, s18, v198
	v_fma_f32 v171, v171, s18, v198
	v_fma_f32 v172, v172, s18, v198
	v_fma_f32 v173, v173, s18, v198
	v_fma_f32 v174, v174, s18, v198
	v_fma_f32 v175, v175, s18, v198
	v_mul_f32_e32 v168, v86, v168
	v_mul_f32_e32 v169, v87, v169
	v_mul_f32_e32 v170, v88, v170
	v_mul_f32_e32 v171, v89, v171
	v_mul_f32_e32 v172, v82, v172
	v_mul_f32_e32 v173, v83, v173
	v_mul_f32_e32 v174, v84, v174
	v_mul_f32_e32 v175, v85, v175
	v_exp_f32_e32 v168, v168
	v_exp_f32_e32 v169, v169
	v_exp_f32_e32 v170, v170
	v_exp_f32_e32 v171, v171
; #define GAS __attribute__((address_space(1)))
; __device__ __forceinline__ uint2 pack4(f32x4 v) { return make_uint2(pack2(v[0], v[1]), pack2(v[2], v[3])); }
; template <int MODE>
; __device__ __forceinline__ void epi_elem(char* ws, float* outp, const float* b_gate, int g0, int rl, int col, f32x4 v) {
;   if (MODE == E_U || MODE == E_GV) {
;     int lc = col & 1023;
;     f32x4 o; for (int i = 0; i < 4; ++i) o[i] = gelu_f(v[i]);
;     u16* dst = (u16*)(ws + (MODE == E_U ? W_U : W_GV));
;     *(GAS uint2*)(dst + (size_t)rl * 1024 + lc) = pack4(o);
; template <int MODE>
; __device__ __forceinline__ void epi_store(char* ws, float* outp, const float* b_gate, int g0, const f32x4 (&acc)[2][2][4][2], int rbase, int cbase) {
; #pragma unroll
;   for (int ai = 0; ai < 2; ++ai)
; #pragma unroll
;     for (int bj = 0; bj < 2; ++bj)
; #pragma unroll
;       for (int m = 0; m < 4; ++m) {
; #pragma unroll
;         for (int n = 0; n < 2; ++n)
;           epi_elem<MODE>(ws, outp, b_gate, g0, rbase + ai * HALF + m * 16, cbase + bj * HALF + n * 16, acc[ai][bj][m][n]);
;         if ((m & 1) && (MODE != E_M1 && MODE != E_MG)) __builtin_amdgcn_sched_barrier(0);
;         if (m == 3 && (MODE == E_M1 || MODE == E_MG)) __builtin_amdgcn_sched_barrier(0);
;       }
	v_exp_f32_e32 v172, v172
	v_exp_f32_e32 v173, v173
	v_exp_f32_e32 v174, v174
	v_exp_f32_e32 v175, v175
	v_add_f32_e32 v168, 1.0, v168
	v_add_f32_e32 v169, 1.0, v169
	v_add_f32_e32 v170, 1.0, v170
	v_add_f32_e32 v171, 1.0, v171
	v_add_f32_e32 v172, 1.0, v172
	v_add_f32_e32 v173, 1.0, v173
	v_add_f32_e32 v174, 1.0, v174
	v_add_f32_e32 v175, 1.0, v175
	v_rcp_f32_e32 v168, v168
	v_rcp_f32_e32 v169, v169
	v_rcp_f32_e32 v170, v170
	v_rcp_f32_e32 v171, v171
	v_rcp_f32_e32 v172, v172
	v_rcp_f32_e32 v173, v173
	v_rcp_f32_e32 v174, v174
	v_rcp_f32_e32 v175, v175
	v_mul_f32_e32 v168, v86, v168
	v_mul_f32_e32 v169, v87, v169
	v_mul_f32_e32 v170, v88, v170
	v_mul_f32_e32 v171, v89, v171
	v_mul_f32_e32 v172, v82, v172
	v_mul_f32_e32 v173, v83, v173
	v_mul_f32_e32 v174, v84, v174
	v_mul_f32_e32 v175, v85, v175
	v_cvt_pk_bf16_f32 v148, v168, v169
	v_cvt_pk_bf16_f32 v149, v170, v171
	v_cvt_pk_bf16_f32 v150, v172, v173
	v_cvt_pk_bf16_f32 v151, v174, v175
	v_permlane16_swap_b32_e32 v144, v146
	v_permlane16_swap_b32_e32 v145, v147
	global_store_dwordx4 v250, v[144:147], s[4:5] offset:256
	v_mul_f32_e32 v160, v78, v78
	v_mul_f32_e32 v161, v79, v79
	v_mul_f32_e32 v162, v80, v80
	v_mul_f32_e32 v163, v81, v81
	v_mul_f32_e32 v164, v74, v74
	v_mul_f32_e32 v165, v75, v75
	v_mul_f32_e32 v166, v76, v76
	v_mul_f32_e32 v167, v77, v77
	v_fma_f32 v160, v160, s18, v198
	v_fma_f32 v161, v161, s18, v198
	v_fma_f32 v162, v162, s18, v198
	v_fma_f32 v163, v163, s18, v198
	v_fma_f32 v164, v164, s18, v198
	v_fma_f32 v165, v165, s18, v198
	v_fma_f32 v166, v166, s18, v198
	v_fma_f32 v167, v167, s18, v198
	v_mul_f32_e32 v160, v78, v160
	v_mul_f32_e32 v161, v79, v161
	v_mul_f32_e32 v162, v80, v162
	v_mul_f32_e32 v163, v81, v163
	v_mul_f32_e32 v164, v74, v164
	v_mul_f32_e32 v165, v75, v165
	v_mul_f32_e32 v166, v76, v166
	v_mul_f32_e32 v167, v77, v167
	v_exp_f32_e32 v160, v160
	v_exp_f32_e32 v161, v161
	v_exp_f32_e32 v162, v162
	v_exp_f32_e32 v163, v163
	v_exp_f32_e32 v164, v164
	v_exp_f32_e32 v165, v165
	v_exp_f32_e32 v166, v166
	v_exp_f32_e32 v167, v167
	v_add_f32_e32 v160, 1.0, v160
	v_add_f32_e32 v161, 1.0, v161
	v_add_f32_e32 v162, 1.0, v162
	v_add_f32_e32 v163, 1.0, v163
	v_add_f32_e32 v164, 1.0, v164
	v_add_f32_e32 v165, 1.0, v165
	v_add_f32_e32 v166, 1.0, v166
	v_add_f32_e32 v167, 1.0, v167
	v_rcp_f32_e32 v160, v160
	v_rcp_f32_e32 v161, v161
	v_rcp_f32_e32 v162, v162
	v_rcp_f32_e32 v163, v163
	v_rcp_f32_e32 v164, v164
	v_rcp_f32_e32 v165, v165
	v_rcp_f32_e32 v166, v166
	v_rcp_f32_e32 v167, v167
	v_mul_f32_e32 v160, v78, v160
	v_mul_f32_e32 v161, v79, v161
	v_mul_f32_e32 v162, v80, v162
	v_mul_f32_e32 v163, v81, v163
	v_mul_f32_e32 v164, v74, v164
	v_mul_f32_e32 v165, v75, v165
	v_mul_f32_e32 v166, v76, v166
	v_mul_f32_e32 v167, v77, v167
	v_cvt_pk_bf16_f32 v152, v160, v161
	v_cvt_pk_bf16_f32 v153, v162, v163
	v_cvt_pk_bf16_f32 v154, v164, v165
	v_cvt_pk_bf16_f32 v155, v166, v167
	v_permlane16_swap_b32_e32 v148, v150
	v_permlane16_swap_b32_e32 v149, v151
	global_store_dwordx4 v251, v[148:151], s[4:5] offset:256
	v_mul_f32_e32 v168, v70, v70
	v_mul_f32_e32 v169, v71, v71
	v_mul_f32_e32 v170, v72, v72
	v_mul_f32_e32 v171, v73, v73
	v_mul_f32_e32 v172, v66, v66
	v_mul_f32_e32 v173, v67, v67
	v_mul_f32_e32 v174, v68, v68
	v_mul_f32_e32 v175, v69, v69
	v_fma_f32 v168, v168, s18, v198
	v_fma_f32 v169, v169, s18, v198
	v_fma_f32 v170, v170, s18, v198
	v_fma_f32 v171, v171, s18, v198
	v_fma_f32 v172, v172, s18, v198
	v_fma_f32 v173, v173, s18, v198
	v_fma_f32 v174, v174, s18, v198
	v_fma_f32 v175, v175, s18, v198
	v_mul_f32_e32 v168, v70, v168
	v_mul_f32_e32 v169, v71, v169
	v_mul_f32_e32 v170, v72, v170
	v_mul_f32_e32 v171, v73, v171
	v_mul_f32_e32 v172, v66, v172
	v_mul_f32_e32 v173, v67, v173
	v_mul_f32_e32 v174, v68, v174
	v_mul_f32_e32 v175, v69, v175
	v_exp_f32_e32 v168, v168
	v_exp_f32_e32 v169, v169
	v_exp_f32_e32 v170, v170
	v_exp_f32_e32 v171, v171
	v_exp_f32_e32 v172, v172
	v_exp_f32_e32 v173, v173
	v_exp_f32_e32 v174, v174
	v_exp_f32_e32 v175, v175
	v_add_f32_e32 v168, 1.0, v168
	v_add_f32_e32 v169, 1.0, v169
	v_add_f32_e32 v170, 1.0, v170
	v_add_f32_e32 v171, 1.0, v171
	v_add_f32_e32 v172, 1.0, v172
	v_add_f32_e32 v173, 1.0, v173
	v_add_f32_e32 v174, 1.0, v174
	v_add_f32_e32 v175, 1.0, v175
	v_rcp_f32_e32 v168, v168
	v_rcp_f32_e32 v169, v169
	v_rcp_f32_e32 v170, v170
	v_rcp_f32_e32 v171, v171
	v_rcp_f32_e32 v172, v172
	v_rcp_f32_e32 v173, v173
	v_rcp_f32_e32 v174, v174
	v_rcp_f32_e32 v175, v175
	v_mul_f32_e32 v168, v70, v168
	v_mul_f32_e32 v169, v71, v169
	v_mul_f32_e32 v170, v72, v170
	v_mul_f32_e32 v171, v73, v171
	v_mul_f32_e32 v172, v66, v172
	v_mul_f32_e32 v173, v67, v173
	v_mul_f32_e32 v174, v68, v174
	v_mul_f32_e32 v175, v69, v175
	v_cvt_pk_bf16_f32 v156, v168, v169
	v_cvt_pk_bf16_f32 v157, v170, v171
	v_cvt_pk_bf16_f32 v158, v172, v173
	v_cvt_pk_bf16_f32 v159, v174, v175
	v_permlane16_swap_b32_e32 v152, v154
	v_permlane16_swap_b32_e32 v153, v155
	global_store_dwordx4 v252, v[152:155], s[4:5] offset:256
	v_mul_f32_e32 v160, v62, v62
	v_mul_f32_e32 v161, v63, v63
	v_mul_f32_e32 v162, v64, v64
	v_mul_f32_e32 v163, v65, v65
	v_mul_f32_e32 v164, v58, v58
	v_mul_f32_e32 v165, v59, v59
	v_mul_f32_e32 v166, v60, v60
	v_mul_f32_e32 v167, v61, v61
	v_fma_f32 v160, v160, s18, v198
	v_fma_f32 v161, v161, s18, v198
	v_fma_f32 v162, v162, s18, v198
	v_fma_f32 v163, v163, s18, v198
	v_fma_f32 v164, v164, s18, v198
	v_fma_f32 v165, v165, s18, v198
	v_fma_f32 v166, v166, s18, v198
	v_fma_f32 v167, v167, s18, v198
	v_mul_f32_e32 v160, v62, v160
	v_mul_f32_e32 v161, v63, v161
	v_mul_f32_e32 v162, v64, v162
	v_mul_f32_e32 v163, v65, v163
	v_mul_f32_e32 v164, v58, v164
; #define GAS __attribute__((address_space(1)))
; __device__ __forceinline__ uint2 pack4(f32x4 v) { return make_uint2(pack2(v[0], v[1]), pack2(v[2], v[3])); }
; template <int MODE>
; __device__ __forceinline__ void epi_elem(char* ws, float* outp, const float* b_gate, int g0, int rl, int col, f32x4 v) {
;   if (MODE == E_U || MODE == E_GV) {
;     int lc = col & 1023;
;     f32x4 o; for (int i = 0; i < 4; ++i) o[i] = gelu_f(v[i]);
;     u16* dst = (u16*)(ws + (MODE == E_U ? W_U : W_GV));
;     *(GAS uint2*)(dst + (size_t)rl * 1024 + lc) = pack4(o);
; template <int MODE>
; __device__ __forceinline__ void epi_store(char* ws, float* outp, const float* b_gate, int g0, const f32x4 (&acc)[2][2][4][2], int rbase, int cbase) {
; #pragma unroll
;   for (int ai = 0; ai < 2; ++ai)
; #pragma unroll
;     for (int bj = 0; bj < 2; ++bj)
; #pragma unroll
;       for (int m = 0; m < 4; ++m) {
; #pragma unroll
;         for (int n = 0; n < 2; ++n)
;           epi_elem<MODE>(ws, outp, b_gate, g0, rbase + ai * HALF + m * 16, cbase + bj * HALF + n * 16, acc[ai][bj][m][n]);
;         if ((m & 1) && (MODE != E_M1 && MODE != E_MG)) __builtin_amdgcn_sched_barrier(0);
;         if (m == 3 && (MODE == E_M1 || MODE == E_MG)) __builtin_amdgcn_sched_barrier(0);
;       }
	v_mul_f32_e32 v165, v59, v165
	v_mul_f32_e32 v166, v60, v166
	v_mul_f32_e32 v167, v61, v167
	v_exp_f32_e32 v160, v160
	v_exp_f32_e32 v161, v161
	v_exp_f32_e32 v162, v162
	v_exp_f32_e32 v163, v163
	v_exp_f32_e32 v164, v164
	v_exp_f32_e32 v165, v165
	v_exp_f32_e32 v166, v166
	v_exp_f32_e32 v167, v167
	v_add_f32_e32 v160, 1.0, v160
	v_add_f32_e32 v161, 1.0, v161
	v_add_f32_e32 v162, 1.0, v162
	v_add_f32_e32 v163, 1.0, v163
	v_add_f32_e32 v164, 1.0, v164
	v_add_f32_e32 v165, 1.0, v165
	v_add_f32_e32 v166, 1.0, v166
	v_add_f32_e32 v167, 1.0, v167
	v_rcp_f32_e32 v160, v160
	v_rcp_f32_e32 v161, v161
	v_rcp_f32_e32 v162, v162
	v_rcp_f32_e32 v163, v163
	v_rcp_f32_e32 v164, v164
	v_rcp_f32_e32 v165, v165
	v_rcp_f32_e32 v166, v166
	v_rcp_f32_e32 v167, v167
	v_mul_f32_e32 v160, v62, v160
	v_mul_f32_e32 v161, v63, v161
	v_mul_f32_e32 v162, v64, v162
	v_mul_f32_e32 v163, v65, v163
	v_mul_f32_e32 v164, v58, v164
	v_mul_f32_e32 v165, v59, v165
	v_mul_f32_e32 v166, v60, v166
	v_mul_f32_e32 v167, v61, v167
	v_cvt_pk_bf16_f32 v144, v160, v161
	v_cvt_pk_bf16_f32 v145, v162, v163
	v_cvt_pk_bf16_f32 v146, v164, v165
	v_cvt_pk_bf16_f32 v147, v166, v167
	v_permlane16_swap_b32_e32 v156, v158
	v_permlane16_swap_b32_e32 v157, v159
	global_store_dwordx4 v253, v[156:159], s[4:5] offset:256
	v_mul_f32_e32 v168, v54, v54
	v_mul_f32_e32 v169, v55, v55
	v_mul_f32_e32 v170, v56, v56
	v_mul_f32_e32 v171, v57, v57
	v_mul_f32_e32 v172, v50, v50
	v_mul_f32_e32 v173, v51, v51
	v_mul_f32_e32 v174, v52, v52
	v_mul_f32_e32 v175, v53, v53
	v_fma_f32 v168, v168, s18, v198
	v_fma_f32 v169, v169, s18, v198
	v_fma_f32 v170, v170, s18, v198
	v_fma_f32 v171, v171, s18, v198
	v_fma_f32 v172, v172, s18, v198
	v_fma_f32 v173, v173, s18, v198
	v_fma_f32 v174, v174, s18, v198
	v_fma_f32 v175, v175, s18, v198
	v_mul_f32_e32 v168, v54, v168
	v_mul_f32_e32 v169, v55, v169
	v_mul_f32_e32 v170, v56, v170
	v_mul_f32_e32 v171, v57, v171
	v_mul_f32_e32 v172, v50, v172
	v_mul_f32_e32 v173, v51, v173
	v_mul_f32_e32 v174, v52, v174
	v_mul_f32_e32 v175, v53, v175
	v_exp_f32_e32 v168, v168
	v_exp_f32_e32 v169, v169
	v_exp_f32_e32 v170, v170
	v_exp_f32_e32 v171, v171
	v_exp_f32_e32 v172, v172
	v_exp_f32_e32 v173, v173
	v_exp_f32_e32 v174, v174
	v_exp_f32_e32 v175, v175
	v_add_f32_e32 v168, 1.0, v168
	v_add_f32_e32 v169, 1.0, v169
	v_add_f32_e32 v170, 1.0, v170
	v_add_f32_e32 v171, 1.0, v171
	v_add_f32_e32 v172, 1.0, v172
	v_add_f32_e32 v173, 1.0, v173
	v_add_f32_e32 v174, 1.0, v174
	v_add_f32_e32 v175, 1.0, v175
	v_rcp_f32_e32 v168, v168
	v_rcp_f32_e32 v169, v169
	v_rcp_f32_e32 v170, v170
	v_rcp_f32_e32 v171, v171
	v_rcp_f32_e32 v172, v172
	v_rcp_f32_e32 v173, v173
	v_rcp_f32_e32 v174, v174
	v_rcp_f32_e32 v175, v175
	v_mul_f32_e32 v168, v54, v168
	v_mul_f32_e32 v169, v55, v169
	v_mul_f32_e32 v170, v56, v170
	v_mul_f32_e32 v171, v57, v171
	v_mul_f32_e32 v172, v50, v172
	v_mul_f32_e32 v173, v51, v173
	v_mul_f32_e32 v174, v52, v174
	v_mul_f32_e32 v175, v53, v175
	v_cvt_pk_bf16_f32 v148, v168, v169
	v_cvt_pk_bf16_f32 v149, v170, v171
	v_cvt_pk_bf16_f32 v150, v172, v173
	v_cvt_pk_bf16_f32 v151, v174, v175
	v_permlane16_swap_b32_e32 v144, v146
	v_permlane16_swap_b32_e32 v145, v147
	global_store_dwordx4 v250, v[144:147], s[6:7]
	v_mul_f32_e32 v160, v46, v46
	v_mul_f32_e32 v161, v47, v47
	v_mul_f32_e32 v162, v48, v48
	v_mul_f32_e32 v163, v49, v49
	v_mul_f32_e32 v164, v42, v42
	v_mul_f32_e32 v165, v43, v43
	v_mul_f32_e32 v166, v44, v44
	v_mul_f32_e32 v167, v45, v45
	v_fma_f32 v160, v160, s18, v198
	v_fma_f32 v161, v161, s18, v198
	v_fma_f32 v162, v162, s18, v198
	v_fma_f32 v163, v163, s18, v198
	v_fma_f32 v164, v164, s18, v198
	v_fma_f32 v165, v165, s18, v198
	v_fma_f32 v166, v166, s18, v198
	v_fma_f32 v167, v167, s18, v198
	v_mul_f32_e32 v160, v46, v160
	v_mul_f32_e32 v161, v47, v161
	v_mul_f32_e32 v162, v48, v162
	v_mul_f32_e32 v163, v49, v163
	v_mul_f32_e32 v164, v42, v164
	v_mul_f32_e32 v165, v43, v165
	v_mul_f32_e32 v166, v44, v166
	v_mul_f32_e32 v167, v45, v167
	v_exp_f32_e32 v160, v160
	v_exp_f32_e32 v161, v161
	v_exp_f32_e32 v162, v162
	v_exp_f32_e32 v163, v163
	v_exp_f32_e32 v164, v164
	v_exp_f32_e32 v165, v165
	v_exp_f32_e32 v166, v166
	v_exp_f32_e32 v167, v167
	v_add_f32_e32 v160, 1.0, v160
	v_add_f32_e32 v161, 1.0, v161
	v_add_f32_e32 v162, 1.0, v162
	v_add_f32_e32 v163, 1.0, v163
	v_add_f32_e32 v164, 1.0, v164
	v_add_f32_e32 v165, 1.0, v165
	v_add_f32_e32 v166, 1.0, v166
	v_add_f32_e32 v167, 1.0, v167
	v_rcp_f32_e32 v160, v160
	v_rcp_f32_e32 v161, v161
	v_rcp_f32_e32 v162, v162
	v_rcp_f32_e32 v163, v163
	v_rcp_f32_e32 v164, v164
	v_rcp_f32_e32 v165, v165
	v_rcp_f32_e32 v166, v166
	v_rcp_f32_e32 v167, v167
	v_mul_f32_e32 v160, v46, v160
	v_mul_f32_e32 v161, v47, v161
	v_mul_f32_e32 v162, v48, v162
	v_mul_f32_e32 v163, v49, v163
	v_mul_f32_e32 v164, v42, v164
	v_mul_f32_e32 v165, v43, v165
	v_mul_f32_e32 v166, v44, v166
	v_mul_f32_e32 v167, v45, v167
	v_cvt_pk_bf16_f32 v152, v160, v161
	v_cvt_pk_bf16_f32 v153, v162, v163
	v_cvt_pk_bf16_f32 v154, v164, v165
	v_cvt_pk_bf16_f32 v155, v166, v167
	v_permlane16_swap_b32_e32 v148, v150
	v_permlane16_swap_b32_e32 v149, v151
	global_store_dwordx4 v251, v[148:151], s[6:7]
	v_mul_f32_e32 v168, v38, v38
	v_mul_f32_e32 v169, v39, v39
	v_mul_f32_e32 v170, v40, v40
	v_mul_f32_e32 v171, v41, v41
	v_mul_f32_e32 v172, v34, v34
	v_mul_f32_e32 v173, v35, v35
	v_mul_f32_e32 v174, v36, v36
	v_mul_f32_e32 v175, v37, v37
	v_fma_f32 v168, v168, s18, v198
	v_fma_f32 v169, v169, s18, v198
	v_fma_f32 v170, v170, s18, v198
	v_fma_f32 v171, v171, s18, v198
	v_fma_f32 v172, v172, s18, v198
	v_fma_f32 v173, v173, s18, v198
	v_fma_f32 v174, v174, s18, v198
	v_fma_f32 v175, v175, s18, v198
; #define GAS __attribute__((address_space(1)))
; __device__ __forceinline__ uint2 pack4(f32x4 v) { return make_uint2(pack2(v[0], v[1]), pack2(v[2], v[3])); }
; template <int MODE>
; __device__ __forceinline__ void epi_elem(char* ws, float* outp, const float* b_gate, int g0, int rl, int col, f32x4 v) {
;   if (MODE == E_U || MODE == E_GV) {
;     int lc = col & 1023;
;     f32x4 o; for (int i = 0; i < 4; ++i) o[i] = gelu_f(v[i]);
;     u16* dst = (u16*)(ws + (MODE == E_U ? W_U : W_GV));
;     *(GAS uint2*)(dst + (size_t)rl * 1024 + lc) = pack4(o);
; template <int MODE>
; __device__ __forceinline__ void epi_store(char* ws, float* outp, const float* b_gate, int g0, const f32x4 (&acc)[2][2][4][2], int rbase, int cbase) {
; #pragma unroll
;   for (int ai = 0; ai < 2; ++ai)
; #pragma unroll
;     for (int bj = 0; bj < 2; ++bj)
; #pragma unroll
;       for (int m = 0; m < 4; ++m) {
; #pragma unroll
;         for (int n = 0; n < 2; ++n)
;           epi_elem<MODE>(ws, outp, b_gate, g0, rbase + ai * HALF + m * 16, cbase + bj * HALF + n * 16, acc[ai][bj][m][n]);
;         if ((m & 1) && (MODE != E_M1 && MODE != E_MG)) __builtin_amdgcn_sched_barrier(0);
;         if (m == 3 && (MODE == E_M1 || MODE == E_MG)) __builtin_amdgcn_sched_barrier(0);
;       }
	v_mul_f32_e32 v168, v38, v168
	v_mul_f32_e32 v169, v39, v169
	v_mul_f32_e32 v170, v40, v170
	v_mul_f32_e32 v171, v41, v171
	v_mul_f32_e32 v172, v34, v172
	v_mul_f32_e32 v173, v35, v173
	v_mul_f32_e32 v174, v36, v174
	v_mul_f32_e32 v175, v37, v175
	v_exp_f32_e32 v168, v168
	v_exp_f32_e32 v169, v169
	v_exp_f32_e32 v170, v170
	v_exp_f32_e32 v171, v171
	v_exp_f32_e32 v172, v172
	v_exp_f32_e32 v173, v173
	v_exp_f32_e32 v174, v174
	v_exp_f32_e32 v175, v175
	v_add_f32_e32 v168, 1.0, v168
	v_add_f32_e32 v169, 1.0, v169
	v_add_f32_e32 v170, 1.0, v170
	v_add_f32_e32 v171, 1.0, v171
	v_add_f32_e32 v172, 1.0, v172
	v_add_f32_e32 v173, 1.0, v173
	v_add_f32_e32 v174, 1.0, v174
	v_add_f32_e32 v175, 1.0, v175
	v_rcp_f32_e32 v168, v168
	v_rcp_f32_e32 v169, v169
	v_rcp_f32_e32 v170, v170
	v_rcp_f32_e32 v171, v171
	v_rcp_f32_e32 v172, v172
	v_rcp_f32_e32 v173, v173
	v_rcp_f32_e32 v174, v174
	v_rcp_f32_e32 v175, v175
	v_mul_f32_e32 v168, v38, v168
	v_mul_f32_e32 v169, v39, v169
	v_mul_f32_e32 v170, v40, v170
	v_mul_f32_e32 v171, v41, v171
	v_mul_f32_e32 v172, v34, v172
	v_mul_f32_e32 v173, v35, v173
	v_mul_f32_e32 v174, v36, v174
	v_mul_f32_e32 v175, v37, v175
	v_cvt_pk_bf16_f32 v156, v168, v169
	v_cvt_pk_bf16_f32 v157, v170, v171
	v_cvt_pk_bf16_f32 v158, v172, v173
	v_cvt_pk_bf16_f32 v159, v174, v175
	v_permlane16_swap_b32_e32 v152, v154
	v_permlane16_swap_b32_e32 v153, v155
	global_store_dwordx4 v252, v[152:155], s[6:7]
	v_mul_f32_e32 v160, v30, v30
	v_mul_f32_e32 v161, v31, v31
	v_mul_f32_e32 v162, v32, v32
	v_mul_f32_e32 v163, v33, v33
	v_mul_f32_e32 v164, v26, v26
	v_mul_f32_e32 v165, v27, v27
	v_mul_f32_e32 v166, v28, v28
	v_mul_f32_e32 v167, v29, v29
	v_fma_f32 v160, v160, s18, v198
	v_fma_f32 v161, v161, s18, v198
	v_fma_f32 v162, v162, s18, v198
	v_fma_f32 v163, v163, s18, v198
	v_fma_f32 v164, v164, s18, v198
	v_fma_f32 v165, v165, s18, v198
	v_fma_f32 v166, v166, s18, v198
	v_fma_f32 v167, v167, s18, v198
	v_mul_f32_e32 v160, v30, v160
	v_mul_f32_e32 v161, v31, v161
	v_mul_f32_e32 v162, v32, v162
	v_mul_f32_e32 v163, v33, v163
	v_mul_f32_e32 v164, v26, v164
	v_mul_f32_e32 v165, v27, v165
	v_mul_f32_e32 v166, v28, v166
	v_mul_f32_e32 v167, v29, v167
	v_exp_f32_e32 v160, v160
	v_exp_f32_e32 v161, v161
	v_exp_f32_e32 v162, v162
	v_exp_f32_e32 v163, v163
	v_exp_f32_e32 v164, v164
	v_exp_f32_e32 v165, v165
	v_exp_f32_e32 v166, v166
	v_exp_f32_e32 v167, v167
	v_add_f32_e32 v160, 1.0, v160
	v_add_f32_e32 v161, 1.0, v161
	v_add_f32_e32 v162, 1.0, v162
	v_add_f32_e32 v163, 1.0, v163
	v_add_f32_e32 v164, 1.0, v164
	v_add_f32_e32 v165, 1.0, v165
	v_add_f32_e32 v166, 1.0, v166
	v_add_f32_e32 v167, 1.0, v167
	v_rcp_f32_e32 v160, v160
	v_rcp_f32_e32 v161, v161
	v_rcp_f32_e32 v162, v162
	v_rcp_f32_e32 v163, v163
	v_rcp_f32_e32 v164, v164
	v_rcp_f32_e32 v165, v165
	v_rcp_f32_e32 v166, v166
	v_rcp_f32_e32 v167, v167
	v_mul_f32_e32 v160, v30, v160
	v_mul_f32_e32 v161, v31, v161
	v_mul_f32_e32 v162, v32, v162
	v_mul_f32_e32 v163, v33, v163
	v_mul_f32_e32 v164, v26, v164
	v_mul_f32_e32 v165, v27, v165
	v_mul_f32_e32 v166, v28, v166
	v_mul_f32_e32 v167, v29, v167
	v_cvt_pk_bf16_f32 v144, v160, v161
	v_cvt_pk_bf16_f32 v145, v162, v163
	v_cvt_pk_bf16_f32 v146, v164, v165
	v_cvt_pk_bf16_f32 v147, v166, v167
	v_permlane16_swap_b32_e32 v156, v158
	v_permlane16_swap_b32_e32 v157, v159
	global_store_dwordx4 v253, v[156:159], s[6:7]
	v_mul_f32_e32 v168, v22, v22
	v_mul_f32_e32 v169, v23, v23
	v_mul_f32_e32 v170, v24, v24
	v_mul_f32_e32 v171, v25, v25
	v_mul_f32_e32 v172, v18, v18
	v_mul_f32_e32 v173, v19, v19
	v_mul_f32_e32 v174, v20, v20
	v_mul_f32_e32 v175, v21, v21
	v_fma_f32 v168, v168, s18, v198
	v_fma_f32 v169, v169, s18, v198
	v_fma_f32 v170, v170, s18, v198
	v_fma_f32 v171, v171, s18, v198
	v_fma_f32 v172, v172, s18, v198
	v_fma_f32 v173, v173, s18, v198
	v_fma_f32 v174, v174, s18, v198
	v_fma_f32 v175, v175, s18, v198
	v_mul_f32_e32 v168, v22, v168
	v_mul_f32_e32 v169, v23, v169
	v_mul_f32_e32 v170, v24, v170
	v_mul_f32_e32 v171, v25, v171
	v_mul_f32_e32 v172, v18, v172
	v_mul_f32_e32 v173, v19, v173
	v_mul_f32_e32 v174, v20, v174
	v_mul_f32_e32 v175, v21, v175
	v_exp_f32_e32 v168, v168
	v_exp_f32_e32 v169, v169
	v_exp_f32_e32 v170, v170
	v_exp_f32_e32 v171, v171
	v_exp_f32_e32 v172, v172
	v_exp_f32_e32 v173, v173
	v_exp_f32_e32 v174, v174
	v_exp_f32_e32 v175, v175
	v_add_f32_e32 v168, 1.0, v168
	v_add_f32_e32 v169, 1.0, v169
	v_add_f32_e32 v170, 1.0, v170
	v_add_f32_e32 v171, 1.0, v171
	v_add_f32_e32 v172, 1.0, v172
	v_add_f32_e32 v173, 1.0, v173
	v_add_f32_e32 v174, 1.0, v174
	v_add_f32_e32 v175, 1.0, v175
	v_rcp_f32_e32 v168, v168
	v_rcp_f32_e32 v169, v169
	v_rcp_f32_e32 v170, v170
; #define GAS __attribute__((address_space(1)))
; __device__ __forceinline__ uint2 pack4(f32x4 v) { return make_uint2(pack2(v[0], v[1]), pack2(v[2], v[3])); }
; template <int MODE>
; __device__ __forceinline__ void epi_elem(char* ws, float* outp, const float* b_gate, int g0, int rl, int col, f32x4 v) {
;   if (MODE == E_U || MODE == E_GV) {
;     int lc = col & 1023;
;     f32x4 o; for (int i = 0; i < 4; ++i) o[i] = gelu_f(v[i]);
;     u16* dst = (u16*)(ws + (MODE == E_U ? W_U : W_GV));
;     *(GAS uint2*)(dst + (size_t)rl * 1024 + lc) = pack4(o);
; template <int MODE>
; __device__ __forceinline__ void epi_store(char* ws, float* outp, const float* b_gate, int g0, const f32x4 (&acc)[2][2][4][2], int rbase, int cbase) {
; #pragma unroll
;   for (int ai = 0; ai < 2; ++ai)
; #pragma unroll
;     for (int bj = 0; bj < 2; ++bj)
; #pragma unroll
;       for (int m = 0; m < 4; ++m) {
; #pragma unroll
;         for (int n = 0; n < 2; ++n)
;           epi_elem<MODE>(ws, outp, b_gate, g0, rbase + ai * HALF + m * 16, cbase + bj * HALF + n * 16, acc[ai][bj][m][n]);
;         if ((m & 1) && (MODE != E_M1 && MODE != E_MG)) __builtin_amdgcn_sched_barrier(0);
;         if (m == 3 && (MODE == E_M1 || MODE == E_MG)) __builtin_amdgcn_sched_barrier(0);
;       }
	v_rcp_f32_e32 v171, v171
	v_rcp_f32_e32 v172, v172
	v_rcp_f32_e32 v173, v173
	v_rcp_f32_e32 v174, v174
	v_rcp_f32_e32 v175, v175
	v_mul_f32_e32 v168, v22, v168
	v_mul_f32_e32 v169, v23, v169
	v_mul_f32_e32 v170, v24, v170
	v_mul_f32_e32 v171, v25, v171
	v_mul_f32_e32 v172, v18, v172
	v_mul_f32_e32 v173, v19, v173
	v_mul_f32_e32 v174, v20, v174
	v_mul_f32_e32 v175, v21, v175
	v_cvt_pk_bf16_f32 v148, v168, v169
	v_cvt_pk_bf16_f32 v149, v170, v171
	v_cvt_pk_bf16_f32 v150, v172, v173
	v_cvt_pk_bf16_f32 v151, v174, v175
	v_permlane16_swap_b32_e32 v144, v146
	v_permlane16_swap_b32_e32 v145, v147
	global_store_dwordx4 v250, v[144:147], s[6:7] offset:256
	v_mul_f32_e32 v160, v14, v14
	v_mul_f32_e32 v161, v15, v15
	v_mul_f32_e32 v162, v16, v16
	v_mul_f32_e32 v163, v17, v17
	v_mul_f32_e32 v164, v10, v10
	v_mul_f32_e32 v165, v11, v11
	v_mul_f32_e32 v166, v12, v12
	v_mul_f32_e32 v167, v13, v13
	v_fma_f32 v160, v160, s18, v198
	v_fma_f32 v161, v161, s18, v198
	v_fma_f32 v162, v162, s18, v198
	v_fma_f32 v163, v163, s18, v198
	v_fma_f32 v164, v164, s18, v198
	v_fma_f32 v165, v165, s18, v198
	v_fma_f32 v166, v166, s18, v198
	v_fma_f32 v167, v167, s18, v198
	v_mul_f32_e32 v160, v14, v160
	v_mul_f32_e32 v161, v15, v161
	v_mul_f32_e32 v162, v16, v162
	v_mul_f32_e32 v163, v17, v163
	v_mul_f32_e32 v164, v10, v164
	v_mul_f32_e32 v165, v11, v165
	v_mul_f32_e32 v166, v12, v166
	v_mul_f32_e32 v167, v13, v167
	v_exp_f32_e32 v160, v160
	v_exp_f32_e32 v161, v161
	v_exp_f32_e32 v162, v162
	v_exp_f32_e32 v163, v163
	v_exp_f32_e32 v164, v164
	v_exp_f32_e32 v165, v165
	v_exp_f32_e32 v166, v166
	v_exp_f32_e32 v167, v167
	v_add_f32_e32 v160, 1.0, v160
	v_add_f32_e32 v161, 1.0, v161
	v_add_f32_e32 v162, 1.0, v162
	v_add_f32_e32 v163, 1.0, v163
	v_add_f32_e32 v164, 1.0, v164
	v_add_f32_e32 v165, 1.0, v165
	v_add_f32_e32 v166, 1.0, v166
	v_add_f32_e32 v167, 1.0, v167
	v_rcp_f32_e32 v160, v160
	v_rcp_f32_e32 v161, v161
	v_rcp_f32_e32 v162, v162
	v_rcp_f32_e32 v163, v163
	v_rcp_f32_e32 v164, v164
	v_rcp_f32_e32 v165, v165
	v_rcp_f32_e32 v166, v166
	v_rcp_f32_e32 v167, v167
	v_mul_f32_e32 v160, v14, v160
	v_mul_f32_e32 v161, v15, v161
	v_mul_f32_e32 v162, v16, v162
	v_mul_f32_e32 v163, v17, v163
	v_mul_f32_e32 v164, v10, v164
	v_mul_f32_e32 v165, v11, v165
	v_mul_f32_e32 v166, v12, v166
	v_mul_f32_e32 v167, v13, v167
	v_cvt_pk_bf16_f32 v152, v160, v161
	v_cvt_pk_bf16_f32 v153, v162, v163
	v_cvt_pk_bf16_f32 v154, v164, v165
	v_cvt_pk_bf16_f32 v155, v166, v167
	v_permlane16_swap_b32_e32 v148, v150
	v_permlane16_swap_b32_e32 v149, v151
	global_store_dwordx4 v251, v[148:151], s[6:7] offset:256
	v_mul_f32_e32 v168, v6, v6
	v_mul_f32_e32 v169, v7, v7
	v_mul_f32_e32 v170, v8, v8
	v_mul_f32_e32 v171, v9, v9
	v_mul_f32_e32 v172, v2, v2
	v_mul_f32_e32 v173, v3, v3
	v_mul_f32_e32 v174, v4, v4
	v_mul_f32_e32 v175, v5, v5
	v_fma_f32 v168, v168, s18, v198
	v_fma_f32 v169, v169, s18, v198
	v_fma_f32 v170, v170, s18, v198
	v_fma_f32 v171, v171, s18, v198
	v_fma_f32 v172, v172, s18, v198
	v_fma_f32 v173, v173, s18, v198
	v_fma_f32 v174, v174, s18, v198
	v_fma_f32 v175, v175, s18, v198
	v_mul_f32_e32 v168, v6, v168
	v_mul_f32_e32 v169, v7, v169
	v_mul_f32_e32 v170, v8, v170
	v_mul_f32_e32 v171, v9, v171
	v_mul_f32_e32 v172, v2, v172
	v_mul_f32_e32 v173, v3, v173
	v_mul_f32_e32 v174, v4, v174
	v_mul_f32_e32 v175, v5, v175
	v_exp_f32_e32 v168, v168
	v_exp_f32_e32 v169, v169
	v_exp_f32_e32 v170, v170
	v_exp_f32_e32 v171, v171
	v_exp_f32_e32 v172, v172
	v_exp_f32_e32 v173, v173
	v_exp_f32_e32 v174, v174
	v_exp_f32_e32 v175, v175
	v_add_f32_e32 v168, 1.0, v168
	v_add_f32_e32 v169, 1.0, v169
	v_add_f32_e32 v170, 1.0, v170
	v_add_f32_e32 v171, 1.0, v171
	v_add_f32_e32 v172, 1.0, v172
	v_add_f32_e32 v173, 1.0, v173
	v_add_f32_e32 v174, 1.0, v174
	v_add_f32_e32 v175, 1.0, v175
	v_rcp_f32_e32 v168, v168
	v_rcp_f32_e32 v169, v169
	v_rcp_f32_e32 v170, v170
	v_rcp_f32_e32 v171, v171
	v_rcp_f32_e32 v172, v172
	v_rcp_f32_e32 v173, v173
	v_rcp_f32_e32 v174, v174
	v_rcp_f32_e32 v175, v175
	v_mul_f32_e32 v168, v6, v168
	v_mul_f32_e32 v169, v7, v169
	v_mul_f32_e32 v170, v8, v170
	v_mul_f32_e32 v171, v9, v171
	v_mul_f32_e32 v172, v2, v172
	v_mul_f32_e32 v173, v3, v173
	v_mul_f32_e32 v174, v4, v174
	v_mul_f32_e32 v175, v5, v175
	v_cvt_pk_bf16_f32 v156, v168, v169
	v_cvt_pk_bf16_f32 v157, v170, v171
	v_cvt_pk_bf16_f32 v158, v172, v173
	v_cvt_pk_bf16_f32 v159, v174, v175
	v_permlane16_swap_b32_e32 v152, v154
	v_permlane16_swap_b32_e32 v153, v155
	global_store_dwordx4 v252, v[152:155], s[6:7] offset:256
	s_nop 1
	v_permlane16_swap_b32_e32 v156, v158
	v_permlane16_swap_b32_e32 v157, v159
	global_store_dwordx4 v253, v[156:159], s[6:7] offset:256
	s_branch .LBB0_996

; #define GAS __attribute__((address_space(1)))
; __device__ __forceinline__ uint2 pack4(f32x4 v) { return make_uint2(pack2(v[0], v[1]), pack2(v[2], v[3])); }
; template <int MODE>
; __device__ __forceinline__ void epi_elem(char* ws, float* outp, const float* b_gate, int g0, int rl, int col, f32x4 v) {
;     ...
;   } else if (MODE == E_T || MODE == E_FF) {
;     *(GAS uint2*)((u16*)(ws + (MODE == E_T ? W_T : W_FF)) + (size_t)rl * 1024 + col) = pack4(v);
; template <int MODE>
; __device__ __forceinline__ void epi_store(char* ws, float* outp, const float* b_gate, int g0, const f32x4 (&acc)[2][2][4][2], int rbase, int cbase) {
; #pragma unroll
;   for (int ai = 0; ai < 2; ++ai)
; #pragma unroll
;     for (int bj = 0; bj < 2; ++bj)
; #pragma unroll
;       for (int m = 0; m < 4; ++m) {
; #pragma unroll
;         for (int n = 0; n < 2; ++n)
;           epi_elem<MODE>(ws, outp, b_gate, g0, rbase + ai * HALF + m * 16, cbase + bj * HALF + n * 16, acc[ai][bj][m][n]);
;         if ((m & 1) && (MODE != E_M1 && MODE != E_MG)) __builtin_amdgcn_sched_barrier(0);
;         if (m == 3 && (MODE == E_M1 || MODE == E_MG)) __builtin_amdgcn_sched_barrier(0);
;       }
.LBB0_992:
	s_and_b64 vcc, exec, s[4:5]
	v_ashrrev_i32_e32 v143, 31, v142
	s_cbranch_vccz .LBB0_994
	v_bfe_u32 v141, v184, 2, 2
	v_and_b32_e32 v143, 1, v141
	v_lshrrev_b32_e32 v187, 1, v141
	v_lshlrev_b32_e32 v143, 4, v143
	v_lshl_add_u32 v143, v187, 3, v143
	v_lshlrev_b32_e32 v141, 2, v141
	v_sub_u32_e32 v143, v143, v141
	v_add_u32_e32 v143, v140, v143
	v_lshlrev_b32_e32 v141, 11, v142
	v_lshl_add_u32 v250, v143, 1, v141
	v_add_u32_e32 v251, 0x8000, v250
	v_add_u32_e32 v252, 0x10000, v250
	v_add_u32_e32 v253, 0x18000, v250
	s_add_u32 s4, s2, 0x26dc0000
	s_addc_u32 s5, s3, 0
	s_add_u32 s6, s2, 0x26e00000
	s_addc_u32 s7, s3, 0
	v_cvt_pk_bf16_f32 v144, v126, v127
	v_cvt_pk_bf16_f32 v145, v128, v129
	v_cvt_pk_bf16_f32 v146, v122, v123
	v_cvt_pk_bf16_f32 v147, v124, v125
	v_cvt_pk_bf16_f32 v148, v118, v119
	v_cvt_pk_bf16_f32 v149, v120, v121
	v_cvt_pk_bf16_f32 v150, v114, v115
	v_cvt_pk_bf16_f32 v151, v116, v117
	v_permlane16_swap_b32_e32 v144, v146
	v_permlane16_swap_b32_e32 v145, v147
	global_store_dwordx4 v250, v[144:147], s[4:5]
	v_cvt_pk_bf16_f32 v152, v110, v111
	v_cvt_pk_bf16_f32 v153, v112, v113
	v_cvt_pk_bf16_f32 v154, v106, v107
	v_cvt_pk_bf16_f32 v155, v108, v109
	v_permlane16_swap_b32_e32 v148, v150
	v_permlane16_swap_b32_e32 v149, v151
	global_store_dwordx4 v251, v[148:151], s[4:5]
	v_cvt_pk_bf16_f32 v156, v102, v103
	v_cvt_pk_bf16_f32 v157, v104, v105
	v_cvt_pk_bf16_f32 v158, v98, v99
	v_cvt_pk_bf16_f32 v159, v100, v101
	v_permlane16_swap_b32_e32 v152, v154
	v_permlane16_swap_b32_e32 v153, v155
	global_store_dwordx4 v252, v[152:155], s[4:5]
	v_cvt_pk_bf16_f32 v144, v94, v95
	v_cvt_pk_bf16_f32 v145, v96, v97
	v_cvt_pk_bf16_f32 v146, v90, v91
	v_cvt_pk_bf16_f32 v147, v92, v93
	v_permlane16_swap_b32_e32 v156, v158
	v_permlane16_swap_b32_e32 v157, v159
	global_store_dwordx4 v253, v[156:159], s[4:5]
	v_cvt_pk_bf16_f32 v148, v86, v87
	v_cvt_pk_bf16_f32 v149, v88, v89
	v_cvt_pk_bf16_f32 v150, v82, v83
	v_cvt_pk_bf16_f32 v151, v84, v85
	v_permlane16_swap_b32_e32 v144, v146
	v_permlane16_swap_b32_e32 v145, v147
	global_store_dwordx4 v250, v[144:147], s[4:5] offset:256
	v_cvt_pk_bf16_f32 v152, v78, v79
	v_cvt_pk_bf16_f32 v153, v80, v81
	v_cvt_pk_bf16_f32 v154, v74, v75
	v_cvt_pk_bf16_f32 v155, v76, v77
	v_permlane16_swap_b32_e32 v148, v150
	v_permlane16_swap_b32_e32 v149, v151
	global_store_dwordx4 v251, v[148:151], s[4:5] offset:256
	v_cvt_pk_bf16_f32 v156, v70, v71
	v_cvt_pk_bf16_f32 v157, v72, v73
	v_cvt_pk_bf16_f32 v158, v66, v67
	v_cvt_pk_bf16_f32 v159, v68, v69
	v_permlane16_swap_b32_e32 v152, v154
	v_permlane16_swap_b32_e32 v153, v155
	global_store_dwordx4 v252, v[152:155], s[4:5] offset:256
	v_cvt_pk_bf16_f32 v144, v62, v63
	v_cvt_pk_bf16_f32 v145, v64, v65
	v_cvt_pk_bf16_f32 v146, v58, v59
	v_cvt_pk_bf16_f32 v147, v60, v61
	v_permlane16_swap_b32_e32 v156, v158
	v_permlane16_swap_b32_e32 v157, v159
	global_store_dwordx4 v253, v[156:159], s[4:5] offset:256
	v_cvt_pk_bf16_f32 v148, v54, v55
	v_cvt_pk_bf16_f32 v149, v56, v57
	v_cvt_pk_bf16_f32 v150, v50, v51
	v_cvt_pk_bf16_f32 v151, v52, v53
	v_permlane16_swap_b32_e32 v144, v146
	v_permlane16_swap_b32_e32 v145, v147
	global_store_dwordx4 v250, v[144:147], s[6:7]
	v_cvt_pk_bf16_f32 v152, v46, v47
	v_cvt_pk_bf16_f32 v153, v48, v49
	v_cvt_pk_bf16_f32 v154, v42, v43
	v_cvt_pk_bf16_f32 v155, v44, v45
	v_permlane16_swap_b32_e32 v148, v150
	v_permlane16_swap_b32_e32 v149, v151
	global_store_dwordx4 v251, v[148:151], s[6:7]
	v_cvt_pk_bf16_f32 v156, v38, v39
	v_cvt_pk_bf16_f32 v157, v40, v41
	v_cvt_pk_bf16_f32 v158, v34, v35
	v_cvt_pk_bf16_f32 v159, v36, v37
	v_permlane16_swap_b32_e32 v152, v154
	v_permlane16_swap_b32_e32 v153, v155
	global_store_dwordx4 v252, v[152:155], s[6:7]
	v_cvt_pk_bf16_f32 v144, v30, v31
	v_cvt_pk_bf16_f32 v145, v32, v33
	v_cvt_pk_bf16_f32 v146, v26, v27
	v_cvt_pk_bf16_f32 v147, v28, v29
	v_permlane16_swap_b32_e32 v156, v158
	v_permlane16_swap_b32_e32 v157, v159
	global_store_dwordx4 v253, v[156:159], s[6:7]
	v_cvt_pk_bf16_f32 v148, v22, v23
	v_cvt_pk_bf16_f32 v149, v24, v25
	v_cvt_pk_bf16_f32 v150, v18, v19
	v_cvt_pk_bf16_f32 v151, v20, v21
	v_permlane16_swap_b32_e32 v144, v146
	v_permlane16_swap_b32_e32 v145, v147
	global_store_dwordx4 v250, v[144:147], s[6:7] offset:256
	v_cvt_pk_bf16_f32 v152, v14, v15
	v_cvt_pk_bf16_f32 v153, v16, v17
	v_cvt_pk_bf16_f32 v154, v10, v11
	v_cvt_pk_bf16_f32 v155, v12, v13
	v_permlane16_swap_b32_e32 v148, v150
	v_permlane16_swap_b32_e32 v149, v151
	global_store_dwordx4 v251, v[148:151], s[6:7] offset:256
	v_cvt_pk_bf16_f32 v156, v6, v7
	v_cvt_pk_bf16_f32 v157, v8, v9
	v_cvt_pk_bf16_f32 v158, v2, v3
	v_cvt_pk_bf16_f32 v159, v4, v5
	v_permlane16_swap_b32_e32 v152, v154
	v_permlane16_swap_b32_e32 v153, v155
	global_store_dwordx4 v252, v[152:155], s[6:7] offset:256
	s_nop 1
	v_permlane16_swap_b32_e32 v156, v158
	v_permlane16_swap_b32_e32 v157, v159
	global_store_dwordx4 v253, v[156:159], s[6:7] offset:256
	s_branch .LBB0_996
; #define GAS __attribute__((address_space(1)))
; __device__ __forceinline__ uint2 pack4(f32x4 v) { return make_uint2(pack2(v[0], v[1]), pack2(v[2], v[3])); }
; template <int MODE>
; __device__ __forceinline__ void epi_elem(char* ws, float* outp, const float* b_gate, int g0, int rl, int col, f32x4 v) {
;   if (MODE == E_U || MODE == E_GV) {
;     int lc = col & 1023;
;     f32x4 o; for (int i = 0; i < 4; ++i) o[i] = gelu_f(v[i]);
;     u16* dst = (u16*)(ws + (MODE == E_U ? W_U : W_GV));
;     *(GAS uint2*)(dst + (size_t)rl * 1024 + lc) = pack4(o);
; template <int MODE>
; __device__ __forceinline__ void epi_store(char* ws, float* outp, const float* b_gate, int g0, const f32x4 (&acc)[2][2][4][2], int rbase, int cbase) {
; #pragma unroll
;   for (int ai = 0; ai < 2; ++ai)
; #pragma unroll
;     for (int bj = 0; bj < 2; ++bj)
; #pragma unroll
;       for (int m = 0; m < 4; ++m) {
; #pragma unroll
;         for (int n = 0; n < 2; ++n)
;           epi_elem<MODE>(ws, outp, b_gate, g0, rbase + ai * HALF + m * 16, cbase + bj * HALF + n * 16, acc[ai][bj][m][n]);
;         if ((m & 1) && (MODE != E_M1 && MODE != E_MG)) __builtin_amdgcn_sched_barrier(0);
;         if (m == 3 && (MODE == E_M1 || MODE == E_MG)) __builtin_amdgcn_sched_barrier(0);
;       }
.LBB0_994:
	s_andn2_b64 vcc, exec, s[8:9]
	s_cbranch_vccnz .LBB0_996
	v_bfe_u32 v141, v184, 2, 2
	v_and_b32_e32 v143, 1, v141
	v_lshrrev_b32_e32 v187, 1, v141
	v_lshlrev_b32_e32 v143, 4, v143
	v_lshl_add_u32 v143, v187, 3, v143
	v_lshlrev_b32_e32 v141, 2, v141
	v_sub_u32_e32 v143, v143, v141
	v_add_u32_e32 v143, v140, v143
	v_and_b32_e32 v143, 0x3ff, v143
	v_lshlrev_b32_e32 v141, 11, v142
	v_lshl_add_u32 v250, v143, 1, v141
	v_add_u32_e32 v251, 0x8000, v250
	v_add_u32_e32 v252, 0x10000, v250
	v_add_u32_e32 v253, 0x18000, v250
	s_add_u32 s4, s2, 0x65c0000
	s_addc_u32 s5, s3, 0
	s_add_u32 s6, s2, 0x6600000
	s_addc_u32 s7, s3, 0
	s_mov_b32 s18, 0xbdd2d3e7
	v_mul_f32_e32 v160, v126, v126
	v_mul_f32_e32 v161, v127, v127
	v_mul_f32_e32 v162, v128, v128
	v_mul_f32_e32 v163, v129, v129
	v_mul_f32_e32 v164, v122, v122
	v_mul_f32_e32 v165, v123, v123
	v_mul_f32_e32 v166, v124, v124
	v_mul_f32_e32 v167, v125, v125
	v_fma_f32 v160, v160, s18, v198
	v_fma_f32 v161, v161, s18, v198
	v_fma_f32 v162, v162, s18, v198
	v_fma_f32 v163, v163, s18, v198
	v_fma_f32 v164, v164, s18, v198
	v_fma_f32 v165, v165, s18, v198
	v_fma_f32 v166, v166, s18, v198
	v_fma_f32 v167, v167, s18, v198
	v_mul_f32_e32 v160, v126, v160
	v_mul_f32_e32 v161, v127, v161
	v_mul_f32_e32 v162, v128, v162
	v_mul_f32_e32 v163, v129, v163
	v_mul_f32_e32 v164, v122, v164
	v_mul_f32_e32 v165, v123, v165
	v_mul_f32_e32 v166, v124, v166
	v_mul_f32_e32 v167, v125, v167
	v_exp_f32_e32 v160, v160
	v_exp_f32_e32 v161, v161
	v_exp_f32_e32 v162, v162
	v_exp_f32_e32 v163, v163
	v_exp_f32_e32 v164, v164
	v_exp_f32_e32 v165, v165
	v_exp_f32_e32 v166, v166
	v_exp_f32_e32 v167, v167
	v_add_f32_e32 v160, 1.0, v160
	v_add_f32_e32 v161, 1.0, v161
	v_add_f32_e32 v162, 1.0, v162
	v_add_f32_e32 v163, 1.0, v163
	v_add_f32_e32 v164, 1.0, v164
	v_add_f32_e32 v165, 1.0, v165
	v_add_f32_e32 v166, 1.0, v166
	v_add_f32_e32 v167, 1.0, v167
	v_rcp_f32_e32 v160, v160
	v_rcp_f32_e32 v161, v161
	v_rcp_f32_e32 v162, v162
	v_rcp_f32_e32 v163, v163
	v_rcp_f32_e32 v164, v164
	v_rcp_f32_e32 v165, v165
	v_rcp_f32_e32 v166, v166
	v_rcp_f32_e32 v167, v167
	v_mul_f32_e32 v160, v126, v160
	v_mul_f32_e32 v161, v127, v161
	v_mul_f32_e32 v162, v128, v162
	v_mul_f32_e32 v163, v129, v163
	v_mul_f32_e32 v164, v122, v164
	v_mul_f32_e32 v165, v123, v165
	v_mul_f32_e32 v166, v124, v166
	v_mul_f32_e32 v167, v125, v167
	v_cvt_pk_bf16_f32 v144, v160, v161
	v_cvt_pk_bf16_f32 v145, v162, v163
	v_cvt_pk_bf16_f32 v146, v164, v165
	v_cvt_pk_bf16_f32 v147, v166, v167
	v_mul_f32_e32 v168, v118, v118
	v_mul_f32_e32 v169, v119, v119
	v_mul_f32_e32 v170, v120, v120
	v_mul_f32_e32 v171, v121, v121
	v_mul_f32_e32 v172, v114, v114
	v_mul_f32_e32 v173, v115, v115
	v_mul_f32_e32 v174, v116, v116
	v_mul_f32_e32 v175, v117, v117
	v_fma_f32 v168, v168, s18, v198
	v_fma_f32 v169, v169, s18, v198
	v_fma_f32 v170, v170, s18, v198
	v_fma_f32 v171, v171, s18, v198
	v_fma_f32 v172, v172, s18, v198
	v_fma_f32 v173, v173, s18, v198
	v_fma_f32 v174, v174, s18, v198
	v_fma_f32 v175, v175, s18, v198
	v_mul_f32_e32 v168, v118, v168
	v_mul_f32_e32 v169, v119, v169
	v_mul_f32_e32 v170, v120, v170
	v_mul_f32_e32 v171, v121, v171
	v_mul_f32_e32 v172, v114, v172
	v_mul_f32_e32 v173, v115, v173
	v_mul_f32_e32 v174, v116, v174
	v_mul_f32_e32 v175, v117, v175
	v_exp_f32_e32 v168, v168
	v_exp_f32_e32 v169, v169
	v_exp_f32_e32 v170, v170
	v_exp_f32_e32 v171, v171
	v_exp_f32_e32 v172, v172
	v_exp_f32_e32 v173, v173
	v_exp_f32_e32 v174, v174
	v_exp_f32_e32 v175, v175
	v_add_f32_e32 v168, 1.0, v168
	v_add_f32_e32 v169, 1.0, v169
	v_add_f32_e32 v170, 1.0, v170
	v_add_f32_e32 v171, 1.0, v171
	v_add_f32_e32 v172, 1.0, v172
	v_add_f32_e32 v173, 1.0, v173
	v_add_f32_e32 v174, 1.0, v174
	v_add_f32_e32 v175, 1.0, v175
	v_rcp_f32_e32 v168, v168
	v_rcp_f32_e32 v169, v169
	v_rcp_f32_e32 v170, v170
	v_rcp_f32_e32 v171, v171
	v_rcp_f32_e32 v172, v172
	v_rcp_f32_e32 v173, v173
	v_rcp_f32_e32 v174, v174
	v_rcp_f32_e32 v175, v175
	v_mul_f32_e32 v168, v118, v168
	v_mul_f32_e32 v169, v119, v169
	v_mul_f32_e32 v170, v120, v170
	v_mul_f32_e32 v171, v121, v171
	v_mul_f32_e32 v172, v114, v172
	v_mul_f32_e32 v173, v115, v173
	v_mul_f32_e32 v174, v116, v174
	v_mul_f32_e32 v175, v117, v175
	v_cvt_pk_bf16_f32 v148, v168, v169
	v_cvt_pk_bf16_f32 v149, v170, v171
	v_cvt_pk_bf16_f32 v150, v172, v173
	v_cvt_pk_bf16_f32 v151, v174, v175
	v_permlane16_swap_b32_e32 v144, v146
	v_permlane16_swap_b32_e32 v145, v147
	global_store_dwordx4 v250, v[144:147], s[4:5]
	v_mul_f32_e32 v160, v110, v110
	v_mul_f32_e32 v161, v111, v111
	v_mul_f32_e32 v162, v112, v112
	v_mul_f32_e32 v163, v113, v113
	v_mul_f32_e32 v164, v106, v106
	v_mul_f32_e32 v165, v107, v107
	v_mul_f32_e32 v166, v108, v108
	v_mul_f32_e32 v167, v109, v109
	v_fma_f32 v160, v160, s18, v198
	v_fma_f32 v161, v161, s18, v198
	v_fma_f32 v162, v162, s18, v198
	v_fma_f32 v163, v163, s18, v198
	v_fma_f32 v164, v164, s18, v198
	v_fma_f32 v165, v165, s18, v198
	v_fma_f32 v166, v166, s18, v198
	v_fma_f32 v167, v167, s18, v198
	v_mul_f32_e32 v160, v110, v160
	v_mul_f32_e32 v161, v111, v161
	v_mul_f32_e32 v162, v112, v162
	v_mul_f32_e32 v163, v113, v163
	v_mul_f32_e32 v164, v106, v164
	v_mul_f32_e32 v165, v107, v165
	v_mul_f32_e32 v166, v108, v166
	v_mul_f32_e32 v167, v109, v167
	v_exp_f32_e32 v160, v160
	v_exp_f32_e32 v161, v161
	v_exp_f32_e32 v162, v162
	v_exp_f32_e32 v163, v163
	v_exp_f32_e32 v164, v164
	v_exp_f32_e32 v165, v165
	v_exp_f32_e32 v166, v166
	v_exp_f32_e32 v167, v167
	v_add_f32_e32 v160, 1.0, v160
	v_add_f32_e32 v161, 1.0, v161
	v_add_f32_e32 v162, 1.0, v162
	v_add_f32_e32 v163, 1.0, v163
	v_add_f32_e32 v164, 1.0, v164
	v_add_f32_e32 v165, 1.0, v165
; #define GAS __attribute__((address_space(1)))
; __device__ __forceinline__ uint2 pack4(f32x4 v) { return make_uint2(pack2(v[0], v[1]), pack2(v[2], v[3])); }
; template <int MODE>
; __device__ __forceinline__ void epi_elem(char* ws, float* outp, const float* b_gate, int g0, int rl, int col, f32x4 v) {
;   if (MODE == E_U || MODE == E_GV) {
;     int lc = col & 1023;
;     f32x4 o; for (int i = 0; i < 4; ++i) o[i] = gelu_f(v[i]);
;     u16* dst = (u16*)(ws + (MODE == E_U ? W_U : W_GV));
;     *(GAS uint2*)(dst + (size_t)rl * 1024 + lc) = pack4(o);
; template <int MODE>
; __device__ __forceinline__ void epi_store(char* ws, float* outp, const float* b_gate, int g0, const f32x4 (&acc)[2][2][4][2], int rbase, int cbase) {
; #pragma unroll
;   for (int ai = 0; ai < 2; ++ai)
; #pragma unroll
;     for (int bj = 0; bj < 2; ++bj)
; #pragma unroll
;       for (int m = 0; m < 4; ++m) {
; #pragma unroll
;         for (int n = 0; n < 2; ++n)
;           epi_elem<MODE>(ws, outp, b_gate, g0, rbase + ai * HALF + m * 16, cbase + bj * HALF + n * 16, acc[ai][bj][m][n]);
;         if ((m & 1) && (MODE != E_M1 && MODE != E_MG)) __builtin_amdgcn_sched_barrier(0);
;         if (m == 3 && (MODE == E_M1 || MODE == E_MG)) __builtin_amdgcn_sched_barrier(0);
;       }
	v_add_f32_e32 v166, 1.0, v166
	v_add_f32_e32 v167, 1.0, v167
	v_rcp_f32_e32 v160, v160
	v_rcp_f32_e32 v161, v161
	v_rcp_f32_e32 v162, v162
	v_rcp_f32_e32 v163, v163
	v_rcp_f32_e32 v164, v164
	v_rcp_f32_e32 v165, v165
	v_rcp_f32_e32 v166, v166
	v_rcp_f32_e32 v167, v167
	v_mul_f32_e32 v160, v110, v160
	v_mul_f32_e32 v161, v111, v161
	v_mul_f32_e32 v162, v112, v162
	v_mul_f32_e32 v163, v113, v163
	v_mul_f32_e32 v164, v106, v164
	v_mul_f32_e32 v165, v107, v165
	v_mul_f32_e32 v166, v108, v166
	v_mul_f32_e32 v167, v109, v167
	v_cvt_pk_bf16_f32 v152, v160, v161
	v_cvt_pk_bf16_f32 v153, v162, v163
	v_cvt_pk_bf16_f32 v154, v164, v165
	v_cvt_pk_bf16_f32 v155, v166, v167
	v_permlane16_swap_b32_e32 v148, v150
	v_permlane16_swap_b32_e32 v149, v151
	global_store_dwordx4 v251, v[148:151], s[4:5]
	v_mul_f32_e32 v168, v102, v102
	v_mul_f32_e32 v169, v103, v103
	v_mul_f32_e32 v170, v104, v104
	v_mul_f32_e32 v171, v105, v105
	v_mul_f32_e32 v172, v98, v98
	v_mul_f32_e32 v173, v99, v99
	v_mul_f32_e32 v174, v100, v100
	v_mul_f32_e32 v175, v101, v101
	v_fma_f32 v168, v168, s18, v198
	v_fma_f32 v169, v169, s18, v198
	v_fma_f32 v170, v170, s18, v198
	v_fma_f32 v171, v171, s18, v198
	v_fma_f32 v172, v172, s18, v198
	v_fma_f32 v173, v173, s18, v198
	v_fma_f32 v174, v174, s18, v198
	v_fma_f32 v175, v175, s18, v198
	v_mul_f32_e32 v168, v102, v168
	v_mul_f32_e32 v169, v103, v169
	v_mul_f32_e32 v170, v104, v170
	v_mul_f32_e32 v171, v105, v171
	v_mul_f32_e32 v172, v98, v172
	v_mul_f32_e32 v173, v99, v173
	v_mul_f32_e32 v174, v100, v174
	v_mul_f32_e32 v175, v101, v175
	v_exp_f32_e32 v168, v168
	v_exp_f32_e32 v169, v169
	v_exp_f32_e32 v170, v170
	v_exp_f32_e32 v171, v171
	v_exp_f32_e32 v172, v172
	v_exp_f32_e32 v173, v173
	v_exp_f32_e32 v174, v174
	v_exp_f32_e32 v175, v175
	v_add_f32_e32 v168, 1.0, v168
	v_add_f32_e32 v169, 1.0, v169
	v_add_f32_e32 v170, 1.0, v170
	v_add_f32_e32 v171, 1.0, v171
	v_add_f32_e32 v172, 1.0, v172
	v_add_f32_e32 v173, 1.0, v173
	v_add_f32_e32 v174, 1.0, v174
	v_add_f32_e32 v175, 1.0, v175
	v_rcp_f32_e32 v168, v168
	v_rcp_f32_e32 v169, v169
	v_rcp_f32_e32 v170, v170
	v_rcp_f32_e32 v171, v171
	v_rcp_f32_e32 v172, v172
	v_rcp_f32_e32 v173, v173
	v_rcp_f32_e32 v174, v174
	v_rcp_f32_e32 v175, v175
	v_mul_f32_e32 v168, v102, v168
	v_mul_f32_e32 v169, v103, v169
	v_mul_f32_e32 v170, v104, v170
	v_mul_f32_e32 v171, v105, v171
	v_mul_f32_e32 v172, v98, v172
	v_mul_f32_e32 v173, v99, v173
	v_mul_f32_e32 v174, v100, v174
	v_mul_f32_e32 v175, v101, v175
	v_cvt_pk_bf16_f32 v156, v168, v169
	v_cvt_pk_bf16_f32 v157, v170, v171
	v_cvt_pk_bf16_f32 v158, v172, v173
	v_cvt_pk_bf16_f32 v159, v174, v175
	v_permlane16_swap_b32_e32 v152, v154
	v_permlane16_swap_b32_e32 v153, v155
	global_store_dwordx4 v252, v[152:155], s[4:5]
	v_mul_f32_e32 v160, v94, v94
	v_mul_f32_e32 v161, v95, v95
	v_mul_f32_e32 v162, v96, v96
	v_mul_f32_e32 v163, v97, v97
	v_mul_f32_e32 v164, v90, v90
	v_mul_f32_e32 v165, v91, v91
	v_mul_f32_e32 v166, v92, v92
	v_mul_f32_e32 v167, v93, v93
	v_fma_f32 v160, v160, s18, v198
	v_fma_f32 v161, v161, s18, v198
	v_fma_f32 v162, v162, s18, v198
	v_fma_f32 v163, v163, s18, v198
	v_fma_f32 v164, v164, s18, v198
	v_fma_f32 v165, v165, s18, v198
	v_fma_f32 v166, v166, s18, v198
	v_fma_f32 v167, v167, s18, v198
	v_mul_f32_e32 v160, v94, v160
	v_mul_f32_e32 v161, v95, v161
	v_mul_f32_e32 v162, v96, v162
	v_mul_f32_e32 v163, v97, v163
	v_mul_f32_e32 v164, v90, v164
	v_mul_f32_e32 v165, v91, v165
	v_mul_f32_e32 v166, v92, v166
	v_mul_f32_e32 v167, v93, v167
	v_exp_f32_e32 v160, v160
	v_exp_f32_e32 v161, v161
	v_exp_f32_e32 v162, v162
	v_exp_f32_e32 v163, v163
	v_exp_f32_e32 v164, v164
	v_exp_f32_e32 v165, v165
	v_exp_f32_e32 v166, v166
	v_exp_f32_e32 v167, v167
	v_add_f32_e32 v160, 1.0, v160
	v_add_f32_e32 v161, 1.0, v161
	v_add_f32_e32 v162, 1.0, v162
	v_add_f32_e32 v163, 1.0, v163
	v_add_f32_e32 v164, 1.0, v164
	v_add_f32_e32 v165, 1.0, v165
	v_add_f32_e32 v166, 1.0, v166
	v_add_f32_e32 v167, 1.0, v167
	v_rcp_f32_e32 v160, v160
	v_rcp_f32_e32 v161, v161
	v_rcp_f32_e32 v162, v162
	v_rcp_f32_e32 v163, v163
	v_rcp_f32_e32 v164, v164
	v_rcp_f32_e32 v165, v165
	v_rcp_f32_e32 v166, v166
	v_rcp_f32_e32 v167, v167
	v_mul_f32_e32 v160, v94, v160
	v_mul_f32_e32 v161, v95, v161
	v_mul_f32_e32 v162, v96, v162
	v_mul_f32_e32 v163, v97, v163
	v_mul_f32_e32 v164, v90, v164
	v_mul_f32_e32 v165, v91, v165
	v_mul_f32_e32 v166, v92, v166
	v_mul_f32_e32 v167, v93, v167
	v_cvt_pk_bf16_f32 v144, v160, v161
	v_cvt_pk_bf16_f32 v145, v162, v163
	v_cvt_pk_bf16_f32 v146, v164, v165
	v_cvt_pk_bf16_f32 v147, v166, v167
	v_permlane16_swap_b32_e32 v156, v158
	v_permlane16_swap_b32_e32 v157, v159
	global_store_dwordx4 v253, v[156:159], s[4:5]
	v_mul_f32_e32 v168, v86, v86
	v_mul_f32_e32 v169, v87, v87
	v_mul_f32_e32 v170, v88, v88
	v_mul_f32_e32 v171, v89, v89
	v_mul_f32_e32 v172, v82, v82
	v_mul_f32_e32 v173, v83, v83
	v_mul_f32_e32 v174, v84, v84
	v_mul_f32_e32 v175, v85, v85
	v_fma_f32 v168, v168, s18, v198
	v_fma_f32 v169, v169, s18, v198
	v_fma_f32 v170, v170, s18, v198
	v_fma_f32 v171, v171, s18, v198
	v_fma_f32 v172, v172, s18, v198
	v_fma_f32 v173, v173, s18, v198
	v_fma_f32 v174, v174, s18, v198
	v_fma_f32 v175, v175, s18, v198
	v_mul_f32_e32 v168, v86, v168
	v_mul_f32_e32 v169, v87, v169
	v_mul_f32_e32 v170, v88, v170
	v_mul_f32_e32 v171, v89, v171
	v_mul_f32_e32 v172, v82, v172
	v_mul_f32_e32 v173, v83, v173
	v_mul_f32_e32 v174, v84, v174
	v_mul_f32_e32 v175, v85, v175
	v_exp_f32_e32 v168, v168
	v_exp_f32_e32 v169, v169
	v_exp_f32_e32 v170, v170
	v_exp_f32_e32 v171, v171
	v_exp_f32_e32 v172, v172
	v_exp_f32_e32 v173, v173
	v_exp_f32_e32 v174, v174
	v_exp_f32_e32 v175, v175
; #define GAS __attribute__((address_space(1)))
; __device__ __forceinline__ uint2 pack4(f32x4 v) { return make_uint2(pack2(v[0], v[1]), pack2(v[2], v[3])); }
; template <int MODE>
; __device__ __forceinline__ void epi_elem(char* ws, float* outp, const float* b_gate, int g0, int rl, int col, f32x4 v) {
;   if (MODE == E_U || MODE == E_GV) {
;     int lc = col & 1023;
;     f32x4 o; for (int i = 0; i < 4; ++i) o[i] = gelu_f(v[i]);
;     u16* dst = (u16*)(ws + (MODE == E_U ? W_U : W_GV));
;     *(GAS uint2*)(dst + (size_t)rl * 1024 + lc) = pack4(o);
; template <int MODE>
; __device__ __forceinline__ void epi_store(char* ws, float* outp, const float* b_gate, int g0, const f32x4 (&acc)[2][2][4][2], int rbase, int cbase) {
; #pragma unroll
;   for (int ai = 0; ai < 2; ++ai)
; #pragma unroll
;     for (int bj = 0; bj < 2; ++bj)
; #pragma unroll
;       for (int m = 0; m < 4; ++m) {
; #pragma unroll
;         for (int n = 0; n < 2; ++n)
;           epi_elem<MODE>(ws, outp, b_gate, g0, rbase + ai * HALF + m * 16, cbase + bj * HALF + n * 16, acc[ai][bj][m][n]);
;         if ((m & 1) && (MODE != E_M1 && MODE != E_MG)) __builtin_amdgcn_sched_barrier(0);
;         if (m == 3 && (MODE == E_M1 || MODE == E_MG)) __builtin_amdgcn_sched_barrier(0);
;       }
	v_add_f32_e32 v168, 1.0, v168
	v_add_f32_e32 v169, 1.0, v169
	v_add_f32_e32 v170, 1.0, v170
	v_add_f32_e32 v171, 1.0, v171
	v_add_f32_e32 v172, 1.0, v172
	v_add_f32_e32 v173, 1.0, v173
	v_add_f32_e32 v174, 1.0, v174
	v_add_f32_e32 v175, 1.0, v175
	v_rcp_f32_e32 v168, v168
	v_rcp_f32_e32 v169, v169
	v_rcp_f32_e32 v170, v170
	v_rcp_f32_e32 v171, v171
	v_rcp_f32_e32 v172, v172
	v_rcp_f32_e32 v173, v173
	v_rcp_f32_e32 v174, v174
	v_rcp_f32_e32 v175, v175
	v_mul_f32_e32 v168, v86, v168
	v_mul_f32_e32 v169, v87, v169
	v_mul_f32_e32 v170, v88, v170
	v_mul_f32_e32 v171, v89, v171
	v_mul_f32_e32 v172, v82, v172
	v_mul_f32_e32 v173, v83, v173
	v_mul_f32_e32 v174, v84, v174
	v_mul_f32_e32 v175, v85, v175
	v_cvt_pk_bf16_f32 v148, v168, v169
	v_cvt_pk_bf16_f32 v149, v170, v171
	v_cvt_pk_bf16_f32 v150, v172, v173
	v_cvt_pk_bf16_f32 v151, v174, v175
	v_permlane16_swap_b32_e32 v144, v146
	v_permlane16_swap_b32_e32 v145, v147
	global_store_dwordx4 v250, v[144:147], s[4:5] offset:256
	v_mul_f32_e32 v160, v78, v78
	v_mul_f32_e32 v161, v79, v79
	v_mul_f32_e32 v162, v80, v80
	v_mul_f32_e32 v163, v81, v81
	v_mul_f32_e32 v164, v74, v74
	v_mul_f32_e32 v165, v75, v75
	v_mul_f32_e32 v166, v76, v76
	v_mul_f32_e32 v167, v77, v77
	v_fma_f32 v160, v160, s18, v198
	v_fma_f32 v161, v161, s18, v198
	v_fma_f32 v162, v162, s18, v198
	v_fma_f32 v163, v163, s18, v198
	v_fma_f32 v164, v164, s18, v198
	v_fma_f32 v165, v165, s18, v198
	v_fma_f32 v166, v166, s18, v198
	v_fma_f32 v167, v167, s18, v198
	v_mul_f32_e32 v160, v78, v160
	v_mul_f32_e32 v161, v79, v161
	v_mul_f32_e32 v162, v80, v162
	v_mul_f32_e32 v163, v81, v163
	v_mul_f32_e32 v164, v74, v164
	v_mul_f32_e32 v165, v75, v165
	v_mul_f32_e32 v166, v76, v166
	v_mul_f32_e32 v167, v77, v167
	v_exp_f32_e32 v160, v160
	v_exp_f32_e32 v161, v161
	v_exp_f32_e32 v162, v162
	v_exp_f32_e32 v163, v163
	v_exp_f32_e32 v164, v164
	v_exp_f32_e32 v165, v165
	v_exp_f32_e32 v166, v166
	v_exp_f32_e32 v167, v167
	v_add_f32_e32 v160, 1.0, v160
	v_add_f32_e32 v161, 1.0, v161
	v_add_f32_e32 v162, 1.0, v162
	v_add_f32_e32 v163, 1.0, v163
	v_add_f32_e32 v164, 1.0, v164
	v_add_f32_e32 v165, 1.0, v165
	v_add_f32_e32 v166, 1.0, v166
	v_add_f32_e32 v167, 1.0, v167
	v_rcp_f32_e32 v160, v160
	v_rcp_f32_e32 v161, v161
	v_rcp_f32_e32 v162, v162
	v_rcp_f32_e32 v163, v163
	v_rcp_f32_e32 v164, v164
	v_rcp_f32_e32 v165, v165
	v_rcp_f32_e32 v166, v166
	v_rcp_f32_e32 v167, v167
	v_mul_f32_e32 v160, v78, v160
	v_mul_f32_e32 v161, v79, v161
	v_mul_f32_e32 v162, v80, v162
	v_mul_f32_e32 v163, v81, v163
	v_mul_f32_e32 v164, v74, v164
	v_mul_f32_e32 v165, v75, v165
	v_mul_f32_e32 v166, v76, v166
	v_mul_f32_e32 v167, v77, v167
	v_cvt_pk_bf16_f32 v152, v160, v161
	v_cvt_pk_bf16_f32 v153, v162, v163
	v_cvt_pk_bf16_f32 v154, v164, v165
	v_cvt_pk_bf16_f32 v155, v166, v167
	v_permlane16_swap_b32_e32 v148, v150
	v_permlane16_swap_b32_e32 v149, v151
	global_store_dwordx4 v251, v[148:151], s[4:5] offset:256
	v_mul_f32_e32 v168, v70, v70
	v_mul_f32_e32 v169, v71, v71
	v_mul_f32_e32 v170, v72, v72
	v_mul_f32_e32 v171, v73, v73
	v_mul_f32_e32 v172, v66, v66
	v_mul_f32_e32 v173, v67, v67
	v_mul_f32_e32 v174, v68, v68
	v_mul_f32_e32 v175, v69, v69
	v_fma_f32 v168, v168, s18, v198
	v_fma_f32 v169, v169, s18, v198
	v_fma_f32 v170, v170, s18, v198
	v_fma_f32 v171, v171, s18, v198
	v_fma_f32 v172, v172, s18, v198
	v_fma_f32 v173, v173, s18, v198
	v_fma_f32 v174, v174, s18, v198
	v_fma_f32 v175, v175, s18, v198
	v_mul_f32_e32 v168, v70, v168
	v_mul_f32_e32 v169, v71, v169
	v_mul_f32_e32 v170, v72, v170
	v_mul_f32_e32 v171, v73, v171
	v_mul_f32_e32 v172, v66, v172
	v_mul_f32_e32 v173, v67, v173
	v_mul_f32_e32 v174, v68, v174
	v_mul_f32_e32 v175, v69, v175
	v_exp_f32_e32 v168, v168
	v_exp_f32_e32 v169, v169
	v_exp_f32_e32 v170, v170
	v_exp_f32_e32 v171, v171
	v_exp_f32_e32 v172, v172
	v_exp_f32_e32 v173, v173
	v_exp_f32_e32 v174, v174
	v_exp_f32_e32 v175, v175
	v_add_f32_e32 v168, 1.0, v168
	v_add_f32_e32 v169, 1.0, v169
	v_add_f32_e32 v170, 1.0, v170
	v_add_f32_e32 v171, 1.0, v171
	v_add_f32_e32 v172, 1.0, v172
	v_add_f32_e32 v173, 1.0, v173
	v_add_f32_e32 v174, 1.0, v174
	v_add_f32_e32 v175, 1.0, v175
	v_rcp_f32_e32 v168, v168
	v_rcp_f32_e32 v169, v169
	v_rcp_f32_e32 v170, v170
	v_rcp_f32_e32 v171, v171
	v_rcp_f32_e32 v172, v172
	v_rcp_f32_e32 v173, v173
	v_rcp_f32_e32 v174, v174
	v_rcp_f32_e32 v175, v175
	v_mul_f32_e32 v168, v70, v168
	v_mul_f32_e32 v169, v71, v169
	v_mul_f32_e32 v170, v72, v170
	v_mul_f32_e32 v171, v73, v171
	v_mul_f32_e32 v172, v66, v172
	v_mul_f32_e32 v173, v67, v173
	v_mul_f32_e32 v174, v68, v174
	v_mul_f32_e32 v175, v69, v175
	v_cvt_pk_bf16_f32 v156, v168, v169
	v_cvt_pk_bf16_f32 v157, v170, v171
	v_cvt_pk_bf16_f32 v158, v172, v173
	v_cvt_pk_bf16_f32 v159, v174, v175
	v_permlane16_swap_b32_e32 v152, v154
	v_permlane16_swap_b32_e32 v153, v155
	global_store_dwordx4 v252, v[152:155], s[4:5] offset:256
	v_mul_f32_e32 v160, v62, v62
	v_mul_f32_e32 v161, v63, v63
	v_mul_f32_e32 v162, v64, v64
	v_mul_f32_e32 v163, v65, v65
	v_mul_f32_e32 v164, v58, v58
	v_mul_f32_e32 v165, v59, v59
	v_mul_f32_e32 v166, v60, v60
	v_mul_f32_e32 v167, v61, v61
	v_fma_f32 v160, v160, s18, v198
	v_fma_f32 v161, v161, s18, v198
	v_fma_f32 v162, v162, s18, v198
	v_fma_f32 v163, v163, s18, v198
	v_fma_f32 v164, v164, s18, v198
	v_fma_f32 v165, v165, s18, v198
	v_fma_f32 v166, v166, s18, v198
	v_fma_f32 v167, v167, s18, v198
	v_mul_f32_e32 v160, v62, v160
	v_mul_f32_e32 v161, v63, v161
	v_mul_f32_e32 v162, v64, v162
	v_mul_f32_e32 v163, v65, v163
	v_mul_f32_e32 v164, v58, v164
	v_mul_f32_e32 v165, v59, v165
	v_mul_f32_e32 v166, v60, v166
	v_mul_f32_e32 v167, v61, v167
	v_exp_f32_e32 v160, v160
; #define GAS __attribute__((address_space(1)))
; __device__ __forceinline__ uint2 pack4(f32x4 v) { return make_uint2(pack2(v[0], v[1]), pack2(v[2], v[3])); }
; template <int MODE>
; __device__ __forceinline__ void epi_elem(char* ws, float* outp, const float* b_gate, int g0, int rl, int col, f32x4 v) {
;   if (MODE == E_U || MODE == E_GV) {
;     int lc = col & 1023;
;     f32x4 o; for (int i = 0; i < 4; ++i) o[i] = gelu_f(v[i]);
;     u16* dst = (u16*)(ws + (MODE == E_U ? W_U : W_GV));
;     *(GAS uint2*)(dst + (size_t)rl * 1024 + lc) = pack4(o);
; template <int MODE>
; __device__ __forceinline__ void epi_store(char* ws, float* outp, const float* b_gate, int g0, const f32x4 (&acc)[2][2][4][2], int rbase, int cbase) {
; #pragma unroll
;   for (int ai = 0; ai < 2; ++ai)
; #pragma unroll
;     for (int bj = 0; bj < 2; ++bj)
; #pragma unroll
;       for (int m = 0; m < 4; ++m) {
; #pragma unroll
;         for (int n = 0; n < 2; ++n)
;           epi_elem<MODE>(ws, outp, b_gate, g0, rbase + ai * HALF + m * 16, cbase + bj * HALF + n * 16, acc[ai][bj][m][n]);
;         if ((m & 1) && (MODE != E_M1 && MODE != E_MG)) __builtin_amdgcn_sched_barrier(0);
;         if (m == 3 && (MODE == E_M1 || MODE == E_MG)) __builtin_amdgcn_sched_barrier(0);
;       }
	v_exp_f32_e32 v161, v161
	v_exp_f32_e32 v162, v162
	v_exp_f32_e32 v163, v163
	v_exp_f32_e32 v164, v164
	v_exp_f32_e32 v165, v165
	v_exp_f32_e32 v166, v166
	v_exp_f32_e32 v167, v167
	v_add_f32_e32 v160, 1.0, v160
	v_add_f32_e32 v161, 1.0, v161
	v_add_f32_e32 v162, 1.0, v162
	v_add_f32_e32 v163, 1.0, v163
	v_add_f32_e32 v164, 1.0, v164
	v_add_f32_e32 v165, 1.0, v165
	v_add_f32_e32 v166, 1.0, v166
	v_add_f32_e32 v167, 1.0, v167
	v_rcp_f32_e32 v160, v160
	v_rcp_f32_e32 v161, v161
	v_rcp_f32_e32 v162, v162
	v_rcp_f32_e32 v163, v163
	v_rcp_f32_e32 v164, v164
	v_rcp_f32_e32 v165, v165
	v_rcp_f32_e32 v166, v166
	v_rcp_f32_e32 v167, v167
	v_mul_f32_e32 v160, v62, v160
	v_mul_f32_e32 v161, v63, v161
	v_mul_f32_e32 v162, v64, v162
	v_mul_f32_e32 v163, v65, v163
	v_mul_f32_e32 v164, v58, v164
	v_mul_f32_e32 v165, v59, v165
	v_mul_f32_e32 v166, v60, v166
	v_mul_f32_e32 v167, v61, v167
	v_cvt_pk_bf16_f32 v144, v160, v161
	v_cvt_pk_bf16_f32 v145, v162, v163
	v_cvt_pk_bf16_f32 v146, v164, v165
	v_cvt_pk_bf16_f32 v147, v166, v167
	v_permlane16_swap_b32_e32 v156, v158
	v_permlane16_swap_b32_e32 v157, v159
	global_store_dwordx4 v253, v[156:159], s[4:5] offset:256
	v_mul_f32_e32 v168, v54, v54
	v_mul_f32_e32 v169, v55, v55
	v_mul_f32_e32 v170, v56, v56
	v_mul_f32_e32 v171, v57, v57
	v_mul_f32_e32 v172, v50, v50
	v_mul_f32_e32 v173, v51, v51
	v_mul_f32_e32 v174, v52, v52
	v_mul_f32_e32 v175, v53, v53
	v_fma_f32 v168, v168, s18, v198
	v_fma_f32 v169, v169, s18, v198
	v_fma_f32 v170, v170, s18, v198
	v_fma_f32 v171, v171, s18, v198
	v_fma_f32 v172, v172, s18, v198
	v_fma_f32 v173, v173, s18, v198
	v_fma_f32 v174, v174, s18, v198
	v_fma_f32 v175, v175, s18, v198
	v_mul_f32_e32 v168, v54, v168
	v_mul_f32_e32 v169, v55, v169
	v_mul_f32_e32 v170, v56, v170
	v_mul_f32_e32 v171, v57, v171
	v_mul_f32_e32 v172, v50, v172
	v_mul_f32_e32 v173, v51, v173
	v_mul_f32_e32 v174, v52, v174
	v_mul_f32_e32 v175, v53, v175
	v_exp_f32_e32 v168, v168
	v_exp_f32_e32 v169, v169
	v_exp_f32_e32 v170, v170
	v_exp_f32_e32 v171, v171
	v_exp_f32_e32 v172, v172
	v_exp_f32_e32 v173, v173
	v_exp_f32_e32 v174, v174
	v_exp_f32_e32 v175, v175
	v_add_f32_e32 v168, 1.0, v168
	v_add_f32_e32 v169, 1.0, v169
	v_add_f32_e32 v170, 1.0, v170
	v_add_f32_e32 v171, 1.0, v171
	v_add_f32_e32 v172, 1.0, v172
	v_add_f32_e32 v173, 1.0, v173
	v_add_f32_e32 v174, 1.0, v174
	v_add_f32_e32 v175, 1.0, v175
	v_rcp_f32_e32 v168, v168
	v_rcp_f32_e32 v169, v169
	v_rcp_f32_e32 v170, v170
	v_rcp_f32_e32 v171, v171
	v_rcp_f32_e32 v172, v172
	v_rcp_f32_e32 v173, v173
	v_rcp_f32_e32 v174, v174
	v_rcp_f32_e32 v175, v175
	v_mul_f32_e32 v168, v54, v168
	v_mul_f32_e32 v169, v55, v169
	v_mul_f32_e32 v170, v56, v170
	v_mul_f32_e32 v171, v57, v171
	v_mul_f32_e32 v172, v50, v172
	v_mul_f32_e32 v173, v51, v173
	v_mul_f32_e32 v174, v52, v174
	v_mul_f32_e32 v175, v53, v175
	v_cvt_pk_bf16_f32 v148, v168, v169
	v_cvt_pk_bf16_f32 v149, v170, v171
	v_cvt_pk_bf16_f32 v150, v172, v173
	v_cvt_pk_bf16_f32 v151, v174, v175
	v_permlane16_swap_b32_e32 v144, v146
	v_permlane16_swap_b32_e32 v145, v147
	global_store_dwordx4 v250, v[144:147], s[6:7]
	v_mul_f32_e32 v160, v46, v46
	v_mul_f32_e32 v161, v47, v47
	v_mul_f32_e32 v162, v48, v48
	v_mul_f32_e32 v163, v49, v49
	v_mul_f32_e32 v164, v42, v42
	v_mul_f32_e32 v165, v43, v43
	v_mul_f32_e32 v166, v44, v44
	v_mul_f32_e32 v167, v45, v45
	v_fma_f32 v160, v160, s18, v198
	v_fma_f32 v161, v161, s18, v198
	v_fma_f32 v162, v162, s18, v198
	v_fma_f32 v163, v163, s18, v198
	v_fma_f32 v164, v164, s18, v198
	v_fma_f32 v165, v165, s18, v198
	v_fma_f32 v166, v166, s18, v198
	v_fma_f32 v167, v167, s18, v198
	v_mul_f32_e32 v160, v46, v160
	v_mul_f32_e32 v161, v47, v161
	v_mul_f32_e32 v162, v48, v162
	v_mul_f32_e32 v163, v49, v163
	v_mul_f32_e32 v164, v42, v164
	v_mul_f32_e32 v165, v43, v165
	v_mul_f32_e32 v166, v44, v166
	v_mul_f32_e32 v167, v45, v167
	v_exp_f32_e32 v160, v160
	v_exp_f32_e32 v161, v161
	v_exp_f32_e32 v162, v162
	v_exp_f32_e32 v163, v163
	v_exp_f32_e32 v164, v164
	v_exp_f32_e32 v165, v165
	v_exp_f32_e32 v166, v166
	v_exp_f32_e32 v167, v167
	v_add_f32_e32 v160, 1.0, v160
	v_add_f32_e32 v161, 1.0, v161
	v_add_f32_e32 v162, 1.0, v162
	v_add_f32_e32 v163, 1.0, v163
	v_add_f32_e32 v164, 1.0, v164
	v_add_f32_e32 v165, 1.0, v165
	v_add_f32_e32 v166, 1.0, v166
	v_add_f32_e32 v167, 1.0, v167
	v_rcp_f32_e32 v160, v160
	v_rcp_f32_e32 v161, v161
	v_rcp_f32_e32 v162, v162
	v_rcp_f32_e32 v163, v163
	v_rcp_f32_e32 v164, v164
	v_rcp_f32_e32 v165, v165
	v_rcp_f32_e32 v166, v166
	v_rcp_f32_e32 v167, v167
	v_mul_f32_e32 v160, v46, v160
	v_mul_f32_e32 v161, v47, v161
	v_mul_f32_e32 v162, v48, v162
	v_mul_f32_e32 v163, v49, v163
	v_mul_f32_e32 v164, v42, v164
	v_mul_f32_e32 v165, v43, v165
	v_mul_f32_e32 v166, v44, v166
	v_mul_f32_e32 v167, v45, v167
	v_cvt_pk_bf16_f32 v152, v160, v161
	v_cvt_pk_bf16_f32 v153, v162, v163
	v_cvt_pk_bf16_f32 v154, v164, v165
	v_cvt_pk_bf16_f32 v155, v166, v167
	v_permlane16_swap_b32_e32 v148, v150
	v_permlane16_swap_b32_e32 v149, v151
	global_store_dwordx4 v251, v[148:151], s[6:7]
	v_mul_f32_e32 v168, v38, v38
	v_mul_f32_e32 v169, v39, v39
	v_mul_f32_e32 v170, v40, v40
	v_mul_f32_e32 v171, v41, v41
	v_mul_f32_e32 v172, v34, v34
	v_mul_f32_e32 v173, v35, v35
	v_mul_f32_e32 v174, v36, v36
	v_mul_f32_e32 v175, v37, v37
	v_fma_f32 v168, v168, s18, v198
	v_fma_f32 v169, v169, s18, v198
	v_fma_f32 v170, v170, s18, v198
	v_fma_f32 v171, v171, s18, v198
	v_fma_f32 v172, v172, s18, v198
	v_fma_f32 v173, v173, s18, v198
	v_fma_f32 v174, v174, s18, v198
	v_fma_f32 v175, v175, s18, v198
	v_mul_f32_e32 v168, v38, v168
	v_mul_f32_e32 v169, v39, v169
	v_mul_f32_e32 v170, v40, v170
	v_mul_f32_e32 v171, v41, v171
; #define GAS __attribute__((address_space(1)))
; __device__ __forceinline__ uint2 pack4(f32x4 v) { return make_uint2(pack2(v[0], v[1]), pack2(v[2], v[3])); }
; template <int MODE>
; __device__ __forceinline__ void epi_elem(char* ws, float* outp, const float* b_gate, int g0, int rl, int col, f32x4 v) {
;   if (MODE == E_U || MODE == E_GV) {
;     int lc = col & 1023;
;     f32x4 o; for (int i = 0; i < 4; ++i) o[i] = gelu_f(v[i]);
;     u16* dst = (u16*)(ws + (MODE == E_U ? W_U : W_GV));
;     *(GAS uint2*)(dst + (size_t)rl * 1024 + lc) = pack4(o);
; template <int MODE>
; __device__ __forceinline__ void epi_store(char* ws, float* outp, const float* b_gate, int g0, const f32x4 (&acc)[2][2][4][2], int rbase, int cbase) {
; #pragma unroll
;   for (int ai = 0; ai < 2; ++ai)
; #pragma unroll
;     for (int bj = 0; bj < 2; ++bj)
; #pragma unroll
;       for (int m = 0; m < 4; ++m) {
; #pragma unroll
;         for (int n = 0; n < 2; ++n)
;           epi_elem<MODE>(ws, outp, b_gate, g0, rbase + ai * HALF + m * 16, cbase + bj * HALF + n * 16, acc[ai][bj][m][n]);
;         if ((m & 1) && (MODE != E_M1 && MODE != E_MG)) __builtin_amdgcn_sched_barrier(0);
;         if (m == 3 && (MODE == E_M1 || MODE == E_MG)) __builtin_amdgcn_sched_barrier(0);
;       }
	v_mul_f32_e32 v172, v34, v172
	v_mul_f32_e32 v173, v35, v173
	v_mul_f32_e32 v174, v36, v174
	v_mul_f32_e32 v175, v37, v175
	v_exp_f32_e32 v168, v168
	v_exp_f32_e32 v169, v169
	v_exp_f32_e32 v170, v170
	v_exp_f32_e32 v171, v171
	v_exp_f32_e32 v172, v172
	v_exp_f32_e32 v173, v173
	v_exp_f32_e32 v174, v174
	v_exp_f32_e32 v175, v175
	v_add_f32_e32 v168, 1.0, v168
	v_add_f32_e32 v169, 1.0, v169
	v_add_f32_e32 v170, 1.0, v170
	v_add_f32_e32 v171, 1.0, v171
	v_add_f32_e32 v172, 1.0, v172
	v_add_f32_e32 v173, 1.0, v173
	v_add_f32_e32 v174, 1.0, v174
	v_add_f32_e32 v175, 1.0, v175
	v_rcp_f32_e32 v168, v168
	v_rcp_f32_e32 v169, v169
	v_rcp_f32_e32 v170, v170
	v_rcp_f32_e32 v171, v171
	v_rcp_f32_e32 v172, v172
	v_rcp_f32_e32 v173, v173
	v_rcp_f32_e32 v174, v174
	v_rcp_f32_e32 v175, v175
	v_mul_f32_e32 v168, v38, v168
	v_mul_f32_e32 v169, v39, v169
	v_mul_f32_e32 v170, v40, v170
	v_mul_f32_e32 v171, v41, v171
	v_mul_f32_e32 v172, v34, v172
	v_mul_f32_e32 v173, v35, v173
	v_mul_f32_e32 v174, v36, v174
	v_mul_f32_e32 v175, v37, v175
	v_cvt_pk_bf16_f32 v156, v168, v169
	v_cvt_pk_bf16_f32 v157, v170, v171
	v_cvt_pk_bf16_f32 v158, v172, v173
	v_cvt_pk_bf16_f32 v159, v174, v175
	v_permlane16_swap_b32_e32 v152, v154
	v_permlane16_swap_b32_e32 v153, v155
	global_store_dwordx4 v252, v[152:155], s[6:7]
	v_mul_f32_e32 v160, v30, v30
	v_mul_f32_e32 v161, v31, v31
	v_mul_f32_e32 v162, v32, v32
	v_mul_f32_e32 v163, v33, v33
	v_mul_f32_e32 v164, v26, v26
	v_mul_f32_e32 v165, v27, v27
	v_mul_f32_e32 v166, v28, v28
	v_mul_f32_e32 v167, v29, v29
	v_fma_f32 v160, v160, s18, v198
	v_fma_f32 v161, v161, s18, v198
	v_fma_f32 v162, v162, s18, v198
	v_fma_f32 v163, v163, s18, v198
	v_fma_f32 v164, v164, s18, v198
	v_fma_f32 v165, v165, s18, v198
	v_fma_f32 v166, v166, s18, v198
	v_fma_f32 v167, v167, s18, v198
	v_mul_f32_e32 v160, v30, v160
	v_mul_f32_e32 v161, v31, v161
	v_mul_f32_e32 v162, v32, v162
	v_mul_f32_e32 v163, v33, v163
	v_mul_f32_e32 v164, v26, v164
	v_mul_f32_e32 v165, v27, v165
	v_mul_f32_e32 v166, v28, v166
	v_mul_f32_e32 v167, v29, v167
	v_exp_f32_e32 v160, v160
	v_exp_f32_e32 v161, v161
	v_exp_f32_e32 v162, v162
	v_exp_f32_e32 v163, v163
	v_exp_f32_e32 v164, v164
	v_exp_f32_e32 v165, v165
	v_exp_f32_e32 v166, v166
	v_exp_f32_e32 v167, v167
	v_add_f32_e32 v160, 1.0, v160
	v_add_f32_e32 v161, 1.0, v161
	v_add_f32_e32 v162, 1.0, v162
	v_add_f32_e32 v163, 1.0, v163
	v_add_f32_e32 v164, 1.0, v164
	v_add_f32_e32 v165, 1.0, v165
	v_add_f32_e32 v166, 1.0, v166
	v_add_f32_e32 v167, 1.0, v167
	v_rcp_f32_e32 v160, v160
	v_rcp_f32_e32 v161, v161
	v_rcp_f32_e32 v162, v162
	v_rcp_f32_e32 v163, v163
	v_rcp_f32_e32 v164, v164
	v_rcp_f32_e32 v165, v165
	v_rcp_f32_e32 v166, v166
	v_rcp_f32_e32 v167, v167
	v_mul_f32_e32 v160, v30, v160
	v_mul_f32_e32 v161, v31, v161
	v_mul_f32_e32 v162, v32, v162
	v_mul_f32_e32 v163, v33, v163
	v_mul_f32_e32 v164, v26, v164
	v_mul_f32_e32 v165, v27, v165
	v_mul_f32_e32 v166, v28, v166
	v_mul_f32_e32 v167, v29, v167
	v_cvt_pk_bf16_f32 v144, v160, v161
	v_cvt_pk_bf16_f32 v145, v162, v163
	v_cvt_pk_bf16_f32 v146, v164, v165
	v_cvt_pk_bf16_f32 v147, v166, v167
	v_permlane16_swap_b32_e32 v156, v158
	v_permlane16_swap_b32_e32 v157, v159
	global_store_dwordx4 v253, v[156:159], s[6:7]
	v_mul_f32_e32 v168, v22, v22
	v_mul_f32_e32 v169, v23, v23
	v_mul_f32_e32 v170, v24, v24
	v_mul_f32_e32 v171, v25, v25
	v_mul_f32_e32 v172, v18, v18
	v_mul_f32_e32 v173, v19, v19
	v_mul_f32_e32 v174, v20, v20
	v_mul_f32_e32 v175, v21, v21
	v_fma_f32 v168, v168, s18, v198
	v_fma_f32 v169, v169, s18, v198
	v_fma_f32 v170, v170, s18, v198
	v_fma_f32 v171, v171, s18, v198
	v_fma_f32 v172, v172, s18, v198
	v_fma_f32 v173, v173, s18, v198
	v_fma_f32 v174, v174, s18, v198
	v_fma_f32 v175, v175, s18, v198
	v_mul_f32_e32 v168, v22, v168
	v_mul_f32_e32 v169, v23, v169
	v_mul_f32_e32 v170, v24, v170
	v_mul_f32_e32 v171, v25, v171
	v_mul_f32_e32 v172, v18, v172
	v_mul_f32_e32 v173, v19, v173
	v_mul_f32_e32 v174, v20, v174
	v_mul_f32_e32 v175, v21, v175
	v_exp_f32_e32 v168, v168
	v_exp_f32_e32 v169, v169
	v_exp_f32_e32 v170, v170
	v_exp_f32_e32 v171, v171
	v_exp_f32_e32 v172, v172
	v_exp_f32_e32 v173, v173
	v_exp_f32_e32 v174, v174
	v_exp_f32_e32 v175, v175
	v_add_f32_e32 v168, 1.0, v168
	v_add_f32_e32 v169, 1.0, v169
	v_add_f32_e32 v170, 1.0, v170
	v_add_f32_e32 v171, 1.0, v171
	v_add_f32_e32 v172, 1.0, v172
	v_add_f32_e32 v173, 1.0, v173
	v_add_f32_e32 v174, 1.0, v174
	v_add_f32_e32 v175, 1.0, v175
	v_rcp_f32_e32 v168, v168
	v_rcp_f32_e32 v169, v169
	v_rcp_f32_e32 v170, v170
	v_rcp_f32_e32 v171, v171
	v_rcp_f32_e32 v172, v172
	v_rcp_f32_e32 v173, v173
; #define GAS __attribute__((address_space(1)))
; __device__ __forceinline__ uint2 pack4(f32x4 v) { return make_uint2(pack2(v[0], v[1]), pack2(v[2], v[3])); }
; template <int MODE>
; __device__ __forceinline__ void epi_elem(char* ws, float* outp, const float* b_gate, int g0, int rl, int col, f32x4 v) {
;   if (MODE == E_U || MODE == E_GV) {
;     int lc = col & 1023;
;     f32x4 o; for (int i = 0; i < 4; ++i) o[i] = gelu_f(v[i]);
;     u16* dst = (u16*)(ws + (MODE == E_U ? W_U : W_GV));
;     *(GAS uint2*)(dst + (size_t)rl * 1024 + lc) = pack4(o);
; template <int MODE>
; __device__ __forceinline__ void epi_store(char* ws, float* outp, const float* b_gate, int g0, const f32x4 (&acc)[2][2][4][2], int rbase, int cbase) {
; #pragma unroll
;   for (int ai = 0; ai < 2; ++ai)
; #pragma unroll
;     for (int bj = 0; bj < 2; ++bj)
; #pragma unroll
;       for (int m = 0; m < 4; ++m) {
; #pragma unroll
;         for (int n = 0; n < 2; ++n)
;           epi_elem<MODE>(ws, outp, b_gate, g0, rbase + ai * HALF + m * 16, cbase + bj * HALF + n * 16, acc[ai][bj][m][n]);
;         if ((m & 1) && (MODE != E_M1 && MODE != E_MG)) __builtin_amdgcn_sched_barrier(0);
;         if (m == 3 && (MODE == E_M1 || MODE == E_MG)) __builtin_amdgcn_sched_barrier(0);
;       }
	v_rcp_f32_e32 v174, v174
	v_rcp_f32_e32 v175, v175
	v_mul_f32_e32 v168, v22, v168
	v_mul_f32_e32 v169, v23, v169
	v_mul_f32_e32 v170, v24, v170
	v_mul_f32_e32 v171, v25, v171
	v_mul_f32_e32 v172, v18, v172
	v_mul_f32_e32 v173, v19, v173
	v_mul_f32_e32 v174, v20, v174
	v_mul_f32_e32 v175, v21, v175
	v_cvt_pk_bf16_f32 v148, v168, v169
	v_cvt_pk_bf16_f32 v149, v170, v171
	v_cvt_pk_bf16_f32 v150, v172, v173
	v_cvt_pk_bf16_f32 v151, v174, v175
	v_permlane16_swap_b32_e32 v144, v146
	v_permlane16_swap_b32_e32 v145, v147
	global_store_dwordx4 v250, v[144:147], s[6:7] offset:256
	v_mul_f32_e32 v160, v14, v14
	v_mul_f32_e32 v161, v15, v15
	v_mul_f32_e32 v162, v16, v16
	v_mul_f32_e32 v163, v17, v17
	v_mul_f32_e32 v164, v10, v10
	v_mul_f32_e32 v165, v11, v11
	v_mul_f32_e32 v166, v12, v12
	v_mul_f32_e32 v167, v13, v13
	v_fma_f32 v160, v160, s18, v198
	v_fma_f32 v161, v161, s18, v198
	v_fma_f32 v162, v162, s18, v198
	v_fma_f32 v163, v163, s18, v198
	v_fma_f32 v164, v164, s18, v198
	v_fma_f32 v165, v165, s18, v198
	v_fma_f32 v166, v166, s18, v198
	v_fma_f32 v167, v167, s18, v198
	v_mul_f32_e32 v160, v14, v160
	v_mul_f32_e32 v161, v15, v161
	v_mul_f32_e32 v162, v16, v162
	v_mul_f32_e32 v163, v17, v163
	v_mul_f32_e32 v164, v10, v164
	v_mul_f32_e32 v165, v11, v165
	v_mul_f32_e32 v166, v12, v166
	v_mul_f32_e32 v167, v13, v167
	v_exp_f32_e32 v160, v160
	v_exp_f32_e32 v161, v161
	v_exp_f32_e32 v162, v162
	v_exp_f32_e32 v163, v163
	v_exp_f32_e32 v164, v164
	v_exp_f32_e32 v165, v165
	v_exp_f32_e32 v166, v166
	v_exp_f32_e32 v167, v167
	v_add_f32_e32 v160, 1.0, v160
	v_add_f32_e32 v161, 1.0, v161
	v_add_f32_e32 v162, 1.0, v162
	v_add_f32_e32 v163, 1.0, v163
	v_add_f32_e32 v164, 1.0, v164
	v_add_f32_e32 v165, 1.0, v165
	v_add_f32_e32 v166, 1.0, v166
	v_add_f32_e32 v167, 1.0, v167
	v_rcp_f32_e32 v160, v160
	v_rcp_f32_e32 v161, v161
	v_rcp_f32_e32 v162, v162
	v_rcp_f32_e32 v163, v163
	v_rcp_f32_e32 v164, v164
	v_rcp_f32_e32 v165, v165
	v_rcp_f32_e32 v166, v166
	v_rcp_f32_e32 v167, v167
	v_mul_f32_e32 v160, v14, v160
	v_mul_f32_e32 v161, v15, v161
	v_mul_f32_e32 v162, v16, v162
	v_mul_f32_e32 v163, v17, v163
	v_mul_f32_e32 v164, v10, v164
	v_mul_f32_e32 v165, v11, v165
	v_mul_f32_e32 v166, v12, v166
	v_mul_f32_e32 v167, v13, v167
	v_cvt_pk_bf16_f32 v152, v160, v161
	v_cvt_pk_bf16_f32 v153, v162, v163
	v_cvt_pk_bf16_f32 v154, v164, v165
	v_cvt_pk_bf16_f32 v155, v166, v167
	v_permlane16_swap_b32_e32 v148, v150
	v_permlane16_swap_b32_e32 v149, v151
	global_store_dwordx4 v251, v[148:151], s[6:7] offset:256
	v_mul_f32_e32 v168, v6, v6
	v_mul_f32_e32 v169, v7, v7
	v_mul_f32_e32 v170, v8, v8
	v_mul_f32_e32 v171, v9, v9
	v_mul_f32_e32 v172, v2, v2
	v_mul_f32_e32 v173, v3, v3
	v_mul_f32_e32 v174, v4, v4
	v_mul_f32_e32 v175, v5, v5
	v_fma_f32 v168, v168, s18, v198
	v_fma_f32 v169, v169, s18, v198
	v_fma_f32 v170, v170, s18, v198
	v_fma_f32 v171, v171, s18, v198
	v_fma_f32 v172, v172, s18, v198
	v_fma_f32 v173, v173, s18, v198
	v_fma_f32 v174, v174, s18, v198
	v_fma_f32 v175, v175, s18, v198
	v_mul_f32_e32 v168, v6, v168
	v_mul_f32_e32 v169, v7, v169
	v_mul_f32_e32 v170, v8, v170
	v_mul_f32_e32 v171, v9, v171
	v_mul_f32_e32 v172, v2, v172
	v_mul_f32_e32 v173, v3, v173
	v_mul_f32_e32 v174, v4, v174
	v_mul_f32_e32 v175, v5, v175
	v_exp_f32_e32 v168, v168
	v_exp_f32_e32 v169, v169
	v_exp_f32_e32 v170, v170
	v_exp_f32_e32 v171, v171
	v_exp_f32_e32 v172, v172
	v_exp_f32_e32 v173, v173
	v_exp_f32_e32 v174, v174
	v_exp_f32_e32 v175, v175
	v_add_f32_e32 v168, 1.0, v168
	v_add_f32_e32 v169, 1.0, v169
	v_add_f32_e32 v170, 1.0, v170
	v_add_f32_e32 v171, 1.0, v171
	v_add_f32_e32 v172, 1.0, v172
	v_add_f32_e32 v173, 1.0, v173
	v_add_f32_e32 v174, 1.0, v174
	v_add_f32_e32 v175, 1.0, v175
	v_rcp_f32_e32 v168, v168
	v_rcp_f32_e32 v169, v169
	v_rcp_f32_e32 v170, v170
	v_rcp_f32_e32 v171, v171
	v_rcp_f32_e32 v172, v172
	v_rcp_f32_e32 v173, v173
	v_rcp_f32_e32 v174, v174
	v_rcp_f32_e32 v175, v175
	v_mul_f32_e32 v168, v6, v168
	v_mul_f32_e32 v169, v7, v169
	v_mul_f32_e32 v170, v8, v170
	v_mul_f32_e32 v171, v9, v171
	v_mul_f32_e32 v172, v2, v172
	v_mul_f32_e32 v173, v3, v173
	v_mul_f32_e32 v174, v4, v174
	v_mul_f32_e32 v175, v5, v175
	v_cvt_pk_bf16_f32 v156, v168, v169
	v_cvt_pk_bf16_f32 v157, v170, v171
	v_cvt_pk_bf16_f32 v158, v172, v173
	v_cvt_pk_bf16_f32 v159, v174, v175
	v_permlane16_swap_b32_e32 v152, v154
	v_permlane16_swap_b32_e32 v153, v155
	global_store_dwordx4 v252, v[152:155], s[6:7] offset:256
	s_nop 1
	v_permlane16_swap_b32_e32 v156, v158
	v_permlane16_swap_b32_e32 v157, v159
	global_store_dwordx4 v253, v[156:159], s[6:7] offset:256
	s_branch .LBB0_996
